# speedup vs baseline: 1.0182x; 1.0182x over previous
; __global__ void __launch_bounds__(512, 2) mega(Params p) {
;     ...
;     const bool isP = g0 < NTOK_P;
;     const int L = isP ? 4096 : 2048;
;     const int nseq = GT / L;
;     ...
;     } else if (st == 2) {
;       const int nB = nseq * 16, nA = nseq * 24 * (L / 128);
;       int it = blockIdx.x;
;       for (; it < nB; it += gridDim.x) {
;         gla_item(p, layer, it, L);
.LBB0_101:
	s_andn2_b64 vcc, exec, s[0:1]
	s_cbranch_vccnz .LBB0_170
	s_and_b64 s[0:1], s[6:7], exec
	s_movk_i32 s0, 0x800
	s_cselect_b32 s90, 0x1000, s0
	v_cvt_f32_u32_e32 v0, s90
	s_sub_i32 s0, 0, s90
	v_readlane_b32 s9, v254, 54
	v_rcp_iflag_f32_e32 v0, v0
	s_nop 0
	v_mul_f32_e32 v0, 0x4f7ffffe, v0
	v_cvt_u32_f32_e32 v0, v0
	s_nop 0
	v_readfirstlane_b32 s1, v0
	s_mul_i32 s0, s0, s1
	s_mul_hi_u32 s0, s1, s0
	s_add_i32 s1, s1, s0
	s_mul_hi_u32 s0, s9, s1
	s_mul_i32 s1, s0, s90
	s_sub_i32 s1, s9, s1
	s_add_i32 s8, s0, 1
	s_sub_i32 s9, s1, s90
	s_cmp_ge_u32 s1, s90
	s_cselect_b32 s0, s8, s0
	s_cselect_b32 s1, s9, s1
	s_add_i32 s8, s0, 1
	s_cmp_ge_u32 s1, s90
	s_cselect_b32 s0, s8, s0
	s_xor_b32 s0, s0, s35
	s_sub_i32 s0, s0, s35
	s_lshl_b32 s91, s0, 4
	v_writelane_b32 v255, s0, 1
	s_cmp_ge_i32 s2, s91
	s_cbranch_scc1 .LBB0_124
	s_lshr_b32 s37, s90, 6
	s_and_b64 s[0:1], s[6:7], exec
	s_cselect_b32 s33, 12, 11
	s_sub_i32 s36, s90, 64
	s_add_i32 s37, s37, -1
	s_lshr_b32 s38, s91, 3
	s_and_b32 s0, s2, 7
	s_mul_i32 s38, s38, s0
	s_lshr_b32 s0, s2, 3
	s_add_i32 s38, s38, s0
	s_branch .LBB0_105

; DEV void gla_item(const Params& p, int layer, int it, int L) {
;     ...
;   const int tid = tidx(), w = tid >> 6, l = tid & 63, fr = l & 15, kq = l >> 4;
;   const int dvh = it & 1, dir = (it >> 1) & 1, hh = (it >> 2) & 3, b = it >> 4;
;   const int NCH = L / 64;
;   const int colq = C_QB + hh * 128, colk = C_KB + hh * 128, colv = C_VB + hh * 256 + dvh * 128;
;   const int colla = (dir ? C_LAB : C_LAF) + hh * 128;
;   unsigned zop; asm volatile("v_mov_b32 %0, 0" : "=v"(zop));
;   const float zf = __uint_as_float(zop);
;   const int prow = tid >> 3, pc = (tid & 7) * 8;
;   u32x4 pq0, pq1, pk0, pk1, pv0, pv1, pe0, pe1, pd0, pd1;
;   auto tok_of = [&](int nproc, int row) -> long {
;     int n = dir ? (NCH - 1 - nproc) : nproc;
;     int i = dir ? (63 - row) : row;
;     return (long)b * L + n * 64 + i;
;   };
;   auto prefetch = [&](int nproc) {
;     const u16* base = p.proj + tok_of(nproc, prow) * LDR;
;     pq0 = *(const u32x4*)(base + colq + pc); pq1 = *(const u32x4*)(base + colq + 64 + pc);
;     pk0 = *(const u32x4*)(base + colk + pc); pk1 = *(const u32x4*)(base + colk + 64 + pc);
;     pv0 = *(const u32x4*)(base + colv + pc); pv1 = *(const u32x4*)(base + colv + 64 + pc);
;     pe0 = *(const u32x4*)(base + colla + pc); pe1 = *(const u32x4*)(base + colla + 64 + pc);
;     const u16* bl = p.proj + tok_of(nproc, 63) * LDR;
;     pd0 = *(const u32x4*)(bl + colla + pc); pd1 = *(const u32x4*)(bl + colla + 64 + pc);
;   };
;     ...
;       const int it_ = w >> 1;
;       bf16x8 qb[4], ka[2][4];
; #pragma unroll
;       for (int ks = 0; ks < 4; ++ks) qb[ks] = *(const bf16x8*)(Qs + (it_ * 16 + fr) * QS + ks * 32 + kq * 8);
; #pragma unroll
;       for (int ss = 0; ss < 2; ++ss)
; #pragma unroll
;         for (int ks = 0; ks < 4; ++ks) ka[ss][ks] = *(const bf16x8*)(Ksm + (((w & 1) * 2 + ss) * 16 + fr) * QS + ks * 32 + kq * 8);
;       __builtin_amdgcn_sched_barrier(0);
; #pragma unroll
;       for (int ss = 0; ss < 2; ++ss) {
;         const int stl = (w & 1) * 2 + ss;
;         f32x4 a = {0.f, 0.f, 0.f, 0.f};
;         if (stl <= it_) {
; #pragma unroll
;           for (int ks = 0; ks < 4; ++ks) a = __builtin_amdgcn_mfma_f32_16x16x32_bf16(ka[ss][ks], qb[ks], a, 0, 0, 0);
;         }
;         const int irow = it_ * 16 + fr;
;         float o[4];
; #pragma unroll
;         for (int j = 0; j < 4; ++j) {
;           int s = stl * 16 + kq * 4 + j;
.LBB0_105:
	s_bfe_u32 s45, s38, 0x20002
	s_lshl_b32 s1, s38, 7
	s_lshl_b32 s58, s45, 8
	s_and_b32 s39, s1, 0x80
	s_bfe_i32 s10, s38, 0x10001
	s_bfe_u32 s46, s38, 0x10001
	s_ashr_i32 s0, s38, 4
	s_lshl_b32 s41, s45, 7
	s_or_b32 s44, s39, s58
	s_cmp_eq_u32 s46, 0
	s_cselect_b64 s[28:29], -1, 0
	s_and_b64 s[8:9], s[28:29], exec
	s_movk_i32 s1, 0x1400
	s_cselect_b32 s1, s1, 0x1600
	s_cselect_b32 s42, 63, 0
	s_or_b32 s47, s1, s41
	s_ashr_i32 s1, s0, 31
	s_mov_b32 s43, 0
	s_lshl_b64 s[94:95], s[0:1], s33
	s_or_b64 s[96:97], s[42:43], s[94:95]
	s_and_b32 s8, s10, s36
	s_add_u32 s0, s96, s8
	v_mov_b32_e32 v13, v143
	s_addc_u32 s1, s97, 0
	s_mulk_i32 s1, 0x3000
	v_ashrrev_i32_e32 v16, 3, v13
	s_mul_hi_u32 s9, s0, 0x3000
	v_sub_u32_e32 v0, 63, v16
	s_add_i32 s9, s9, s1
	s_mulk_i32 s0, 0x3000
	v_cndmask_b32_e64 v10, v0, v16, s[28:29]
	s_add_u32 s0, s76, s0
	v_lshlrev_b32_e32 v17, 3, v13
	s_addc_u32 s1, s77, s9
	s_lshl_b32 s56, s47, 1
	v_add_u32_e32 v0, s8, v10
	v_and_b32_e32 v12, 56, v17
	s_add_u32 s0, s0, s56
	v_ashrrev_i32_e32 v1, 31, v0
	s_addc_u32 s1, s1, 0
	v_lshlrev_b32_e32 v4, 1, v12
	v_lshl_add_u64 v[0:1], s[94:95], 0, v[0:1]
	v_mov_b64_e32 v[2:3], s[76:77]
	v_mov_b32 v131, 0
	global_load_dwordx4 v[50:53], v4, s[0:1] offset:128
	global_load_dwordx4 v[66:69], v4, s[0:1]
	v_mad_u64_u32 v[14:15], s[0:1], v0, s61, v[2:3]
	v_mad_i32_i24 v15, v1, s61, v15
	v_lshl_add_u64 v[0:1], v[14:15], 0, s[56:57]
	v_lshl_add_u64 v[0:1], v[0:1], 0, v[4:5]
	s_lshl_b32 s0, s44, 1
	s_mov_b32 s1, s57
	s_mov_b32 s59, s57
	global_load_dwordx4 v[42:45], v[0:1], off offset:128
	global_load_dwordx4 v[62:65], v[0:1], off
	v_lshl_add_u64 v[0:1], v[14:15], 0, s[0:1]
	v_lshl_add_u64 v[14:15], v[14:15], 0, s[58:59]
	v_lshl_add_u64 v[6:7], v[0:1], 0, v[4:5]
	v_lshl_add_u64 v[14:15], v[14:15], 0, v[4:5]
	global_load_dwordx4 v[0:3], v[6:7], off offset:2176
	s_nop 0
	global_load_dwordx4 v[6:9], v[6:7], off offset:2048
	s_nop 0
	global_load_dwordx4 v[54:57], v[14:15], off offset:1152
	global_load_dwordx4 v[70:73], v[14:15], off offset:1024
	global_load_dwordx4 v[34:37], v[14:15], off offset:128
	global_load_dwordx4 v[58:61], v[14:15], off
	s_movk_i32 s0, 0x110
	v_ashrrev_i32_e32 v11, 31, v10
	v_mul_lo_u32 v14, v16, s0
	v_and_b32_e32 v18, 15, v13
	v_add3_u32 v159, 16, v14, v4
	v_lshlrev_b32_e32 v14, 2, v12
	v_readlane_b32 s1, v254, 58
	v_readlane_b32 s8, v254, 59
	v_lshl_add_u64 v[148:149], s[94:95], 0, v[10:11]
	v_ashrrev_i32_e32 v11, 7, v13
	v_add_u32_e32 v163, s1, v14
	v_add_u32_e32 v160, s8, v14
	v_lshl_or_b32 v14, v11, 4, v18
	v_ashrrev_i32_e32 v20, 6, v13
	v_mul_lo_u32 v10, v14, s0
	v_bfe_u32 v19, v13, 4, 2
	v_add_u32_e32 v16, 16, v10
	v_lshlrev_b32_e32 v10, 1, v20
	s_movk_i32 s0, 0x90
	v_and_b32_e32 v15, 2, v10
	v_mul_lo_u32 v23, v14, s0
	v_lshlrev_b32_e32 v10, 3, v19
	v_readlane_b32 s8, v254, 60
	v_lshlrev_b32_e32 v21, 4, v19
	v_lshlrev_b32_e32 v132, 2, v19
	v_add3_u32 v19, s8, v23, v10
	v_bfe_u32 v23, v13, 2, 2
	v_or_b32_e32 v23, v10, v23
	v_mul_u32_u24_e32 v23, 0x88, v23
	v_lshl_add_u32 v23, v23, 1, 16
	v_lshlrev_b32_e32 v134, 4, v20
	v_lshl_add_u32 v20, v20, 5, v23
	v_and_b32_e32 v17, 24, v17
	s_mov_b32 s0, 0x8800
	v_add3_u32 v158, v20, v17, s0
	v_add_u32_e32 v17, v23, v17
	v_lshlrev_b32_e32 v23, 4, v15
	v_or_b32_e32 v24, v23, v18
	v_or_b32_e32 v23, v23, v132
	v_cmp_le_i32_e32 vcc, v23, v14
	v_cmp_le_i32_e64 s[22:23], v15, v11
	v_cmp_lt_i32_e64 s[18:19], v15, v11
	v_cndmask_b32_e64 v25, 0, 1, vcc
	v_cmp_lt_i32_e32 vcc, v23, v14
	v_add_u32_e32 v20, s8, v21
	v_add_u32_e32 v166, s1, v21
	v_cndmask_b32_e64 v26, 0, 1, vcc
	v_cndmask_b32_e64 v25, v26, v25, s[28:29]
	v_and_b32_e32 v25, 1, v25
	v_cmp_eq_u32_e64 s[10:11], 1, v25
	v_or_b32_e32 v25, s46, v23
	v_cmp_gt_i32_e64 s[12:13], v14, v25
	v_or_b32_e32 v25, 2, v23
	v_cmp_le_i32_e32 vcc, v25, v14
	v_or_b32_e32 v23, 3, v23
	s_lshl_b32 s40, s46, 10
	v_cndmask_b32_e64 v26, 0, 1, vcc
	v_cmp_lt_i32_e32 vcc, v25, v14
	v_ashrrev_i32_e32 v135, 31, v134
	v_add_u32_e32 v22, 16, v21
	v_cndmask_b32_e64 v25, 0, 1, vcc
	v_cndmask_b32_e64 v25, v25, v26, s[28:29]
	v_and_b32_e32 v25, 1, v25
	v_cmp_le_i32_e32 vcc, v23, v14
	v_cmp_eq_u32_e64 s[16:17], 1, v25
	v_mul_u32_u24_e32 v24, 0x110, v24
	v_cndmask_b32_e64 v25, 0, 1, vcc
	v_cmp_lt_i32_e32 vcc, v23, v14
	v_cmp_gt_u32_e64 s[24:25], 8, v13
	v_add_u32_e32 v133, 0xcc00, v17
	v_cndmask_b32_e64 v23, 0, 1, vcc
	v_cndmask_b32_e64 v23, v23, v25, s[28:29]
	v_or_b32_e32 v25, 1, v15
	v_lshl_or_b32 v11, v25, 4, v132
	v_and_b32_e32 v23, 1, v23
	v_cmp_le_i32_e32 vcc, v11, v14
	v_cmp_eq_u32_e64 s[26:27], 1, v23
	v_lshlrev_b32_e32 v23, 5, v15
	v_cndmask_b32_e64 v15, 0, 1, vcc
	v_cmp_lt_i32_e32 vcc, v11, v14
	v_lshlrev_b32_e32 v25, 5, v25
	v_add_u32_e32 v141, 0xcc40, v17
	v_cndmask_b32_e64 v26, 0, 1, vcc
	v_cndmask_b32_e64 v15, v26, v15, s[28:29]
	v_and_b32_e32 v15, 1, v15
	v_cmp_eq_u32_e32 vcc, 1, v15
	v_or_b32_e32 v15, s46, v11
	v_cmp_gt_i32_e64 s[8:9], v14, v15
	v_or_b32_e32 v15, 2, v11
	v_cmp_le_i32_e64 s[0:1], v15, v14
	v_or_b32_e32 v11, 3, v11
	v_add_u32_e32 v139, 0xcc80, v17
	v_cndmask_b32_e64 v26, 0, 1, s[0:1]
	v_cmp_lt_i32_e64 s[0:1], v15, v14
	v_add_u32_e32 v137, 0xccc0, v17
	v_add_u32_e32 v165, v16, v21
	v_cndmask_b32_e64 v15, 0, 1, s[0:1]
	v_cndmask_b32_e64 v15, v15, v26, s[28:29]
	v_and_b32_e32 v15, 1, v15
	v_cmp_le_i32_e64 s[0:1], v11, v14
; DEV unsigned pack2h(float a, float b) { unsigned r; asm("v_cvt_pk_bf16_f32 %0, %1, %2" : "=v"(r) : "v"(a), "v"(b)); return r; }
; DEV float bflo(unsigned u) { return __uint_as_float(u << 16); }
; DEV float bfhi(unsigned u) { return __uint_as_float(u & 0xffff0000u); }
; DEV void gla_item(const Params& p, int layer, int it, int L) {
;     ...
;   auto gate8 = [&](const u32x4& q, const u32x4& kk, const u32x4& e, const u32x4& d, u32x4& qe, u32x4& ke, u32x4& kd, f32x4& dlo, f32x4& dhi) {
;     const unsigned qa[4] = {q.x, q.y, q.z, q.w}, ka[4] = {kk.x, kk.y, kk.z, kk.w}, ea[4] = {e.x, e.y, e.z, e.w}, da[4] = {d.x, d.y, d.z, d.w};
;     unsigned qo[4], ko[4], dd[4]; float df[8];
; #pragma unroll
;     for (int i = 0; i < 4; ++i) {
;       const float e0 = bflo(ea[i]), e1 = bfhi(ea[i]);
;       const float r0 = __builtin_amdgcn_rcpf(e0), r1 = __builtin_amdgcn_rcpf(e1);
;       const float k0 = bflo(ka[i]) * r0, k1 = bfhi(ka[i]) * r1;
;       const float d0 = bflo(da[i]), d1 = bfhi(da[i]);
;       qo[i] = pack2h(bflo(qa[i]) * e0 * 0.08838834764831845f, bfhi(qa[i]) * e1 * 0.08838834764831845f);
;       ko[i] = pack2h(k0, k1);
;       dd[i] = pack2h(k0 * d0, k1 * d1);
;       df[2 * i] = d0; df[2 * i + 1] = d1;
;     }
;     qe = (u32x4){qo[0], qo[1], qo[2], qo[3]}; ke = (u32x4){ko[0], ko[1], ko[2], ko[3]}; kd = (u32x4){dd[0], dd[1], dd[2], dd[3]};
;     dlo = (f32x4){df[0], df[1], df[2], df[3]}; dhi = (f32x4){df[4], df[5], df[6], df[7]};
;   };
;   f32x4 S[8];
; #pragma unroll
;   for (int i = 0; i < 8; ++i) S[i] = (f32x4){0.f, 0.f, 0.f, 0.f};
;   prefetch(0);
;   for (int nproc = 0; nproc < NCH; ++nproc) {
;     {
;       u32x4 qe, ke, kd; f32x4 dlo, dhi;
;       gate8(pq0, pk0, pe0, pd0, qe, ke, kd, dlo, dhi);
;       *(u32x4*)(Qs + prow * QS + pc) = qe; *(u32x4*)(Ksm + prow * QS + pc) = ke; *(u32x4*)(KD + prow * QS + pc) = kd;
;       if (prow == 0) { *(f32x4*)(DEC + pc) = dlo; *(f32x4*)(DEC + pc + 4) = dhi; }
;       gate8(pq1, pk1, pe1, pd1, qe, ke, kd, dlo, dhi);
;       *(u32x4*)(Qs + prow * QS + 64 + pc) = qe; *(u32x4*)(Ksm + prow * QS + 64 + pc) = ke; *(u32x4*)(KD + prow * QS + 64 + pc) = kd;
;       if (prow == 0) { *(f32x4*)(DEC + 64 + pc) = dlo; *(f32x4*)(DEC + 64 + pc + 4) = dhi; }
;       *(u32x4*)(Vs + prow * QS + pc) = pv0; *(u32x4*)(Vs + prow * QS + 64 + pc) = pv1;
;     }
	v_cmp_eq_u32_e64 s[14:15], 1, v15
	v_mul_u32_u24_e32 v26, 0x90, v18
	v_cndmask_b32_e64 v15, 0, 1, s[0:1]
	v_cmp_lt_i32_e64 s[0:1], v11, v14
	v_bitop3_b32 v14, v13, 63, 15 bitop3:0x6c
	v_cndmask_b32_e64 v140, v14, v18, s[28:29]
	v_cndmask_b32_e64 v11, 0, 1, s[0:1]
	s_add_u32 s0, s76, s56
	s_addc_u32 s1, s77, 0
	s_lshl_b32 s42, s46, 11
	v_cndmask_b32_e64 v11, v11, v15, s[28:29]
	s_add_u32 s42, s82, s42
	v_and_b32_e32 v11, 1, v11
	s_addc_u32 s46, s83, 0
	s_lshl_b32 s45, s45, 9
	v_cmp_eq_u32_e64 s[20:21], 1, v11
	v_mul_u32_u24_e32 v11, 0x110, v18
	s_add_u32 s42, s42, s45
	v_add3_u32 v157, 16, v11, v10
	v_or_b32_e32 v11, 16, v18
	v_bitop3_b32 v14, v13, 47, 15 bitop3:0x6c
	s_addc_u32 s45, s46, 0
	s_lshl_b32 s46, s39, 1
	v_cndmask_b32_e64 v138, v14, v11, s[28:29]
	v_or_b32_e32 v11, 32, v18
	v_bitop3_b32 v15, v13, 31, 15 bitop3:0x6c
	s_add_u32 s50, s42, s46
	v_or_b32_e32 v14, 48, v18
	v_cndmask_b32_e64 v136, v15, v11, s[28:29]
	v_bitop3_b32 v11, v13, 15, v13 bitop3:0xc
	s_addc_u32 s51, s45, 0
	v_cndmask_b32_e64 v130, v11, v14, s[28:29]
	v_lshl_add_u64 v[14:15], v[134:135], 1, s[50:51]
	v_mov_b32_e32 v11, v5
	v_lshl_add_u64 v[150:151], v[14:15], 0, v[10:11]
	v_mov_b32_e32 v14, 0
	v_add_u32_e32 v156, 0x1100, v157
	v_add_u32_e32 v154, 0x2200, v157
	v_add_u32_e32 v147, 0x3300, v157
	v_lshl_add_u64 v[152:153], s[0:1], 0, v[4:5]
	s_lshl_b32 s56, s41, 1
	v_lshlrev_b32_e32 v4, 1, v12
	s_lshl_b32 s98, s44, 1
	s_lshl_b32 s64, s47, 1
	v_add_u32_e32 v164, v22, v24
	v_add_u32_e32 v162, v19, v23
	v_add_u32_e32 v161, v19, v25
	v_add_u32_e32 v155, v20, v26
	s_mov_b32 s46, s37
	v_mov_b32_e32 v15, v14
	v_mov_b32_e32 v16, v14
	v_mov_b32_e32 v17, v14
	v_mov_b32_e32 v10, v14
	v_mov_b32_e32 v11, v14
	v_mov_b32_e32 v12, v14
	v_mov_b32_e32 v13, v14
	v_mov_b32_e32 v18, v14
	v_mov_b32_e32 v19, v14
	v_mov_b32_e32 v20, v14
	v_mov_b32_e32 v21, v14
	v_mov_b32_e32 v22, v14
	v_mov_b32_e32 v23, v14
	v_mov_b32_e32 v24, v14
	v_mov_b32_e32 v25, v14
	v_mov_b32_e32 v26, v14
	v_mov_b32_e32 v27, v14
	v_mov_b32_e32 v28, v14
	v_mov_b32_e32 v29, v14
	v_mov_b32_e32 v30, v14
	v_mov_b32_e32 v31, v14
	v_mov_b32_e32 v32, v14
	v_mov_b32_e32 v33, v14
	v_mov_b32_e32 v38, v14
	v_mov_b32_e32 v39, v14
	v_mov_b32_e32 v40, v14
	v_mov_b32_e32 v41, v14
	v_mov_b32_e32 v46, v14
	v_mov_b32_e32 v47, v14
	v_mov_b32_e32 v48, v14
	v_mov_b32_e32 v49, v14
	s_waitcnt vmcnt(0)
.LBB0_106:
	s_waitcnt vmcnt(4)
	v_lshlrev_b32_e32 v77, 16, v62
	v_rcp_f32_e32 v78, v77
	v_lshlrev_b32_e32 v76, 16, v70
	v_and_b32_e32 v62, 0xffff0000, v62
	v_and_b32_e32 v70, 0xffff0000, v70
	v_mul_f32_e32 v76, v78, v76
	v_rcp_f32_e32 v78, v62
	v_lshlrev_b32_e32 v74, 16, v66
	v_and_b32_e32 v75, 0xffff0000, v66
	v_lshlrev_b32_e32 v66, 16, v58
	v_and_b32_e32 v58, 0xffff0000, v58
	v_mul_f32_e32 v70, v78, v70
	v_lshlrev_b32_e32 v78, 16, v63
	v_mul_f32_e32 v66, v77, v66
	v_mul_f32_e32 v58, v62, v58
	v_rcp_f32_e32 v79, v78
	v_mul_f32_e32 v66, 0x3db504f3, v66
	v_mul_f32_e32 v58, 0x3db504f3, v58
	v_cvt_pk_bf16_f32 v58, v66, v58
	v_cvt_pk_bf16_f32 v62, v76, v70
	v_mul_f32_e32 v66, v76, v74
	v_mul_f32_e32 v70, v70, v75
	v_cvt_pk_bf16_f32 v70, v66, v70
	v_lshlrev_b32_e32 v66, 16, v71
	v_and_b32_e32 v63, 0xffff0000, v63
	v_mul_f32_e32 v66, v79, v66
	v_rcp_f32_e32 v79, v63
	v_and_b32_e32 v71, 0xffff0000, v71
	v_lshlrev_b32_e32 v76, 16, v67
	v_and_b32_e32 v77, 0xffff0000, v67
	v_mul_f32_e32 v71, v79, v71
	v_lshlrev_b32_e32 v79, 16, v64
	v_rcp_f32_e32 v80, v79
	v_lshlrev_b32_e32 v67, 16, v59
	v_and_b32_e32 v59, 0xffff0000, v59
	v_mul_f32_e32 v67, v78, v67
	v_mul_f32_e32 v59, v63, v59
	v_lshlrev_b32_e32 v78, 16, v72
	v_and_b32_e32 v64, 0xffff0000, v64
	v_mul_f32_e32 v67, 0x3db504f3, v67
	v_mul_f32_e32 v59, 0x3db504f3, v59
	v_mul_f32_e32 v78, v80, v78
	v_rcp_f32_e32 v80, v64
	v_cvt_pk_bf16_f32 v59, v67, v59
	v_cvt_pk_bf16_f32 v63, v66, v71
	v_mul_f32_e32 v66, v66, v76
	v_mul_f32_e32 v67, v71, v77
	v_cvt_pk_bf16_f32 v71, v66, v67
	v_lshlrev_b32_e32 v66, 16, v68
	v_and_b32_e32 v67, 0xffff0000, v68
	v_lshlrev_b32_e32 v68, 16, v60
	v_and_b32_e32 v72, 0xffff0000, v72
	v_mul_f32_e32 v68, v79, v68
	v_lshlrev_b32_e32 v79, 16, v65
	v_and_b32_e32 v60, 0xffff0000, v60
	v_mul_f32_e32 v72, v80, v72
	v_rcp_f32_e32 v80, v79
	v_mul_f32_e32 v60, v64, v60
	v_mul_f32_e32 v68, 0x3db504f3, v68
	v_mul_f32_e32 v60, 0x3db504f3, v60
	v_cvt_pk_bf16_f32 v60, v68, v60
	v_cvt_pk_bf16_f32 v64, v78, v72
	v_mul_f32_e32 v68, v78, v66
	v_lshlrev_b32_e32 v78, 16, v73
	v_and_b32_e32 v65, 0xffff0000, v65
	v_mul_f32_e32 v78, v80, v78
	v_rcp_f32_e32 v80, v65
	v_lshlrev_b32_e32 v81, 16, v61
	v_and_b32_e32 v61, 0xffff0000, v61
	v_mul_f32_e32 v72, v72, v67
	v_and_b32_e32 v73, 0xffff0000, v73
	v_mul_f32_e32 v61, v65, v61
	v_cvt_pk_bf16_f32 v72, v68, v72
	v_lshlrev_b32_e32 v68, 16, v69
	v_and_b32_e32 v69, 0xffff0000, v69
	v_mul_f32_e32 v79, v79, v81
	v_mul_f32_e32 v73, v80, v73
	v_mul_f32_e32 v61, 0x3db504f3, v61
	v_mul_f32_e32 v79, 0x3db504f3, v79
	v_cvt_pk_bf16_f32 v61, v79, v61
	v_cvt_pk_bf16_f32 v65, v78, v73
	v_mul_f32_e32 v73, v73, v69
	v_mul_f32_e32 v78, v78, v68
	v_cvt_pk_bf16_f32 v73, v78, v73
	ds_write_b128 v159, v[58:61]
	ds_write_b128 v159, v[62:65] offset:17408
	ds_write_b128 v159, v[70:73] offset:52224
	s_and_saveexec_b64 s[0:1], s[24:25]
	s_cbranch_execz .LBB0_108
	ds_write_b128 v163, v[74:77]
	ds_write_b128 v163, v[66:69] offset:16

; DEV int tidx() { int t = threadIdx.x; asm volatile("" : "+v"(t)); return t; }
; #define LBAR() do { asm volatile("s_waitcnt lgkmcnt(0)" ::: "memory"); __builtin_amdgcn_s_barrier(); asm volatile("" ::: "memory"); } while (0)
; DEV void attn_load(const Params& p, const AttnDec& d, int tid, u32x4 (&kr)[4], u32x4 (&vr)[4], bf16x8 (&qf)[2]) {
;   const int row0 = tid >> 3, ch = (tid & 7) * 8;
; #pragma unroll
;   for (int i = 0; i < 4; ++i) {
;     int ks = row0 + 64 * i, kj = 128 * d.pb - 64 + ks;
;     bool ok = (kj >= 0) && (kj < d.sub);
;     long tok = d.tbase + (long)(ok ? kj : 0) * d.D;
;     u32x4 z = {0u, 0u, 0u, 0u};
;     kr[i] = ok ? *(const u32x4*)(p.ha + ((long)d.colk * p.GT + tok) * 64 + ch) : z;
;     vr[i] = ok ? *(const u32x4*)(p.ha + ((long)d.colv * p.GT + tok) * 64 + ch) : z;
;   }
;   const int w = tid >> 6, l = tid & 63, fr = l & 15, kq = l >> 4;
;   const long qtok = d.tbase + (long)(128 * d.pb + 16 * w + fr) * d.D;
;   qf[0] = *(const bf16x8*)(p.ha + ((long)d.colq * p.GT + qtok) * 64 + kq * 8);
;   qf[1] = *(const bf16x8*)(p.ha + ((long)d.colq * p.GT + qtok) * 64 + 32 + kq * 8);
; }
; DEV void attn_loop(const Params& p, int* ctr, int nA, int L) {
;     ...
;   volatile int* slot = (volatile int*)(smem + 120000);
;   const int tid = tidx();
;   const int row0 = tid >> 3, ch = (tid & 7) * 8;
;   int pending = 0;
;   if (tid == 0) { slot[0] = atomicAdd(ctr, 1); pending = atomicAdd(ctr, 1); }
;   LBAR();
;   int cur = slot[0];
;   if (cur >= nA) return;
;   u32x4 kr[4], vr[4]; bf16x8 qn[2];
;   { AttnDec d = attn_decode(cur, L); attn_load(p, d, tid, kr, vr, qn); }
.LBB0_130:
	s_or_b64 exec, exec, s[8:9]
	v_mov_b32_e32 v252, v93
	v_readlane_b32 s0, v255, 1
	s_mul_i32 s8, s0, 24
	s_and_b64 s[0:1], s[6:7], exec
	s_cselect_b32 s44, 5, 4
	s_lshl_b32 s45, s8, s44
	s_add_i32 s0, 16, 0x1d4c0
	s_cmp_lg_u32 s0, -1
	s_cselect_b32 s8, s0, 0
	s_mov_b64 s[0:1], src_shared_base
	s_cselect_b32 s0, s1, 0
	s_waitcnt lgkmcnt(0)
	s_barrier
	v_mov_b32_e32 v0, s8
	v_mov_b32_e32 v1, s0
	flat_load_dword v58, v[0:1] sc0 sc1
	s_waitcnt vmcnt(0) lgkmcnt(0)
	v_cmp_gt_i32_e64 s[0:1], s45, v58
	s_and_saveexec_b64 s[28:29], s[0:1]
	s_cbranch_execz .LBB0_169
	v_ashrrev_i32_e32 v0, s44, v58
	s_mov_b32 s0, 0x2aaaaaab
	v_mul_hi_i32 v2, v0, s0
	v_lshlrev_b32_e32 v60, 3, v59
	v_lshrrev_b32_e32 v3, 31, v2
	v_ashrrev_i32_e32 v2, 2, v2
	v_and_b32_e32 v1, 56, v60
	v_add_u32_e32 v2, v2, v3
	s_movk_i32 s0, 0xffe8
	v_mad_u64_u32 v[48:49], s[0:1], v2, s0, v[0:1]
	s_lshl_b32 s8, -1, s44
	v_ashrrev_i32_e32 v0, 2, v48
	v_bitop3_b32 v4, v58, s8, v58 bitop3:0x30
	v_and_b32_e32 v50, -2, v0
	s_and_b64 s[0:1], s[6:7], exec
	v_ashrrev_i32_e32 v121, 3, v59
	v_lshrrev_b32_e32 v6, v50, v4
	v_ashrrev_i32_e32 v3, 31, v2
	s_cselect_b32 s56, 12, 11
	v_lshl_add_u32 v0, 1, v50, 31
	v_lshlrev_b64 v[52:53], s56, v[2:3]
	v_subrev_u32_e32 v130, 64, v121
	v_lshlrev_b32_e32 v49, 7, v6
	v_lshrrev_b32_e64 v55, v50, s90
	v_and_or_b32 v52, v0, v4, v52
	v_add_u32_e32 v4, v49, v130
	v_cmp_lt_i32_e64 s[0:1], -1, v4
	v_cmp_lt_i32_e64 s[6:7], v4, v55
	v_mov_b32_e32 v0, 0
	v_add_u32_e32 v54, 24, v48
	v_add_u32_e32 v51, 48, v48
	s_and_b64 s[6:7], s[0:1], s[6:7]
	v_lshlrev_b32_e32 v56, 1, v1
	v_mov_b32_e32 v1, v0
	v_mov_b32_e32 v2, v0
	v_mov_b32_e32 v3, v0
	v_mov_b32_e32 v36, v0
	v_mov_b32_e32 v37, v0
	v_mov_b32_e32 v38, v0
	v_mov_b32_e32 v39, v0
	s_and_saveexec_b64 s[0:1], s[6:7]
	s_cbranch_execz .LBB0_133
	v_lshlrev_b64 v[0:1], v50, v[4:5]
	v_lshl_add_u64 v[0:1], v[0:1], 0, v[52:53]
	v_mad_i64_i32 v[2:3], s[6:7], v54, s34, v[0:1]
	v_lshlrev_b64 v[2:3], 7, v[2:3]
	v_mad_i64_i32 v[0:1], s[6:7], v51, s34, v[0:1]
	v_lshl_add_u64 v[2:3], s[74:75], 0, v[2:3]
	v_mov_b32_e32 v57, v5
	v_lshlrev_b64 v[0:1], 7, v[0:1]
	v_lshl_add_u64 v[2:3], v[2:3], 0, v[56:57]
	v_lshl_add_u64 v[0:1], s[74:75], 0, v[0:1]
	v_lshl_add_u64 v[6:7], v[0:1], 0, v[56:57]
	global_load_dwordx4 v[0:3], v[2:3], off
	s_nop 0
	global_load_dwordx4 v[36:39], v[6:7], off

; #define LBAR() do { asm volatile("s_waitcnt lgkmcnt(0)" ::: "memory"); __builtin_amdgcn_s_barrier(); asm volatile("" ::: "memory"); } while (0)
; DEV void attn_load(const Params& p, const AttnDec& d, int tid, u32x4 (&kr)[4], u32x4 (&vr)[4], bf16x8 (&qf)[2]) {
;   const int row0 = tid >> 3, ch = (tid & 7) * 8;
; #pragma unroll
;   for (int i = 0; i < 4; ++i) {
;     int ks = row0 + 64 * i, kj = 128 * d.pb - 64 + ks;
;     bool ok = (kj >= 0) && (kj < d.sub);
;     long tok = d.tbase + (long)(ok ? kj : 0) * d.D;
;     u32x4 z = {0u, 0u, 0u, 0u};
;     kr[i] = ok ? *(const u32x4*)(p.ha + ((long)d.colk * p.GT + tok) * 64 + ch) : z;
;     vr[i] = ok ? *(const u32x4*)(p.ha + ((long)d.colv * p.GT + tok) * 64 + ch) : z;
; DEV void attn_loop(const Params& p, int* ctr, int nA, int L) {
;     ...
;   while (cur < nA) {
;     AttnDec d = attn_decode(cur, L);
; #pragma unroll
;     for (int i = 0; i < 4; ++i) {
;       int ks = row0 + 64 * i;
;       *(u32x4*)(Ks + ks * AKS + ch) = kr[i];
;       *(u32x4*)(Vs + ks * AKS + ch) = vr[i];
;     }
;     if (tid == 0) { slot[1] = pending; pending = atomicAdd(ctr, 1); }
;     bf16x8 qc[2] = {qn[0], qn[1]};
;     LBAR();
;     const int nxt = slot[1];
;     if (nxt < nA) { AttnDec dn = attn_decode(nxt, L); attn_load(p, dn, tid, kr, vr, qn); }
.LBB0_147:
	ds_write_b128 v165, v[8:11]
	s_waitcnt vmcnt(2)
	ds_write_b128 v165, v[36:39] offset:36864
	ds_write_b128 v165, v[12:15] offset:9216
	ds_write_b128 v165, v[40:43] offset:46080
	ds_write_b128 v165, v[16:19] offset:18432
	ds_write_b128 v165, v[44:47] offset:55296
	ds_write_b128 v165, v[20:23] offset:27648
	ds_write_b128 v165, v[24:27] offset:64512
	s_and_saveexec_b64 s[24:25], vcc
	s_cbranch_execz .LBB0_151
	s_add_i32 s0, 16, 0x1d4c4
	v_mov_b32_e32 v2, s0
	v_mov_b32_e32 v93, v252
	ds_write_b32 v2, v93
	v_mov_b32_e32 v3, 1
	global_atomic_add v252, v[78:79], v3, off sc0
.LBB0_151:
	s_or_b64 exec, exec, s[24:25]
	s_mov_b64 s[0:1], src_shared_base
	s_add_i32 s0, 16, 0x1d4c4
	s_cmp_lg_u32 s0, -1
	s_cselect_b32 s0, s0, 0
	s_cselect_b32 s1, s1, 0
	s_waitcnt lgkmcnt(0)
	s_barrier
	v_mov_b32_e32 v2, s0
	ds_read_b32 v167, v2
	v_mov_b64_e32 v[28:29], v[48:49]
	v_mov_b64_e32 v[32:33], v[52:53]
	v_mov_b64_e32 v[30:31], v[50:51]
	v_mov_b64_e32 v[34:35], v[54:55]
	s_waitcnt lgkmcnt(0)
	v_cmp_gt_i32_e64 s[0:1], s45, v167
	v_cmp_le_i32_e64 s[24:25], s45, v167
	s_and_saveexec_b64 s[42:43], s[0:1]
	s_cbranch_execz .LBB0_163
	v_ashrrev_i32_e32 v2, s44, v167
	s_mov_b32 s0, 0x2aaaaaab
	v_mul_hi_i32 v3, v2, s0
	v_lshrrev_b32_e32 v4, 31, v3
	v_ashrrev_i32_e32 v3, 2, v3
	v_add_u32_e32 v8, v3, v4
	s_movk_i32 s0, 0xffe8
	v_mad_u64_u32 v[2:3], s[0:1], v8, s0, v[2:3]
	v_ashrrev_i32_e32 v3, 2, v2
	v_and_b32_e32 v10, s64, v167
	v_and_b32_e32 v28, -2, v3
	v_lshrrev_b32_e32 v3, v28, v10
	v_lshlrev_b32_e32 v3, 7, v3
	v_lshrrev_b32_e64 v20, v28, s90
	v_add_u32_e32 v4, v3, v130
	v_cmp_gt_i32_e64 s[0:1], 0, v4
	v_cmp_ge_i32_e64 s[26:27], v4, v20
	s_or_b64 s[0:1], s[0:1], s[26:27]
	s_and_saveexec_b64 s[26:27], s[0:1]
	s_xor_b64 s[0:1], exec, s[26:27]
	s_or_saveexec_b64 s[0:1], s[0:1]
	v_ashrrev_i32_e32 v9, 31, v8
	v_lshl_add_u32 v11, 1, v28, 31
	v_lshlrev_b64 v[30:31], s56, v[8:9]
	v_mov_b32_e32 v8, 0
	v_and_or_b32 v30, v11, v10, v30
	v_add_u32_e32 v32, 24, v2
	v_add_u32_e32 v29, 48, v2
	v_mov_b32_e32 v9, 0
	v_mov_b32_e32 v10, 0
	v_mov_b32_e32 v11, 0
	v_mov_b32_e32 v36, 0
	v_mov_b32_e32 v37, v8
	v_mov_b32_e32 v38, v8
	v_mov_b32_e32 v39, v8
	s_xor_b64 exec, exec, s[0:1]
	s_cbranch_execz .LBB0_154
	v_lshlrev_b64 v[8:9], v28, v[4:5]
	v_lshl_add_u64 v[8:9], v[8:9], 0, v[30:31]
	v_mad_i64_i32 v[10:11], s[26:27], v32, s34, v[8:9]
	v_lshlrev_b64 v[10:11], 7, v[10:11]
	v_mad_i64_i32 v[8:9], s[26:27], v29, s34, v[8:9]
	v_lshl_add_u64 v[10:11], v[112:113], 0, v[10:11]
	v_lshlrev_b64 v[8:9], 7, v[8:9]
	v_lshl_add_u64 v[12:13], v[112:113], 0, v[8:9]
	global_load_dwordx4 v[8:11], v[10:11], off
	s_nop 0
	global_load_dwordx4 v[36:39], v[12:13], off

; #define WAIT_V(n) asm volatile("s_waitcnt vmcnt(" #n ")" ::: "memory")
; #define BAR __builtin_amdgcn_s_barrier()
; DEV void gemm_core(const u16* __restrict__ A, int lda, const u16* __restrict__ Bt, int ldb, int K,
;                    int brow, int bcol, f32x4 (&acc)[2][2][4][2]) {
;   const int wid = threadIdx.x >> 6, lane = threadIdx.x & 63, wr = wid >> 2, wc = wid & 3, fr = lane & 15, fq = lane >> 4;
;   bf16x8 At[4][2], B0[2][2], B1[2][2];
;   const int lo_ = (fr * 64 + fq * 16) ^ ((fr >> 3) << 5); const int aoff = wr * 8192 + lo_, boff = wc * 4096 + lo_;
;   const int nt = K / BK;
;   STAGE(SB(0, 0), Bt, ldb, bcol, 0); STAGE(SA(0, 0), A, lda, brow, 0);
;   STAGE(SB(0, 1), Bt, ldb, bcol + HALF, 0); STAGE(SA(0, 1), A, lda, brow + HALF, 0);
;   if (wr == 1) BAR;
;   WAIT_V(4); BAR;
;   STAGE(SB(1, 0), Bt, ldb, bcol, 1); STAGE(SA(1, 0), A, lda, brow, 1); STAGE(SB(1, 1), Bt, ldb, bcol + HALF, 1);
;   WAIT_V(6); BAR;
;   for (int t = 0; t < nt - 2; t += 2) {
.LBB0_190:
	s_or_b64 exec, exec, s[10:11]
	s_mul_i32 s39, s12, s48
	v_or_b32_e32 v139, s39, v183
	v_mad_i32_i24 v4, s12, v184, v139
	v_add_u32_e32 v138, s87, v178
	v_lshl_add_u64 v[140:141], v[4:5], 1, s[8:9]
	v_readfirstlane_b32 s40, v138
	v_mad_i32_i24 v4, s12, v185, v139
	v_add_u32_e32 v139, 0x2000, v138
	s_mov_b32 m0, s40
	v_readfirstlane_b32 s40, v139
	s_mul_i32 s10, s13, s63
	s_waitcnt vmcnt(4)
	s_barrier
	global_load_lds_dwordx4 v[140:141], off
	v_lshl_add_u64 v[140:141], v[4:5], 1, s[8:9]
	s_mov_b32 m0, s40
	s_lshl_b32 s11, s12, 7
	global_load_lds_dwordx4 v[140:141], off
	v_or_b32_e32 v141, s10, v183
	v_add_u32_e32 v140, 0x8000, v132
	v_mad_i32_i24 v4, s13, v184, v141
	v_readfirstlane_b32 s40, v140
	v_lshl_add_u64 v[148:149], v[4:5], 1, s[6:7]
	s_mov_b32 m0, s40
	v_mad_i32_i24 v4, s13, v185, v141
	global_load_lds_dwordx4 v[148:149], off
	v_add_u32_e32 v148, 0xa000, v132
	s_add_i32 s11, s39, s11
	v_readfirstlane_b32 s40, v148
	v_lshl_add_u64 v[150:151], v[4:5], 1, s[6:7]
	s_mov_b32 m0, s40
	v_or_b32_e32 v141, s11, v183
	global_load_lds_dwordx4 v[150:151], off
	v_add_u32_e32 v150, s62, v178
	v_mad_i32_i24 v4, s12, v184, v141
	v_readfirstlane_b32 s11, v150
	v_add_u32_e32 v151, 0x2000, v150
	v_lshl_add_u64 v[152:153], v[4:5], 1, s[8:9]
	s_mov_b32 m0, s11
	v_mad_i32_i24 v4, s12, v185, v141
	v_readfirstlane_b32 s11, v151
	global_load_lds_dwordx4 v[152:153], off
	v_lshl_add_u64 v[152:153], v[4:5], 1, s[8:9]
	s_mov_b32 m0, s11
	s_lshl_b32 s38, s38, 8
	global_load_lds_dwordx4 v[152:153], off
	s_lshl_b32 s36, s36, 8
	s_add_i32 s40, s63, 0x80
	s_sub_i32 s36, s38, s36
	s_mul_i32 s40, s13, s40
	s_bitset1_b32 s36, 7
	v_mov_b32_e32 v4, s40
	s_mul_i32 s36, s12, s36
	v_mad_i32_i24 v152, s13, v185, v4
	v_mad_i32_i24 v153, s13, v184, v4
	v_mov_b32_e32 v4, s36
	s_mul_i32 s36, s13, s37
	s_lshl_b32 s36, s36, 8
	s_waitcnt vmcnt(6)
	v_mad_i32_i24 v154, s12, v185, v4
	v_mad_i32_i24 v155, s12, v184, v4
	v_mov_b32_e32 v4, s36
	s_lshr_b32 s11, s12, 6
	v_mad_i32_i24 v156, s13, v185, v4
	v_mad_i32_i24 v157, s13, v184, v4
	v_mov_b32_e32 v4, s39
	v_mul_i32_i24_e32 v149, s13, v184
	v_mul_i32_i24_e32 v141, s13, v185
	s_add_i32 s11, s11, -2
	v_mad_i32_i24 v158, s12, v185, v4
	v_mad_i32_i24 v159, s12, v184, v4
	.p2align	6
	s_nop 0
	v_readfirstlane_b32 s38, v132
	v_add_u32_e32 v160, 0xc000, v132
	v_add_u32_e32 v161, 0xe000, v132
	v_add_lshl_u32 v152, v187, v152, 1
	v_add_lshl_u32 v153, v187, v153, 1
	v_add_lshl_u32 v154, v187, v154, 1
	v_add_lshl_u32 v155, v187, v155, 1
	v_add_lshl_u32 v156, v187, v156, 1
	v_add_lshl_u32 v157, v187, v157, 1
	v_add_lshl_u32 v158, v187, v158, 1
	v_add_lshl_u32 v159, v187, v159, 1
	v_add_u32_e32 v152, 0x80, v152
	v_add_u32_e32 v153, 0x80, v153
	v_add_u32_e32 v154, 0x100, v154
	v_add_u32_e32 v155, 0x100, v155
	v_add_u32_e32 v156, 0x100, v156
	v_add_u32_e32 v157, 0x100, v157
	v_add_u32_e32 v158, 0x100, v158
	v_add_u32_e32 v159, 0x100, v159
	v_add_u32_e32 v199, s55, v182
	v_add_u32_e32 v250, s84, v182
	v_add_u32_e32 v251, s87, v182
	v_add_u32_e32 v252, s62, v182
	s_add_i32 m0, s38, 0xc000
	s_mov_b32 s36, 0
	s_barrier

; DEV unsigned pack2h(float a, float b) { unsigned r; asm("v_cvt_pk_bf16_f32 %0, %1, %2" : "=v"(r) : "v"(a), "v"(b)); return r; }
; DEV float bflo(unsigned u) { return __uint_as_float(u << 16); }
; DEV float bfhi(unsigned u) { return __uint_as_float(u & 0xffff0000u); }
; #define LBAR() do { asm volatile("s_waitcnt lgkmcnt(0)" ::: "memory"); __builtin_amdgcn_s_barrier(); asm volatile("" ::: "memory"); } while (0)
; DEV float sigm(float x) { return __builtin_amdgcn_rcpf(1.f + __expf(-x)); }
; DEV void gemm_phase(const GemmJob& J) {
;     ...
;       } else if (mode != 3) {
;         const bool isla = (mode == 1) && (bcol >= G_LAF);
;         u16* sw = (u16*)smem + (wr * 64 + fr) * 264 + wc * 32 + ((fq * 4) ^ ((fr & 8) >> 1));
;         const u16* sr = (const u16*)smem + (wid * 16 + (lane >> 5)) * 264 + (lane & 31) * 8;
;         const float* bp0 = J.bf;
;         if (isla) { const int gc = bcol + wc * 32 + fq * 4 - G_LAF; bp0 = (gc >= 512) ? (J.bb + gc - 512) : (J.bf + gc); }
;         LBAR();
;     ...
;               for (int m = 0; m < 4; ++m) {
;                 f32x4 v = acc[ai][bj][m][n];
;                 float v0 = v[0], v1 = v[1], v2 = v[2], v3 = v[3];
;                 if (mode == 4) {
;                   v0 = fmaxf(v0, 0.f); v1 = fmaxf(v1, 0.f); v2 = fmaxf(v2, 0.f); v3 = fmaxf(v3, 0.f);
;                   v0 *= v0; v1 *= v1; v2 *= v2; v3 *= v3;
;                 } else if (mode == 2) {
;                   const u32x2 gb = *(const u32x2*)(J.gate + (long)(brow + ai * HALF + wr * 64 + m * 16 + fr) * LDR + C_GB + bcol + bj * HALF + wc * 32 + n * 16 + fq * 4);
;                   v0 *= sigm(bflo(gb.x)); v1 *= sigm(bfhi(gb.x)); v2 *= sigm(bflo(gb.y)); v3 *= sigm(bfhi(gb.y));
;                 }
;                 u32x2 o; o.x = pack2h(v0, v1); o.y = pack2h(v2, v3);
;                 *(u32x2*)(sw + m * 16 * 264 + bj * HALF + n * 16) = o;
.LBB0_194:
	s_or_b64 exec, exec, s[6:7]
	v_mov_b32_e32 v156, v143
	s_and_b64 s[0:1], s[14:15], s[0:1]
	v_ashrrev_i32_e32 v157, 6, v156
	v_ashrrev_i32_e32 v201, 8, v156
	v_and_b32_e32 v200, 3, v157
	v_and_b32_e32 v202, 15, v156
	v_bfe_u32 v199, v156, 4, 2
	s_andn2_b64 vcc, exec, s[0:1]
	s_mov_b64 s[0:1], -1
	s_cbranch_vccz .LBB0_250
	v_and_b32_e32 v158, 63, v156
	s_andn2_b64 vcc, exec, s[18:19]
	s_cbranch_vccnz .LBB0_430
	v_lshlrev_b32_e32 v4, 6, v201
	s_cmp_gt_i32 s33, 37
	v_or_b32_e32 v130, v4, v202
	s_movk_i32 s6, 0x210
	v_lshlrev_b32_e32 v161, 2, v199
	v_lshrrev_b32_e32 v132, 1, v156
	s_cselect_b64 s[0:1], -1, 0
	v_mul_lo_u32 v130, v130, s6
	v_bitop3_b32 v132, v161, v132, 4 bitop3:0x78
	s_and_b64 s[12:13], s[90:91], s[0:1]
	v_add_u32_e32 v130, 16, v130
	v_lshlrev_b32_e32 v162, 5, v200
	v_lshlrev_b32_e32 v131, 6, v200
	v_lshlrev_b32_e32 v132, 1, v132
	s_waitcnt lgkmcnt(0)
	s_barrier
	s_ashr_i32 s49, s48, 31
	v_add3_u32 v159, v130, v131, v132
	v_or3_b32 v134, v162, s48, v161
	s_movk_i32 s6, 0x27ff
	v_or_b32_e32 v130, s63, v202
	s_cmp_gt_u32 s33, 39
	s_mov_b64 s[0:1], -1
	v_cmp_lt_i32_e64 s[8:9], s6, v134
	v_add_u32_e32 v163, v130, v4
	s_cselect_b64 s[6:7], -1, 0
	s_and_b64 vcc, exec, s[14:15]
	s_cbranch_vccz .Lgp1_skip
	v_mov_b64_e32 v[132:133], s[76:77]
	v_mad_i64_i32 v[132:133], vcc, v163, s61, v[132:133]
	v_lshl_add_u64 v[132:133], s[48:49], 1, v[132:133]
	v_lshlrev_b32_e32 v4, 1, v162
	v_lshl_add_u64 v[132:133], v[132:133], 0, v[4:5]
	v_lshlrev_b32_e32 v4, 1, v161
	v_lshl_add_u64 v[132:133], v[132:133], 0, v[4:5]
	v_add_co_u32_e32 v132, vcc, 0x2000, v132
	s_nop 1
	v_addc_co_u32_e32 v133, vcc, 0, v133, vcc
	global_load_dwordx2 v[166:167], v[132:133], off
	global_load_dwordx2 v[174:175], v[132:133], off offset:32
	global_load_dwordx2 v[208:209], v[132:133], off offset:256
	global_load_dwordx2 v[216:217], v[132:133], off offset:288
	v_add_co_u32_e32 v132, vcc, 0x30000, v132
	s_nop 1
	v_addc_co_u32_e32 v133, vcc, 0, v133, vcc
	global_load_dwordx2 v[168:169], v[132:133], off
	global_load_dwordx2 v[176:177], v[132:133], off offset:32
	global_load_dwordx2 v[210:211], v[132:133], off offset:256
	global_load_dwordx2 v[218:219], v[132:133], off offset:288
	v_add_co_u32_e32 v132, vcc, 0x30000, v132
	s_nop 1
	v_addc_co_u32_e32 v133, vcc, 0, v133, vcc
	global_load_dwordx2 v[170:171], v[132:133], off
	global_load_dwordx2 v[204:205], v[132:133], off offset:32
	global_load_dwordx2 v[212:213], v[132:133], off offset:256
	global_load_dwordx2 v[220:221], v[132:133], off offset:288
	v_add_co_u32_e32 v132, vcc, 0x30000, v132
	s_nop 1
	v_addc_co_u32_e32 v133, vcc, 0, v133, vcc
	global_load_dwordx2 v[172:173], v[132:133], off
	global_load_dwordx2 v[206:207], v[132:133], off offset:32
	global_load_dwordx2 v[214:215], v[132:133], off offset:256
	global_load_dwordx2 v[222:223], v[132:133], off offset:288
	v_add_co_u32_e32 v132, vcc, 0xf0000, v132
	s_nop 1
	v_addc_co_u32_e32 v133, vcc, 0, v133, vcc
	global_load_dwordx2 v[224:225], v[132:133], off
	global_load_dwordx2 v[232:233], v[132:133], off offset:32
	global_load_dwordx2 v[240:241], v[132:133], off offset:256
	global_load_dwordx2 v[248:249], v[132:133], off offset:288
	v_add_co_u32_e32 v132, vcc, 0x30000, v132
	s_nop 1
	v_addc_co_u32_e32 v133, vcc, 0, v133, vcc
	global_load_dwordx2 v[226:227], v[132:133], off
	global_load_dwordx2 v[234:235], v[132:133], off offset:32
	global_load_dwordx2 v[242:243], v[132:133], off offset:256
	global_load_dwordx2 v[250:251], v[132:133], off offset:288
	v_add_co_u32_e32 v132, vcc, 0x30000, v132
	s_nop 1
	v_addc_co_u32_e32 v133, vcc, 0, v133, vcc
	global_load_dwordx2 v[228:229], v[132:133], off
	global_load_dwordx2 v[236:237], v[132:133], off offset:32
	global_load_dwordx2 v[244:245], v[132:133], off offset:256
	global_load_dwordx2 v[252:253], v[132:133], off offset:288
	v_add_co_u32_e32 v132, vcc, 0x30000, v132
	s_nop 1
	v_addc_co_u32_e32 v133, vcc, 0, v133, vcc
	global_load_dwordx2 v[230:231], v[132:133], off
	global_load_dwordx2 v[238:239], v[132:133], off offset:32
	global_load_dwordx2 v[246:247], v[132:133], off offset:256
	global_load_dwordx2 v[154:155], v[132:133], off offset:288
.Lgp1_skip:
	s_and_b64 vcc, exec, s[12:13]
	s_cbranch_vccnz .LBB0_222
	s_andn2_b64 vcc, s[58:59], s[14:15]
	s_cbranch_vccnz .Lfast1_h0
	s_andn2_b64 vcc, exec, s[58:59]
	s_cbranch_vccnz .Lfast4_h0
	s_and_b64 vcc, exec, s[58:59]
	s_cbranch_vccz .LBB0_201
	s_andn2_b64 vcc, exec, s[14:15]
	v_mov_b32_e32 v133, v3
	v_mov_b32_e32 v132, v2
	v_mov_b32_e32 v131, v1
	v_mov_b32_e32 v130, v0
	s_cbranch_vccnz .LBB0_200
	s_waitcnt vmcnt(0)
	v_mov_b32_e32 v130, v166
	v_mov_b32_e32 v131, v167
	v_lshlrev_b32_e32 v4, 16, v130
	v_and_b32_e32 v130, 0xffff0000, v130
	v_lshlrev_b32_e32 v132, 16, v131
	v_and_b32_e32 v131, 0xffff0000, v131
	v_mul_f32_e32 v4, 0xbfb8aa3b, v4
	v_mul_f32_e32 v130, 0xbfb8aa3b, v130
	v_mul_f32_e32 v132, 0xbfb8aa3b, v132
	v_mul_f32_e32 v131, 0xbfb8aa3b, v131
	v_exp_f32_e32 v4, v4
	v_exp_f32_e32 v130, v130
	v_exp_f32_e32 v132, v132
	v_exp_f32_e32 v131, v131
	v_add_f32_e32 v4, 1.0, v4
	v_add_f32_e32 v133, 1.0, v130
	v_add_f32_e32 v132, 1.0, v132
	v_add_f32_e32 v135, 1.0, v131
	v_rcp_f32_e32 v130, v4
	v_rcp_f32_e32 v131, v133
	v_rcp_f32_e32 v132, v132
	v_rcp_f32_e32 v133, v135
	v_pk_mul_f32 v[130:131], v[0:1], v[130:131]
	v_pk_mul_f32 v[132:133], v[2:3], v[132:133]

; DEV unsigned pack2h(float a, float b) { unsigned r; asm("v_cvt_pk_bf16_f32 %0, %1, %2" : "=v"(r) : "v"(a), "v"(b)); return r; }
; DEV float bflo(unsigned u) { return __uint_as_float(u << 16); }
; DEV float bfhi(unsigned u) { return __uint_as_float(u & 0xffff0000u); }
; DEV float sigm(float x) { return __builtin_amdgcn_rcpf(1.f + __expf(-x)); }
; DEV void gemm_phase(const GemmJob& J) {
;     ...
;               for (int m = 0; m < 4; ++m) {
;                 f32x4 v = acc[ai][bj][m][n];
;                 float v0 = v[0], v1 = v[1], v2 = v[2], v3 = v[3];
;                 if (mode == 4) {
;                   v0 = fmaxf(v0, 0.f); v1 = fmaxf(v1, 0.f); v2 = fmaxf(v2, 0.f); v3 = fmaxf(v3, 0.f);
;                   v0 *= v0; v1 *= v1; v2 *= v2; v3 *= v3;
;                 } else if (mode == 2) {
;                   const u32x2 gb = *(const u32x2*)(J.gate + (long)(brow + ai * HALF + wr * 64 + m * 16 + fr) * LDR + C_GB + bcol + bj * HALF + wc * 32 + n * 16 + fq * 4);
;                   v0 *= sigm(bflo(gb.x)); v1 *= sigm(bfhi(gb.x)); v2 *= sigm(bflo(gb.y)); v3 *= sigm(bfhi(gb.y));
;                 }
;                 u32x2 o; o.x = pack2h(v0, v1); o.y = pack2h(v2, v3);
;                 *(u32x2*)(sw + m * 16 * 264 + bj * HALF + n * 16) = o;
.LBB0_203:
	v_cndmask_b32_e64 v4, 0, 1, s[58:59]
	v_cvt_pk_bf16_f32 v130, v130, v131
	v_cvt_pk_bf16_f32 v131, v132, v133
	v_cmp_ne_u32_e64 s[0:1], 1, v4
	s_andn2_b64 vcc, exec, s[58:59]
	s_mov_b64 s[10:11], -1
	ds_write_b64 v159, v[130:131]
	s_cbranch_vccnz .LBB0_207
	s_andn2_b64 vcc, exec, s[14:15]
	v_mov_b32_e32 v133, v125
	v_mov_b32_e32 v132, v124
	v_mov_b32_e32 v131, v123
	v_mov_b32_e32 v130, v122
	s_cbranch_vccnz .LBB0_206
	v_or_b32_e32 v4, 16, v163
	v_mov_b32_e32 v130, v168
	v_mov_b32_e32 v131, v169
	v_lshlrev_b32_e32 v4, 16, v130
	v_and_b32_e32 v130, 0xffff0000, v130
	v_lshlrev_b32_e32 v132, 16, v131
	v_and_b32_e32 v131, 0xffff0000, v131
	v_mul_f32_e32 v4, 0xbfb8aa3b, v4
	v_mul_f32_e32 v130, 0xbfb8aa3b, v130
	v_mul_f32_e32 v132, 0xbfb8aa3b, v132
	v_mul_f32_e32 v131, 0xbfb8aa3b, v131
	v_exp_f32_e32 v4, v4
	v_exp_f32_e32 v130, v130
	v_exp_f32_e32 v132, v132
	v_exp_f32_e32 v131, v131
	v_add_f32_e32 v4, 1.0, v4
	v_add_f32_e32 v133, 1.0, v130
	v_add_f32_e32 v132, 1.0, v132
	v_add_f32_e32 v135, 1.0, v131
	v_rcp_f32_e32 v130, v4
	v_rcp_f32_e32 v131, v133
	v_rcp_f32_e32 v132, v132
	v_rcp_f32_e32 v133, v135
	v_pk_mul_f32 v[130:131], v[122:123], v[130:131]
	v_pk_mul_f32 v[132:133], v[124:125], v[132:133]

; DEV unsigned pack2h(float a, float b) { unsigned r; asm("v_cvt_pk_bf16_f32 %0, %1, %2" : "=v"(r) : "v"(a), "v"(b)); return r; }
; DEV float bflo(unsigned u) { return __uint_as_float(u << 16); }
; DEV float bfhi(unsigned u) { return __uint_as_float(u & 0xffff0000u); }
; DEV float sigm(float x) { return __builtin_amdgcn_rcpf(1.f + __expf(-x)); }
; DEV void gemm_phase(const GemmJob& J) {
;     ...
;               for (int m = 0; m < 4; ++m) {
;                 f32x4 v = acc[ai][bj][m][n];
;                 float v0 = v[0], v1 = v[1], v2 = v[2], v3 = v[3];
;                 if (mode == 4) {
;                   v0 = fmaxf(v0, 0.f); v1 = fmaxf(v1, 0.f); v2 = fmaxf(v2, 0.f); v3 = fmaxf(v3, 0.f);
;                   v0 *= v0; v1 *= v1; v2 *= v2; v3 *= v3;
;                 } else if (mode == 2) {
;                   const u32x2 gb = *(const u32x2*)(J.gate + (long)(brow + ai * HALF + wr * 64 + m * 16 + fr) * LDR + C_GB + bcol + bj * HALF + wc * 32 + n * 16 + fq * 4);
;                   v0 *= sigm(bflo(gb.x)); v1 *= sigm(bfhi(gb.x)); v2 *= sigm(bflo(gb.y)); v3 *= sigm(bfhi(gb.y));
;                 }
;                 u32x2 o; o.x = pack2h(v0, v1); o.y = pack2h(v2, v3);
;                 *(u32x2*)(sw + m * 16 * 264 + bj * HALF + n * 16) = o;
.LBB0_209:
	v_cvt_pk_bf16_f32 v130, v130, v131
	s_nop 0
	v_cvt_pk_bf16_f32 v131, v132, v133
	s_and_b64 vcc, exec, s[0:1]
	s_mov_b64 s[10:11], -1
	ds_write_b64 v159, v[130:131] offset:8448
	s_cbranch_vccnz .LBB0_213
	s_andn2_b64 vcc, exec, s[14:15]
	v_mov_b32_e32 v133, v117
	v_mov_b32_e32 v132, v116
	v_mov_b32_e32 v131, v115
	v_mov_b32_e32 v130, v114
	s_cbranch_vccnz .LBB0_212
	v_or_b32_e32 v4, 32, v163
	v_mov_b32_e32 v130, v170
	v_mov_b32_e32 v131, v171
	v_lshlrev_b32_e32 v4, 16, v130
	v_and_b32_e32 v130, 0xffff0000, v130
	v_lshlrev_b32_e32 v132, 16, v131
	v_and_b32_e32 v131, 0xffff0000, v131
	v_mul_f32_e32 v4, 0xbfb8aa3b, v4
	v_mul_f32_e32 v130, 0xbfb8aa3b, v130
	v_mul_f32_e32 v132, 0xbfb8aa3b, v132
	v_mul_f32_e32 v131, 0xbfb8aa3b, v131
	v_exp_f32_e32 v4, v4
	v_exp_f32_e32 v130, v130
	v_exp_f32_e32 v132, v132
	v_exp_f32_e32 v131, v131
	v_add_f32_e32 v4, 1.0, v4
	v_add_f32_e32 v133, 1.0, v130
	v_add_f32_e32 v132, 1.0, v132
	v_add_f32_e32 v135, 1.0, v131
	v_rcp_f32_e32 v130, v4
	v_rcp_f32_e32 v131, v133
	v_rcp_f32_e32 v132, v132
	v_rcp_f32_e32 v133, v135
	v_pk_mul_f32 v[130:131], v[114:115], v[130:131]
	v_pk_mul_f32 v[132:133], v[116:117], v[132:133]

; DEV unsigned pack2h(float a, float b) { unsigned r; asm("v_cvt_pk_bf16_f32 %0, %1, %2" : "=v"(r) : "v"(a), "v"(b)); return r; }
; DEV float bflo(unsigned u) { return __uint_as_float(u << 16); }
; DEV float bfhi(unsigned u) { return __uint_as_float(u & 0xffff0000u); }
; DEV float sigm(float x) { return __builtin_amdgcn_rcpf(1.f + __expf(-x)); }
; DEV void gemm_phase(const GemmJob& J) {
;     ...
;               for (int m = 0; m < 4; ++m) {
;                 f32x4 v = acc[ai][bj][m][n];
;                 float v0 = v[0], v1 = v[1], v2 = v[2], v3 = v[3];
;                 if (mode == 4) {
;                   v0 = fmaxf(v0, 0.f); v1 = fmaxf(v1, 0.f); v2 = fmaxf(v2, 0.f); v3 = fmaxf(v3, 0.f);
;                   v0 *= v0; v1 *= v1; v2 *= v2; v3 *= v3;
;                 } else if (mode == 2) {
;                   const u32x2 gb = *(const u32x2*)(J.gate + (long)(brow + ai * HALF + wr * 64 + m * 16 + fr) * LDR + C_GB + bcol + bj * HALF + wc * 32 + n * 16 + fq * 4);
;                   v0 *= sigm(bflo(gb.x)); v1 *= sigm(bfhi(gb.x)); v2 *= sigm(bflo(gb.y)); v3 *= sigm(bfhi(gb.y));
;                 }
;                 u32x2 o; o.x = pack2h(v0, v1); o.y = pack2h(v2, v3);
;                 *(u32x2*)(sw + m * 16 * 264 + bj * HALF + n * 16) = o;
.LBB0_215:
	v_cvt_pk_bf16_f32 v130, v130, v131
	s_nop 0
	v_cvt_pk_bf16_f32 v131, v132, v133
	s_and_b64 vcc, exec, s[0:1]
	s_mov_b64 s[0:1], -1
	ds_write_b64 v159, v[130:131] offset:16896
	s_cbranch_vccnz .LBB0_219
	s_andn2_b64 vcc, exec, s[14:15]
	v_mov_b32_e32 v131, v109
	v_mov_b32_e32 v130, v108
	v_mov_b32_e32 v133, v107
	v_mov_b32_e32 v132, v106
	s_cbranch_vccnz .LBB0_218
	v_or_b32_e32 v4, 48, v163
	v_mov_b32_e32 v130, v172
	v_mov_b32_e32 v131, v173
	v_lshlrev_b32_e32 v4, 16, v130
	v_and_b32_e32 v130, 0xffff0000, v130
	v_lshlrev_b32_e32 v132, 16, v131
	v_and_b32_e32 v131, 0xffff0000, v131
	v_mul_f32_e32 v4, 0xbfb8aa3b, v4
	v_mul_f32_e32 v130, 0xbfb8aa3b, v130
	v_mul_f32_e32 v132, 0xbfb8aa3b, v132
	v_mul_f32_e32 v131, 0xbfb8aa3b, v131
	v_exp_f32_e32 v4, v4
	v_exp_f32_e32 v130, v130
	v_exp_f32_e32 v132, v132
	v_exp_f32_e32 v131, v131
	v_add_f32_e32 v4, 1.0, v4
	v_add_f32_e32 v133, 1.0, v130
	v_add_f32_e32 v132, 1.0, v132
	v_add_f32_e32 v135, 1.0, v131
	v_rcp_f32_e32 v130, v4
	v_rcp_f32_e32 v131, v133
	v_rcp_f32_e32 v136, v132
	v_rcp_f32_e32 v137, v135
	v_pk_mul_f32 v[132:133], v[106:107], v[130:131]
	v_pk_mul_f32 v[130:131], v[108:109], v[136:137]

; DEV unsigned pack2h(float a, float b) { unsigned r; asm("v_cvt_pk_bf16_f32 %0, %1, %2" : "=v"(r) : "v"(a), "v"(b)); return r; }
; DEV float bflo(unsigned u) { return __uint_as_float(u << 16); }
; DEV float bfhi(unsigned u) { return __uint_as_float(u & 0xffff0000u); }
; DEV float sigm(float x) { return __builtin_amdgcn_rcpf(1.f + __expf(-x)); }
; DEV void gemm_phase(const GemmJob& J) {
;     ...
;               for (int m = 0; m < 4; ++m) {
;                 f32x4 v = acc[ai][bj][m][n];
;                 float v0 = v[0], v1 = v[1], v2 = v[2], v3 = v[3];
;                 if (mode == 4) {
;                   v0 = fmaxf(v0, 0.f); v1 = fmaxf(v1, 0.f); v2 = fmaxf(v2, 0.f); v3 = fmaxf(v3, 0.f);
;                   v0 *= v0; v1 *= v1; v2 *= v2; v3 *= v3;
;                 } else if (mode == 2) {
;                   const u32x2 gb = *(const u32x2*)(J.gate + (long)(brow + ai * HALF + wr * 64 + m * 16 + fr) * LDR + C_GB + bcol + bj * HALF + wc * 32 + n * 16 + fq * 4);
;                   v0 *= sigm(bflo(gb.x)); v1 *= sigm(bfhi(gb.x)); v2 *= sigm(bflo(gb.y)); v3 *= sigm(bfhi(gb.y));
;                 }
;                 u32x2 o; o.x = pack2h(v0, v1); o.y = pack2h(v2, v3);
;                 *(u32x2*)(sw + m * 16 * 264 + bj * HALF + n * 16) = o;
.LBB0_224:
	s_xor_b64 s[8:9], s[12:13], -1
	v_cndmask_b32_e64 v4, 0, 1, s[8:9]
	v_cmp_ne_u32_e64 s[10:11], 1, v4
	v_cndmask_b32_e64 v4, 0, 1, s[58:59]
	s_mov_b64 s[0:1], -1
	s_andn2_b64 vcc, exec, s[8:9]
	v_cmp_ne_u32_e64 s[8:9], 1, v4
	ds_write_b64 v159, v[132:133] offset:25344
	s_cbranch_vccnz .LBB0_251
	s_and_b64 vcc, exec, s[8:9]
	s_cbranch_vccnz .LBB0_229
	s_andn2_b64 vcc, exec, s[14:15]
	v_mov_b32_e32 v133, v129
	v_mov_b32_e32 v132, v128
	v_mov_b32_e32 v131, v127
	v_mov_b32_e32 v130, v126
	s_cbranch_vccnz .LBB0_228
	v_mov_b32_e32 v130, v174
	v_mov_b32_e32 v131, v175
	v_lshlrev_b32_e32 v4, 16, v130
	v_and_b32_e32 v130, 0xffff0000, v130
	v_lshlrev_b32_e32 v132, 16, v131
	v_and_b32_e32 v131, 0xffff0000, v131
	v_mul_f32_e32 v4, 0xbfb8aa3b, v4
	v_mul_f32_e32 v130, 0xbfb8aa3b, v130
	v_mul_f32_e32 v132, 0xbfb8aa3b, v132
	v_mul_f32_e32 v131, 0xbfb8aa3b, v131
	v_exp_f32_e32 v4, v4
	v_exp_f32_e32 v130, v130
	v_exp_f32_e32 v132, v132
	v_exp_f32_e32 v131, v131
	v_add_f32_e32 v4, 1.0, v4
	v_add_f32_e32 v133, 1.0, v130
	v_add_f32_e32 v132, 1.0, v132
	v_add_f32_e32 v136, 1.0, v131
	v_rcp_f32_e32 v130, v4
	v_rcp_f32_e32 v131, v133
	v_rcp_f32_e32 v132, v132
	v_rcp_f32_e32 v133, v136
	v_pk_mul_f32 v[130:131], v[126:127], v[130:131]
	v_pk_mul_f32 v[132:133], v[128:129], v[132:133]

; DEV unsigned pack2h(float a, float b) { unsigned r; asm("v_cvt_pk_bf16_f32 %0, %1, %2" : "=v"(r) : "v"(a), "v"(b)); return r; }
; DEV float bflo(unsigned u) { return __uint_as_float(u << 16); }
; DEV float bfhi(unsigned u) { return __uint_as_float(u & 0xffff0000u); }
; DEV float sigm(float x) { return __builtin_amdgcn_rcpf(1.f + __expf(-x)); }
; DEV void gemm_phase(const GemmJob& J) {
;     ...
;               for (int m = 0; m < 4; ++m) {
;                 f32x4 v = acc[ai][bj][m][n];
;                 float v0 = v[0], v1 = v[1], v2 = v[2], v3 = v[3];
;                 if (mode == 4) {
;                   v0 = fmaxf(v0, 0.f); v1 = fmaxf(v1, 0.f); v2 = fmaxf(v2, 0.f); v3 = fmaxf(v3, 0.f);
;                   v0 *= v0; v1 *= v1; v2 *= v2; v3 *= v3;
;                 } else if (mode == 2) {
;                   const u32x2 gb = *(const u32x2*)(J.gate + (long)(brow + ai * HALF + wr * 64 + m * 16 + fr) * LDR + C_GB + bcol + bj * HALF + wc * 32 + n * 16 + fq * 4);
;                   v0 *= sigm(bflo(gb.x)); v1 *= sigm(bfhi(gb.x)); v2 *= sigm(bflo(gb.y)); v3 *= sigm(bfhi(gb.y));
;                 }
;                 u32x2 o; o.x = pack2h(v0, v1); o.y = pack2h(v2, v3);
;                 *(u32x2*)(sw + m * 16 * 264 + bj * HALF + n * 16) = o;
.LBB0_231:
	v_cvt_pk_bf16_f32 v130, v130, v131
	s_nop 0
	v_cvt_pk_bf16_f32 v131, v132, v133
	s_and_b64 vcc, exec, s[8:9]
	s_mov_b64 s[0:1], -1
	ds_write_b64 v159, v[130:131] offset:32
	s_cbranch_vccnz .LBB0_235
	s_andn2_b64 vcc, exec, s[14:15]
	v_mov_b32_e32 v133, v121
	v_mov_b32_e32 v132, v120
	v_mov_b32_e32 v131, v119
	v_mov_b32_e32 v130, v118
	s_cbranch_vccnz .LBB0_234
	v_or_b32_e32 v4, 16, v163
	v_mov_b32_e32 v130, v176
	v_mov_b32_e32 v131, v177
	v_lshlrev_b32_e32 v4, 16, v130
	v_and_b32_e32 v130, 0xffff0000, v130
	v_lshlrev_b32_e32 v132, 16, v131
	v_and_b32_e32 v131, 0xffff0000, v131
	v_mul_f32_e32 v4, 0xbfb8aa3b, v4
	v_mul_f32_e32 v130, 0xbfb8aa3b, v130
	v_mul_f32_e32 v132, 0xbfb8aa3b, v132
	v_mul_f32_e32 v131, 0xbfb8aa3b, v131
	v_exp_f32_e32 v4, v4
	v_exp_f32_e32 v130, v130
	v_exp_f32_e32 v132, v132
	v_exp_f32_e32 v131, v131
	v_add_f32_e32 v4, 1.0, v4
	v_add_f32_e32 v133, 1.0, v130
	v_add_f32_e32 v132, 1.0, v132
	v_add_f32_e32 v136, 1.0, v131
	v_rcp_f32_e32 v130, v4
	v_rcp_f32_e32 v131, v133
	v_rcp_f32_e32 v132, v132
	v_rcp_f32_e32 v133, v136
	v_pk_mul_f32 v[130:131], v[118:119], v[130:131]
	v_pk_mul_f32 v[132:133], v[120:121], v[132:133]

; DEV unsigned pack2h(float a, float b) { unsigned r; asm("v_cvt_pk_bf16_f32 %0, %1, %2" : "=v"(r) : "v"(a), "v"(b)); return r; }
; DEV float bflo(unsigned u) { return __uint_as_float(u << 16); }
; DEV float bfhi(unsigned u) { return __uint_as_float(u & 0xffff0000u); }
; DEV float sigm(float x) { return __builtin_amdgcn_rcpf(1.f + __expf(-x)); }
; DEV void gemm_phase(const GemmJob& J) {
;     ...
;               for (int m = 0; m < 4; ++m) {
;                 f32x4 v = acc[ai][bj][m][n];
;                 float v0 = v[0], v1 = v[1], v2 = v[2], v3 = v[3];
;                 if (mode == 4) {
;                   v0 = fmaxf(v0, 0.f); v1 = fmaxf(v1, 0.f); v2 = fmaxf(v2, 0.f); v3 = fmaxf(v3, 0.f);
;                   v0 *= v0; v1 *= v1; v2 *= v2; v3 *= v3;
;                 } else if (mode == 2) {
;                   const u32x2 gb = *(const u32x2*)(J.gate + (long)(brow + ai * HALF + wr * 64 + m * 16 + fr) * LDR + C_GB + bcol + bj * HALF + wc * 32 + n * 16 + fq * 4);
;                   v0 *= sigm(bflo(gb.x)); v1 *= sigm(bfhi(gb.x)); v2 *= sigm(bflo(gb.y)); v3 *= sigm(bfhi(gb.y));
;                 }
;                 u32x2 o; o.x = pack2h(v0, v1); o.y = pack2h(v2, v3);
;                 *(u32x2*)(sw + m * 16 * 264 + bj * HALF + n * 16) = o;
.LBB0_237:
	v_cvt_pk_bf16_f32 v130, v130, v131
	s_nop 0
	v_cvt_pk_bf16_f32 v131, v132, v133
	s_and_b64 vcc, exec, s[8:9]
	s_mov_b64 s[0:1], -1
	ds_write_b64 v159, v[130:131] offset:8480
	s_cbranch_vccnz .LBB0_241
	s_andn2_b64 vcc, exec, s[14:15]
	v_mov_b32_e32 v133, v113
	v_mov_b32_e32 v132, v112
	v_mov_b32_e32 v131, v111
	v_mov_b32_e32 v130, v110
	s_cbranch_vccnz .LBB0_240
	v_or_b32_e32 v4, 32, v163
	v_mov_b32_e32 v130, v204
	v_mov_b32_e32 v131, v205
	v_lshlrev_b32_e32 v4, 16, v130
	v_and_b32_e32 v130, 0xffff0000, v130
	v_lshlrev_b32_e32 v132, 16, v131
	v_and_b32_e32 v131, 0xffff0000, v131
	v_mul_f32_e32 v4, 0xbfb8aa3b, v4
	v_mul_f32_e32 v130, 0xbfb8aa3b, v130
	v_mul_f32_e32 v132, 0xbfb8aa3b, v132
	v_mul_f32_e32 v131, 0xbfb8aa3b, v131
	v_exp_f32_e32 v4, v4
	v_exp_f32_e32 v130, v130
	v_exp_f32_e32 v132, v132
	v_exp_f32_e32 v131, v131
	v_add_f32_e32 v4, 1.0, v4
	v_add_f32_e32 v133, 1.0, v130
	v_add_f32_e32 v132, 1.0, v132
	v_add_f32_e32 v136, 1.0, v131
	v_rcp_f32_e32 v130, v4
	v_rcp_f32_e32 v131, v133
	v_rcp_f32_e32 v132, v132
	v_rcp_f32_e32 v133, v136
	v_pk_mul_f32 v[130:131], v[110:111], v[130:131]
	v_pk_mul_f32 v[132:133], v[112:113], v[132:133]

; DEV unsigned pack2h(float a, float b) { unsigned r; asm("v_cvt_pk_bf16_f32 %0, %1, %2" : "=v"(r) : "v"(a), "v"(b)); return r; }
; DEV float bflo(unsigned u) { return __uint_as_float(u << 16); }
; DEV float bfhi(unsigned u) { return __uint_as_float(u & 0xffff0000u); }
; DEV float sigm(float x) { return __builtin_amdgcn_rcpf(1.f + __expf(-x)); }
; DEV void gemm_phase(const GemmJob& J) {
;     ...
;               for (int m = 0; m < 4; ++m) {
;                 f32x4 v = acc[ai][bj][m][n];
;                 float v0 = v[0], v1 = v[1], v2 = v[2], v3 = v[3];
;                 if (mode == 4) {
;                   v0 = fmaxf(v0, 0.f); v1 = fmaxf(v1, 0.f); v2 = fmaxf(v2, 0.f); v3 = fmaxf(v3, 0.f);
;                   v0 *= v0; v1 *= v1; v2 *= v2; v3 *= v3;
;                 } else if (mode == 2) {
;                   const u32x2 gb = *(const u32x2*)(J.gate + (long)(brow + ai * HALF + wr * 64 + m * 16 + fr) * LDR + C_GB + bcol + bj * HALF + wc * 32 + n * 16 + fq * 4);
;                   v0 *= sigm(bflo(gb.x)); v1 *= sigm(bfhi(gb.x)); v2 *= sigm(bflo(gb.y)); v3 *= sigm(bfhi(gb.y));
;                 }
;                 u32x2 o; o.x = pack2h(v0, v1); o.y = pack2h(v2, v3);
;                 *(u32x2*)(sw + m * 16 * 264 + bj * HALF + n * 16) = o;
.LBB0_243:
	v_cvt_pk_bf16_f32 v130, v130, v131
	s_nop 0
	v_cvt_pk_bf16_f32 v131, v132, v133
	s_and_b64 vcc, exec, s[8:9]
	s_mov_b64 s[0:1], -1
	ds_write_b64 v159, v[130:131] offset:16928
	s_cbranch_vccnz .LBB0_247
	s_andn2_b64 vcc, exec, s[14:15]
	v_mov_b32_e32 v131, v105
	v_mov_b32_e32 v130, v104
	v_mov_b32_e32 v133, v103
	v_mov_b32_e32 v132, v102
	s_cbranch_vccnz .LBB0_246
	v_or_b32_e32 v4, 48, v163
	v_mov_b32_e32 v130, v206
	v_mov_b32_e32 v131, v207
	v_lshlrev_b32_e32 v4, 16, v130
	v_and_b32_e32 v130, 0xffff0000, v130
	v_lshlrev_b32_e32 v132, 16, v131
	v_and_b32_e32 v131, 0xffff0000, v131
	v_mul_f32_e32 v4, 0xbfb8aa3b, v4
	v_mul_f32_e32 v130, 0xbfb8aa3b, v130
	v_mul_f32_e32 v132, 0xbfb8aa3b, v132
	v_mul_f32_e32 v131, 0xbfb8aa3b, v131
	v_exp_f32_e32 v4, v4
	v_exp_f32_e32 v130, v130
	v_exp_f32_e32 v132, v132
	v_exp_f32_e32 v131, v131
	v_add_f32_e32 v4, 1.0, v4
	v_add_f32_e32 v133, 1.0, v130
	v_add_f32_e32 v132, 1.0, v132
	v_add_f32_e32 v137, 1.0, v131
	v_rcp_f32_e32 v130, v4
	v_rcp_f32_e32 v131, v133
	v_rcp_f32_e32 v136, v132
	v_rcp_f32_e32 v137, v137
	v_pk_mul_f32 v[132:133], v[102:103], v[130:131]
	v_pk_mul_f32 v[130:131], v[104:105], v[136:137]

; DEV unsigned pack2h(float a, float b) { unsigned r; asm("v_cvt_pk_bf16_f32 %0, %1, %2" : "=v"(r) : "v"(a), "v"(b)); return r; }
; DEV float bflo(unsigned u) { return __uint_as_float(u << 16); }
; DEV float bfhi(unsigned u) { return __uint_as_float(u & 0xffff0000u); }
; DEV float sigm(float x) { return __builtin_amdgcn_rcpf(1.f + __expf(-x)); }
; DEV void gemm_phase(const GemmJob& J) {
;     ...
;               for (int m = 0; m < 4; ++m) {
;                 f32x4 v = acc[ai][bj][m][n];
;                 float v0 = v[0], v1 = v[1], v2 = v[2], v3 = v[3];
;                 if (mode == 4) {
;                   v0 = fmaxf(v0, 0.f); v1 = fmaxf(v1, 0.f); v2 = fmaxf(v2, 0.f); v3 = fmaxf(v3, 0.f);
;                   v0 *= v0; v1 *= v1; v2 *= v2; v3 *= v3;
;                 } else if (mode == 2) {
;                   const u32x2 gb = *(const u32x2*)(J.gate + (long)(brow + ai * HALF + wr * 64 + m * 16 + fr) * LDR + C_GB + bcol + bj * HALF + wc * 32 + n * 16 + fq * 4);
;                   v0 *= sigm(bflo(gb.x)); v1 *= sigm(bfhi(gb.x)); v2 *= sigm(bflo(gb.y)); v3 *= sigm(bfhi(gb.y));
;                 }
;                 u32x2 o; o.x = pack2h(v0, v1); o.y = pack2h(v2, v3);
;                 *(u32x2*)(sw + m * 16 * 264 + bj * HALF + n * 16) = o;
.LBB0_253:
	s_and_b64 vcc, exec, s[10:11]
	s_mov_b64 s[0:1], -1
	ds_write_b64 v159, v[132:133] offset:25376
	s_cbranch_vccnz .LBB0_279
	s_and_b64 vcc, exec, s[8:9]
	s_cbranch_vccnz .LBB0_258
	s_andn2_b64 vcc, exec, s[14:15]
	v_mov_b32_e32 v133, v101
	v_mov_b32_e32 v132, v100
	v_mov_b32_e32 v131, v99
	v_mov_b32_e32 v130, v98
	s_cbranch_vccnz .LBB0_257
	v_mov_b32_e32 v130, v208
	v_mov_b32_e32 v131, v209
	v_lshlrev_b32_e32 v4, 16, v130
	v_and_b32_e32 v130, 0xffff0000, v130
	v_lshlrev_b32_e32 v132, 16, v131
	v_and_b32_e32 v131, 0xffff0000, v131
	v_mul_f32_e32 v4, 0xbfb8aa3b, v4
	v_mul_f32_e32 v130, 0xbfb8aa3b, v130
	v_mul_f32_e32 v132, 0xbfb8aa3b, v132
	v_mul_f32_e32 v131, 0xbfb8aa3b, v131
	v_exp_f32_e32 v4, v4
	v_exp_f32_e32 v130, v130
	v_exp_f32_e32 v132, v132
	v_exp_f32_e32 v131, v131
	v_add_f32_e32 v4, 1.0, v4
	v_add_f32_e32 v133, 1.0, v130
	v_add_f32_e32 v132, 1.0, v132
	v_add_f32_e32 v136, 1.0, v131
	v_rcp_f32_e32 v130, v4
	v_rcp_f32_e32 v131, v133
	v_rcp_f32_e32 v132, v132
	v_rcp_f32_e32 v133, v136
	v_pk_mul_f32 v[130:131], v[98:99], v[130:131]
	v_pk_mul_f32 v[132:133], v[100:101], v[132:133]

; DEV unsigned pack2h(float a, float b) { unsigned r; asm("v_cvt_pk_bf16_f32 %0, %1, %2" : "=v"(r) : "v"(a), "v"(b)); return r; }
; DEV float bflo(unsigned u) { return __uint_as_float(u << 16); }
; DEV float bfhi(unsigned u) { return __uint_as_float(u & 0xffff0000u); }
; DEV float sigm(float x) { return __builtin_amdgcn_rcpf(1.f + __expf(-x)); }
; DEV void gemm_phase(const GemmJob& J) {
;     ...
;               for (int m = 0; m < 4; ++m) {
;                 f32x4 v = acc[ai][bj][m][n];
;                 float v0 = v[0], v1 = v[1], v2 = v[2], v3 = v[3];
;                 if (mode == 4) {
;                   v0 = fmaxf(v0, 0.f); v1 = fmaxf(v1, 0.f); v2 = fmaxf(v2, 0.f); v3 = fmaxf(v3, 0.f);
;                   v0 *= v0; v1 *= v1; v2 *= v2; v3 *= v3;
;                 } else if (mode == 2) {
;                   const u32x2 gb = *(const u32x2*)(J.gate + (long)(brow + ai * HALF + wr * 64 + m * 16 + fr) * LDR + C_GB + bcol + bj * HALF + wc * 32 + n * 16 + fq * 4);
;                   v0 *= sigm(bflo(gb.x)); v1 *= sigm(bfhi(gb.x)); v2 *= sigm(bflo(gb.y)); v3 *= sigm(bfhi(gb.y));
;                 }
;                 u32x2 o; o.x = pack2h(v0, v1); o.y = pack2h(v2, v3);
;                 *(u32x2*)(sw + m * 16 * 264 + bj * HALF + n * 16) = o;
.LBB0_260:
	v_cvt_pk_bf16_f32 v130, v130, v131
	s_nop 0
	v_cvt_pk_bf16_f32 v131, v132, v133
	s_and_b64 vcc, exec, s[8:9]
	s_mov_b64 s[0:1], -1
	ds_write_b64 v159, v[130:131] offset:256
	s_cbranch_vccnz .LBB0_264
	s_andn2_b64 vcc, exec, s[14:15]
	v_mov_b32_e32 v133, v93
	v_mov_b32_e32 v132, v92
	v_mov_b32_e32 v131, v91
	v_mov_b32_e32 v130, v90
	s_cbranch_vccnz .LBB0_263
	v_or_b32_e32 v4, 16, v163
	v_mov_b32_e32 v130, v210
	v_mov_b32_e32 v131, v211
	v_lshlrev_b32_e32 v4, 16, v130
	v_and_b32_e32 v130, 0xffff0000, v130
	v_lshlrev_b32_e32 v132, 16, v131
	v_and_b32_e32 v131, 0xffff0000, v131
	v_mul_f32_e32 v4, 0xbfb8aa3b, v4
	v_mul_f32_e32 v130, 0xbfb8aa3b, v130
	v_mul_f32_e32 v132, 0xbfb8aa3b, v132
	v_mul_f32_e32 v131, 0xbfb8aa3b, v131
	v_exp_f32_e32 v4, v4
	v_exp_f32_e32 v130, v130
	v_exp_f32_e32 v132, v132
	v_exp_f32_e32 v131, v131
	v_add_f32_e32 v4, 1.0, v4
	v_add_f32_e32 v133, 1.0, v130
	v_add_f32_e32 v132, 1.0, v132
	v_add_f32_e32 v136, 1.0, v131
	v_rcp_f32_e32 v130, v4
	v_rcp_f32_e32 v131, v133
	v_rcp_f32_e32 v132, v132
	v_rcp_f32_e32 v133, v136
	v_pk_mul_f32 v[130:131], v[90:91], v[130:131]
	v_pk_mul_f32 v[132:133], v[92:93], v[132:133]

; DEV unsigned pack2h(float a, float b) { unsigned r; asm("v_cvt_pk_bf16_f32 %0, %1, %2" : "=v"(r) : "v"(a), "v"(b)); return r; }
; DEV float bflo(unsigned u) { return __uint_as_float(u << 16); }
; DEV float bfhi(unsigned u) { return __uint_as_float(u & 0xffff0000u); }
; DEV float sigm(float x) { return __builtin_amdgcn_rcpf(1.f + __expf(-x)); }
; DEV void gemm_phase(const GemmJob& J) {
;     ...
;               for (int m = 0; m < 4; ++m) {
;                 f32x4 v = acc[ai][bj][m][n];
;                 float v0 = v[0], v1 = v[1], v2 = v[2], v3 = v[3];
;                 if (mode == 4) {
;                   v0 = fmaxf(v0, 0.f); v1 = fmaxf(v1, 0.f); v2 = fmaxf(v2, 0.f); v3 = fmaxf(v3, 0.f);
;                   v0 *= v0; v1 *= v1; v2 *= v2; v3 *= v3;
;                 } else if (mode == 2) {
;                   const u32x2 gb = *(const u32x2*)(J.gate + (long)(brow + ai * HALF + wr * 64 + m * 16 + fr) * LDR + C_GB + bcol + bj * HALF + wc * 32 + n * 16 + fq * 4);
;                   v0 *= sigm(bflo(gb.x)); v1 *= sigm(bfhi(gb.x)); v2 *= sigm(bflo(gb.y)); v3 *= sigm(bfhi(gb.y));
;                 }
;                 u32x2 o; o.x = pack2h(v0, v1); o.y = pack2h(v2, v3);
;                 *(u32x2*)(sw + m * 16 * 264 + bj * HALF + n * 16) = o;
.LBB0_266:
	v_cvt_pk_bf16_f32 v130, v130, v131
	s_nop 0
	v_cvt_pk_bf16_f32 v131, v132, v133
	s_and_b64 vcc, exec, s[8:9]
	s_mov_b64 s[0:1], -1
	ds_write_b64 v159, v[130:131] offset:8704
	s_cbranch_vccnz .LBB0_270
	s_andn2_b64 vcc, exec, s[14:15]
	v_mov_b32_e32 v133, v85
	v_mov_b32_e32 v132, v84
	v_mov_b32_e32 v131, v83
	v_mov_b32_e32 v130, v82
	s_cbranch_vccnz .LBB0_269
	v_or_b32_e32 v4, 32, v163
	v_mov_b32_e32 v130, v212
	v_mov_b32_e32 v131, v213
	v_lshlrev_b32_e32 v4, 16, v130
	v_and_b32_e32 v130, 0xffff0000, v130
	v_lshlrev_b32_e32 v132, 16, v131
	v_and_b32_e32 v131, 0xffff0000, v131
	v_mul_f32_e32 v4, 0xbfb8aa3b, v4
	v_mul_f32_e32 v130, 0xbfb8aa3b, v130
	v_mul_f32_e32 v132, 0xbfb8aa3b, v132
	v_mul_f32_e32 v131, 0xbfb8aa3b, v131
	v_exp_f32_e32 v4, v4
	v_exp_f32_e32 v130, v130
	v_exp_f32_e32 v132, v132
	v_exp_f32_e32 v131, v131
	v_add_f32_e32 v4, 1.0, v4
	v_add_f32_e32 v133, 1.0, v130
	v_add_f32_e32 v132, 1.0, v132
	v_add_f32_e32 v136, 1.0, v131
	v_rcp_f32_e32 v130, v4
	v_rcp_f32_e32 v131, v133
	v_rcp_f32_e32 v132, v132
	v_rcp_f32_e32 v133, v136
	v_pk_mul_f32 v[130:131], v[82:83], v[130:131]
	v_pk_mul_f32 v[132:133], v[84:85], v[132:133]

; DEV unsigned pack2h(float a, float b) { unsigned r; asm("v_cvt_pk_bf16_f32 %0, %1, %2" : "=v"(r) : "v"(a), "v"(b)); return r; }
; DEV float bflo(unsigned u) { return __uint_as_float(u << 16); }
; DEV float bfhi(unsigned u) { return __uint_as_float(u & 0xffff0000u); }
; DEV float sigm(float x) { return __builtin_amdgcn_rcpf(1.f + __expf(-x)); }
; DEV void gemm_phase(const GemmJob& J) {
;     ...
;               for (int m = 0; m < 4; ++m) {
;                 f32x4 v = acc[ai][bj][m][n];
;                 float v0 = v[0], v1 = v[1], v2 = v[2], v3 = v[3];
;                 if (mode == 4) {
;                   v0 = fmaxf(v0, 0.f); v1 = fmaxf(v1, 0.f); v2 = fmaxf(v2, 0.f); v3 = fmaxf(v3, 0.f);
;                   v0 *= v0; v1 *= v1; v2 *= v2; v3 *= v3;
;                 } else if (mode == 2) {
;                   const u32x2 gb = *(const u32x2*)(J.gate + (long)(brow + ai * HALF + wr * 64 + m * 16 + fr) * LDR + C_GB + bcol + bj * HALF + wc * 32 + n * 16 + fq * 4);
;                   v0 *= sigm(bflo(gb.x)); v1 *= sigm(bfhi(gb.x)); v2 *= sigm(bflo(gb.y)); v3 *= sigm(bfhi(gb.y));
;                 }
;                 u32x2 o; o.x = pack2h(v0, v1); o.y = pack2h(v2, v3);
;                 *(u32x2*)(sw + m * 16 * 264 + bj * HALF + n * 16) = o;
.LBB0_272:
	v_cvt_pk_bf16_f32 v130, v130, v131
	s_nop 0
	v_cvt_pk_bf16_f32 v131, v132, v133
	s_and_b64 vcc, exec, s[8:9]
	s_mov_b64 s[0:1], -1
	ds_write_b64 v159, v[130:131] offset:17152
	s_cbranch_vccnz .LBB0_276
	s_andn2_b64 vcc, exec, s[14:15]
	v_mov_b32_e32 v131, v77
	v_mov_b32_e32 v130, v76
	v_mov_b32_e32 v133, v75
	v_mov_b32_e32 v132, v74
	s_cbranch_vccnz .LBB0_275
	v_or_b32_e32 v4, 48, v163
	v_mov_b32_e32 v130, v214
	v_mov_b32_e32 v131, v215
	v_lshlrev_b32_e32 v4, 16, v130
	v_and_b32_e32 v130, 0xffff0000, v130
	v_lshlrev_b32_e32 v132, 16, v131
	v_and_b32_e32 v131, 0xffff0000, v131
	v_mul_f32_e32 v4, 0xbfb8aa3b, v4
	v_mul_f32_e32 v130, 0xbfb8aa3b, v130
	v_mul_f32_e32 v132, 0xbfb8aa3b, v132
	v_mul_f32_e32 v131, 0xbfb8aa3b, v131
	v_exp_f32_e32 v4, v4
	v_exp_f32_e32 v130, v130
	v_exp_f32_e32 v132, v132
	v_exp_f32_e32 v131, v131
	v_add_f32_e32 v4, 1.0, v4
	v_add_f32_e32 v133, 1.0, v130
	v_add_f32_e32 v132, 1.0, v132
	v_add_f32_e32 v137, 1.0, v131
	v_rcp_f32_e32 v130, v4
	v_rcp_f32_e32 v131, v133
	v_rcp_f32_e32 v136, v132
	v_rcp_f32_e32 v137, v137
	v_pk_mul_f32 v[132:133], v[74:75], v[130:131]
	v_pk_mul_f32 v[130:131], v[76:77], v[136:137]

; DEV unsigned pack2h(float a, float b) { unsigned r; asm("v_cvt_pk_bf16_f32 %0, %1, %2" : "=v"(r) : "v"(a), "v"(b)); return r; }
; DEV float bflo(unsigned u) { return __uint_as_float(u << 16); }
; DEV float bfhi(unsigned u) { return __uint_as_float(u & 0xffff0000u); }
; DEV float sigm(float x) { return __builtin_amdgcn_rcpf(1.f + __expf(-x)); }
; DEV void gemm_phase(const GemmJob& J) {
;     ...
;               for (int m = 0; m < 4; ++m) {
;                 f32x4 v = acc[ai][bj][m][n];
;                 float v0 = v[0], v1 = v[1], v2 = v[2], v3 = v[3];
;                 if (mode == 4) {
;                   v0 = fmaxf(v0, 0.f); v1 = fmaxf(v1, 0.f); v2 = fmaxf(v2, 0.f); v3 = fmaxf(v3, 0.f);
;                   v0 *= v0; v1 *= v1; v2 *= v2; v3 *= v3;
;                 } else if (mode == 2) {
;                   const u32x2 gb = *(const u32x2*)(J.gate + (long)(brow + ai * HALF + wr * 64 + m * 16 + fr) * LDR + C_GB + bcol + bj * HALF + wc * 32 + n * 16 + fq * 4);
;                   v0 *= sigm(bflo(gb.x)); v1 *= sigm(bfhi(gb.x)); v2 *= sigm(bflo(gb.y)); v3 *= sigm(bfhi(gb.y));
;                 }
;                 u32x2 o; o.x = pack2h(v0, v1); o.y = pack2h(v2, v3);
;                 *(u32x2*)(sw + m * 16 * 264 + bj * HALF + n * 16) = o;
.LBB0_281:
	s_and_b64 vcc, exec, s[10:11]
	s_mov_b64 s[0:1], -1
	ds_write_b64 v159, v[132:133] offset:25600
	s_cbranch_vccnz .LBB0_307
	s_and_b64 vcc, exec, s[8:9]
	s_cbranch_vccnz .LBB0_286
	s_andn2_b64 vcc, exec, s[14:15]
	v_mov_b32_e32 v133, v97
	v_mov_b32_e32 v132, v96
	v_mov_b32_e32 v131, v95
	v_mov_b32_e32 v130, v94
	s_cbranch_vccnz .LBB0_285
	v_mov_b32_e32 v130, v216
	v_mov_b32_e32 v131, v217
	v_lshlrev_b32_e32 v4, 16, v130
	v_and_b32_e32 v130, 0xffff0000, v130
	v_lshlrev_b32_e32 v132, 16, v131
	v_and_b32_e32 v131, 0xffff0000, v131
	v_mul_f32_e32 v4, 0xbfb8aa3b, v4
	v_mul_f32_e32 v130, 0xbfb8aa3b, v130
	v_mul_f32_e32 v132, 0xbfb8aa3b, v132
	v_mul_f32_e32 v131, 0xbfb8aa3b, v131
	v_exp_f32_e32 v4, v4
	v_exp_f32_e32 v130, v130
	v_exp_f32_e32 v132, v132
	v_exp_f32_e32 v131, v131
	v_add_f32_e32 v4, 1.0, v4
	v_add_f32_e32 v133, 1.0, v130
	v_add_f32_e32 v132, 1.0, v132
	v_add_f32_e32 v138, 1.0, v131
	v_rcp_f32_e32 v130, v4
	v_rcp_f32_e32 v131, v133
	v_rcp_f32_e32 v132, v132
	v_rcp_f32_e32 v133, v138
	v_pk_mul_f32 v[130:131], v[94:95], v[130:131]
	v_pk_mul_f32 v[132:133], v[96:97], v[132:133]

; DEV unsigned pack2h(float a, float b) { unsigned r; asm("v_cvt_pk_bf16_f32 %0, %1, %2" : "=v"(r) : "v"(a), "v"(b)); return r; }
; DEV float bflo(unsigned u) { return __uint_as_float(u << 16); }
; DEV float bfhi(unsigned u) { return __uint_as_float(u & 0xffff0000u); }
; DEV float sigm(float x) { return __builtin_amdgcn_rcpf(1.f + __expf(-x)); }
; DEV void gemm_phase(const GemmJob& J) {
;     ...
;               for (int m = 0; m < 4; ++m) {
;                 f32x4 v = acc[ai][bj][m][n];
;                 float v0 = v[0], v1 = v[1], v2 = v[2], v3 = v[3];
;                 if (mode == 4) {
;                   v0 = fmaxf(v0, 0.f); v1 = fmaxf(v1, 0.f); v2 = fmaxf(v2, 0.f); v3 = fmaxf(v3, 0.f);
;                   v0 *= v0; v1 *= v1; v2 *= v2; v3 *= v3;
;                 } else if (mode == 2) {
;                   const u32x2 gb = *(const u32x2*)(J.gate + (long)(brow + ai * HALF + wr * 64 + m * 16 + fr) * LDR + C_GB + bcol + bj * HALF + wc * 32 + n * 16 + fq * 4);
;                   v0 *= sigm(bflo(gb.x)); v1 *= sigm(bfhi(gb.x)); v2 *= sigm(bflo(gb.y)); v3 *= sigm(bfhi(gb.y));
;                 }
;                 u32x2 o; o.x = pack2h(v0, v1); o.y = pack2h(v2, v3);
;                 *(u32x2*)(sw + m * 16 * 264 + bj * HALF + n * 16) = o;
.LBB0_288:
	v_cvt_pk_bf16_f32 v130, v130, v131
	s_nop 0
	v_cvt_pk_bf16_f32 v131, v132, v133
	s_and_b64 vcc, exec, s[8:9]
	s_mov_b64 s[0:1], -1
	ds_write_b64 v159, v[130:131] offset:288
	s_cbranch_vccnz .LBB0_292
	s_andn2_b64 vcc, exec, s[14:15]
	v_mov_b32_e32 v133, v89
	v_mov_b32_e32 v132, v88
	v_mov_b32_e32 v131, v87
	v_mov_b32_e32 v130, v86
	s_cbranch_vccnz .LBB0_291
	v_or_b32_e32 v4, 16, v163
	v_mov_b32_e32 v130, v218
	v_mov_b32_e32 v131, v219
	v_lshlrev_b32_e32 v4, 16, v130
	v_and_b32_e32 v130, 0xffff0000, v130
	v_lshlrev_b32_e32 v132, 16, v131
	v_and_b32_e32 v131, 0xffff0000, v131
	v_mul_f32_e32 v4, 0xbfb8aa3b, v4
	v_mul_f32_e32 v130, 0xbfb8aa3b, v130
	v_mul_f32_e32 v132, 0xbfb8aa3b, v132
	v_mul_f32_e32 v131, 0xbfb8aa3b, v131
	v_exp_f32_e32 v4, v4
	v_exp_f32_e32 v130, v130
	v_exp_f32_e32 v132, v132
	v_exp_f32_e32 v131, v131
	v_add_f32_e32 v4, 1.0, v4
	v_add_f32_e32 v133, 1.0, v130
	v_add_f32_e32 v132, 1.0, v132
	v_add_f32_e32 v138, 1.0, v131
	v_rcp_f32_e32 v130, v4
	v_rcp_f32_e32 v131, v133
	v_rcp_f32_e32 v132, v132
	v_rcp_f32_e32 v133, v138
	v_pk_mul_f32 v[130:131], v[86:87], v[130:131]
	v_pk_mul_f32 v[132:133], v[88:89], v[132:133]

; DEV unsigned pack2h(float a, float b) { unsigned r; asm("v_cvt_pk_bf16_f32 %0, %1, %2" : "=v"(r) : "v"(a), "v"(b)); return r; }
; DEV float bflo(unsigned u) { return __uint_as_float(u << 16); }
; DEV float bfhi(unsigned u) { return __uint_as_float(u & 0xffff0000u); }
; DEV float sigm(float x) { return __builtin_amdgcn_rcpf(1.f + __expf(-x)); }
; DEV void gemm_phase(const GemmJob& J) {
;     ...
;               for (int m = 0; m < 4; ++m) {
;                 f32x4 v = acc[ai][bj][m][n];
;                 float v0 = v[0], v1 = v[1], v2 = v[2], v3 = v[3];
;                 if (mode == 4) {
;                   v0 = fmaxf(v0, 0.f); v1 = fmaxf(v1, 0.f); v2 = fmaxf(v2, 0.f); v3 = fmaxf(v3, 0.f);
;                   v0 *= v0; v1 *= v1; v2 *= v2; v3 *= v3;
;                 } else if (mode == 2) {
;                   const u32x2 gb = *(const u32x2*)(J.gate + (long)(brow + ai * HALF + wr * 64 + m * 16 + fr) * LDR + C_GB + bcol + bj * HALF + wc * 32 + n * 16 + fq * 4);
;                   v0 *= sigm(bflo(gb.x)); v1 *= sigm(bfhi(gb.x)); v2 *= sigm(bflo(gb.y)); v3 *= sigm(bfhi(gb.y));
;                 }
;                 u32x2 o; o.x = pack2h(v0, v1); o.y = pack2h(v2, v3);
;                 *(u32x2*)(sw + m * 16 * 264 + bj * HALF + n * 16) = o;
.LBB0_294:
	v_cvt_pk_bf16_f32 v130, v130, v131
	s_nop 0
	v_cvt_pk_bf16_f32 v131, v132, v133
	s_and_b64 vcc, exec, s[8:9]
	s_mov_b64 s[0:1], -1
	ds_write_b64 v159, v[130:131] offset:8736
	s_cbranch_vccnz .LBB0_298
	s_andn2_b64 vcc, exec, s[14:15]
	v_mov_b32_e32 v133, v81
	v_mov_b32_e32 v132, v80
	v_mov_b32_e32 v131, v79
	v_mov_b32_e32 v130, v78
	s_cbranch_vccnz .LBB0_297
	v_or_b32_e32 v4, 32, v163
	v_mov_b32_e32 v130, v220
	v_mov_b32_e32 v131, v221
	v_lshlrev_b32_e32 v4, 16, v130
	v_and_b32_e32 v130, 0xffff0000, v130
	v_lshlrev_b32_e32 v132, 16, v131
	v_and_b32_e32 v131, 0xffff0000, v131
	v_mul_f32_e32 v4, 0xbfb8aa3b, v4
	v_mul_f32_e32 v130, 0xbfb8aa3b, v130
	v_mul_f32_e32 v132, 0xbfb8aa3b, v132
	v_mul_f32_e32 v131, 0xbfb8aa3b, v131
	v_exp_f32_e32 v4, v4
	v_exp_f32_e32 v130, v130
	v_exp_f32_e32 v132, v132
	v_exp_f32_e32 v131, v131
	v_add_f32_e32 v4, 1.0, v4
	v_add_f32_e32 v133, 1.0, v130
	v_add_f32_e32 v132, 1.0, v132
	v_add_f32_e32 v138, 1.0, v131
	v_rcp_f32_e32 v130, v4
	v_rcp_f32_e32 v131, v133
	v_rcp_f32_e32 v132, v132
	v_rcp_f32_e32 v133, v138
	v_pk_mul_f32 v[130:131], v[78:79], v[130:131]
	v_pk_mul_f32 v[132:133], v[80:81], v[132:133]

; DEV unsigned pack2h(float a, float b) { unsigned r; asm("v_cvt_pk_bf16_f32 %0, %1, %2" : "=v"(r) : "v"(a), "v"(b)); return r; }
; DEV float bflo(unsigned u) { return __uint_as_float(u << 16); }
; DEV float bfhi(unsigned u) { return __uint_as_float(u & 0xffff0000u); }
; DEV float sigm(float x) { return __builtin_amdgcn_rcpf(1.f + __expf(-x)); }
; DEV void gemm_phase(const GemmJob& J) {
;     ...
;               for (int m = 0; m < 4; ++m) {
;                 f32x4 v = acc[ai][bj][m][n];
;                 float v0 = v[0], v1 = v[1], v2 = v[2], v3 = v[3];
;                 if (mode == 4) {
;                   v0 = fmaxf(v0, 0.f); v1 = fmaxf(v1, 0.f); v2 = fmaxf(v2, 0.f); v3 = fmaxf(v3, 0.f);
;                   v0 *= v0; v1 *= v1; v2 *= v2; v3 *= v3;
;                 } else if (mode == 2) {
;                   const u32x2 gb = *(const u32x2*)(J.gate + (long)(brow + ai * HALF + wr * 64 + m * 16 + fr) * LDR + C_GB + bcol + bj * HALF + wc * 32 + n * 16 + fq * 4);
;                   v0 *= sigm(bflo(gb.x)); v1 *= sigm(bfhi(gb.x)); v2 *= sigm(bflo(gb.y)); v3 *= sigm(bfhi(gb.y));
;                 }
;                 u32x2 o; o.x = pack2h(v0, v1); o.y = pack2h(v2, v3);
;                 *(u32x2*)(sw + m * 16 * 264 + bj * HALF + n * 16) = o;
.LBB0_300:
	v_cvt_pk_bf16_f32 v130, v130, v131
	s_nop 0
	v_cvt_pk_bf16_f32 v131, v132, v133
	s_and_b64 vcc, exec, s[8:9]
	s_mov_b64 s[0:1], -1
	ds_write_b64 v159, v[130:131] offset:17184
	s_cbranch_vccnz .LBB0_304
	s_andn2_b64 vcc, exec, s[14:15]
	v_mov_b32_e32 v131, v73
	v_mov_b32_e32 v130, v72
	v_mov_b32_e32 v133, v71
	v_mov_b32_e32 v132, v70
	s_cbranch_vccnz .LBB0_303
	v_or_b32_e32 v4, 48, v163
	v_mov_b32_e32 v130, v222
	v_mov_b32_e32 v131, v223
	v_lshlrev_b32_e32 v4, 16, v130
	v_and_b32_e32 v130, 0xffff0000, v130
	v_lshlrev_b32_e32 v132, 16, v131
	v_and_b32_e32 v131, 0xffff0000, v131
	v_mul_f32_e32 v4, 0xbfb8aa3b, v4
	v_mul_f32_e32 v130, 0xbfb8aa3b, v130
	v_mul_f32_e32 v132, 0xbfb8aa3b, v132
	v_mul_f32_e32 v131, 0xbfb8aa3b, v131
	v_exp_f32_e32 v4, v4
	v_exp_f32_e32 v130, v130
	v_exp_f32_e32 v132, v132
	v_exp_f32_e32 v131, v131
	v_add_f32_e32 v4, 1.0, v4
	v_add_f32_e32 v133, 1.0, v130
	v_add_f32_e32 v132, 1.0, v132
	v_add_f32_e32 v139, 1.0, v131
	v_rcp_f32_e32 v130, v4
	v_rcp_f32_e32 v131, v133
	v_rcp_f32_e32 v138, v132
	v_rcp_f32_e32 v139, v139
	v_pk_mul_f32 v[132:133], v[70:71], v[130:131]
	v_pk_mul_f32 v[130:131], v[72:73], v[138:139]

; DEV unsigned pack2h(float a, float b) { unsigned r; asm("v_cvt_pk_bf16_f32 %0, %1, %2" : "=v"(r) : "v"(a), "v"(b)); return r; }
; DEV float bflo(unsigned u) { return __uint_as_float(u << 16); }
; DEV float bfhi(unsigned u) { return __uint_as_float(u & 0xffff0000u); }
; #define LBAR() do { asm volatile("s_waitcnt lgkmcnt(0)" ::: "memory"); __builtin_amdgcn_s_barrier(); asm volatile("" ::: "memory"); } while (0)
; DEV float sigm(float x) { return __builtin_amdgcn_rcpf(1.f + __expf(-x)); }
; DEV void gemm_phase(const GemmJob& J) {
;     ...
;               for (int m = 0; m < 4; ++m) {
;                 f32x4 v = acc[ai][bj][m][n];
;                 float v0 = v[0], v1 = v[1], v2 = v[2], v3 = v[3];
;                 if (mode == 4) {
;                   v0 = fmaxf(v0, 0.f); v1 = fmaxf(v1, 0.f); v2 = fmaxf(v2, 0.f); v3 = fmaxf(v3, 0.f);
;                   v0 *= v0; v1 *= v1; v2 *= v2; v3 *= v3;
;                 } else if (mode == 2) {
;                   const u32x2 gb = *(const u32x2*)(J.gate + (long)(brow + ai * HALF + wr * 64 + m * 16 + fr) * LDR + C_GB + bcol + bj * HALF + wc * 32 + n * 16 + fq * 4);
;                   v0 *= sigm(bflo(gb.x)); v1 *= sigm(bfhi(gb.x)); v2 *= sigm(bflo(gb.y)); v3 *= sigm(bfhi(gb.y));
;                 }
;                 u32x2 o; o.x = pack2h(v0, v1); o.y = pack2h(v2, v3);
;                 *(u32x2*)(sw + m * 16 * 264 + bj * HALF + n * 16) = o;
;     ...
;           LBAR();
;           const long orow = brow + ai * HALF + wid * 16 + (lane >> 5);
;           const int ce = bcol + (lane & 31) * 8;
;           u16* gp; long gstep;
;           if (bcol < J.hsplit) { gp = J.ha + ((long)(ce >> 6) * J.M + orow) * 64 + (ce & 63); gstep = 128; }
;           else { gp = J.obf + orow * J.ldo + (ce - J.cofs); gstep = 2 * J.ldo; }
; #pragma unroll
;           for (int i = 0; i < 8; ++i) {
;             u32x4 d = *(const u32x4*)(sr + i * 2 * 264);
;             if (i >= 4) d = (u32x4){d.z, d.w, d.x, d.y};
;             __builtin_nontemporal_store(d, (u32x4*)gp);
;             gp += gstep;
;           }
;           LBAR();
.LBB0_313:
	v_or_b32_e32 v132, v148, v150
	s_movk_i32 s1, 0x210
	v_mul_lo_u32 v132, v132, s1
	v_lshlrev_b32_e32 v133, 1, v149
	v_add3_u32 v141, 16, v132, v133
	ds_read_b128 v[148:151], v141
	s_lshl_b32 s56, s0, 1
	v_add_u32_e32 v165, 0x80, v163
	s_mov_b64 s[0:1], -1
	s_and_b64 vcc, exec, s[10:11]
	s_waitcnt lgkmcnt(0)
	global_store_dwordx4 v[130:131], v[148:151], off nt
	s_nop 1
	v_lshl_add_u64 v[148:149], v[130:131], 0, s[56:57]
	ds_read_b128 v[130:133], v141 offset:1056
	s_waitcnt lgkmcnt(0)
	global_store_dwordx4 v[148:149], v[130:133], off nt
	ds_read_b128 v[130:133], v141 offset:2112
	v_lshl_add_u64 v[148:149], v[148:149], 0, s[56:57]
	s_waitcnt lgkmcnt(0)
	global_store_dwordx4 v[148:149], v[130:133], off nt
	ds_read_b128 v[130:133], v141 offset:3168
	v_lshl_add_u64 v[148:149], v[148:149], 0, s[56:57]
	v_lshl_add_u64 v[152:153], v[148:149], 0, s[56:57]
	s_waitcnt lgkmcnt(0)
	global_store_dwordx4 v[148:149], v[130:133], off nt
	ds_read_b128 v[130:133], v141 offset:4224
	s_waitcnt lgkmcnt(0)
	v_mov_b32_e32 v148, v132
	v_mov_b32_e32 v149, v133
	v_mov_b32_e32 v150, v130
	v_mov_b32_e32 v151, v131
	ds_read_b128 v[130:133], v141 offset:5280
	global_store_dwordx4 v[152:153], v[148:151], off nt
	v_lshl_add_u64 v[152:153], v[152:153], 0, s[56:57]
	s_waitcnt lgkmcnt(0)
	v_mov_b32_e32 v148, v132
	v_mov_b32_e32 v149, v133
	v_mov_b32_e32 v150, v130
	v_mov_b32_e32 v151, v131
	ds_read_b128 v[130:133], v141 offset:6336
	global_store_dwordx4 v[152:153], v[148:151], off nt
	v_lshl_add_u64 v[152:153], v[152:153], 0, s[56:57]
	s_waitcnt lgkmcnt(0)
	v_mov_b32_e32 v148, v132
	v_mov_b32_e32 v149, v133
	v_mov_b32_e32 v150, v130
	v_mov_b32_e32 v151, v131
	ds_read_b128 v[130:133], v141 offset:7392
	global_store_dwordx4 v[152:153], v[148:151], off nt
	v_lshl_add_u64 v[152:153], v[152:153], 0, s[56:57]
	s_waitcnt lgkmcnt(0)
	v_mov_b32_e32 v148, v132
	v_mov_b32_e32 v149, v133
	v_mov_b32_e32 v150, v130
	v_mov_b32_e32 v151, v131
	global_store_dwordx4 v[152:153], v[148:151], off nt
	s_waitcnt lgkmcnt(0)
	s_barrier
	s_cbranch_vccnz .LBB0_339
	s_andn2_b64 vcc, s[58:59], s[14:15]
	s_cbranch_vccnz .Lfast1_h1
	s_andn2_b64 vcc, exec, s[58:59]
	s_cbranch_vccnz .Lfast4_h1
	s_and_b64 vcc, exec, s[8:9]
	s_cbranch_vccnz .LBB0_318
	s_andn2_b64 vcc, exec, s[14:15]
	v_mov_b32_e32 v133, v69
	v_mov_b32_e32 v132, v68
	v_mov_b32_e32 v131, v67
	v_mov_b32_e32 v130, v66
	s_cbranch_vccnz .LBB0_317
	v_mov_b32_e32 v130, v224
	v_mov_b32_e32 v131, v225
	v_lshlrev_b32_e32 v132, 16, v130
	v_and_b32_e32 v130, 0xffff0000, v130
	v_lshlrev_b32_e32 v133, 16, v131
	v_and_b32_e32 v131, 0xffff0000, v131
	v_mul_f32_e32 v132, 0xbfb8aa3b, v132
	v_mul_f32_e32 v130, 0xbfb8aa3b, v130
	v_mul_f32_e32 v133, 0xbfb8aa3b, v133
	v_mul_f32_e32 v131, 0xbfb8aa3b, v131
	v_exp_f32_e32 v132, v132
	v_exp_f32_e32 v130, v130
	v_exp_f32_e32 v133, v133
	v_exp_f32_e32 v131, v131
	v_add_f32_e32 v132, 1.0, v132
	v_add_f32_e32 v148, 1.0, v130
	v_add_f32_e32 v133, 1.0, v133
	v_add_f32_e32 v149, 1.0, v131
	v_rcp_f32_e32 v130, v132
	v_rcp_f32_e32 v131, v148
	v_rcp_f32_e32 v132, v133
	v_rcp_f32_e32 v133, v149
	v_pk_mul_f32 v[130:131], v[66:67], v[130:131]
	v_pk_mul_f32 v[132:133], v[68:69], v[132:133]

; DEV unsigned pack2h(float a, float b) { unsigned r; asm("v_cvt_pk_bf16_f32 %0, %1, %2" : "=v"(r) : "v"(a), "v"(b)); return r; }
; DEV float bflo(unsigned u) { return __uint_as_float(u << 16); }
; DEV float bfhi(unsigned u) { return __uint_as_float(u & 0xffff0000u); }
; DEV float sigm(float x) { return __builtin_amdgcn_rcpf(1.f + __expf(-x)); }
; DEV void gemm_phase(const GemmJob& J) {
;     ...
;               for (int m = 0; m < 4; ++m) {
;                 f32x4 v = acc[ai][bj][m][n];
;                 float v0 = v[0], v1 = v[1], v2 = v[2], v3 = v[3];
;                 if (mode == 4) {
;                   v0 = fmaxf(v0, 0.f); v1 = fmaxf(v1, 0.f); v2 = fmaxf(v2, 0.f); v3 = fmaxf(v3, 0.f);
;                   v0 *= v0; v1 *= v1; v2 *= v2; v3 *= v3;
;                 } else if (mode == 2) {
;                   const u32x2 gb = *(const u32x2*)(J.gate + (long)(brow + ai * HALF + wr * 64 + m * 16 + fr) * LDR + C_GB + bcol + bj * HALF + wc * 32 + n * 16 + fq * 4);
;                   v0 *= sigm(bflo(gb.x)); v1 *= sigm(bfhi(gb.x)); v2 *= sigm(bflo(gb.y)); v3 *= sigm(bfhi(gb.y));
;                 }
;                 u32x2 o; o.x = pack2h(v0, v1); o.y = pack2h(v2, v3);
;                 *(u32x2*)(sw + m * 16 * 264 + bj * HALF + n * 16) = o;
.LBB0_320:
	v_cvt_pk_bf16_f32 v130, v130, v131
	s_nop 0
	v_cvt_pk_bf16_f32 v131, v132, v133
	s_and_b64 vcc, exec, s[8:9]
	s_mov_b64 s[0:1], -1
	ds_write_b64 v159, v[130:131]
	s_cbranch_vccnz .LBB0_324
	s_andn2_b64 vcc, exec, s[14:15]
	v_mov_b32_e32 v133, v61
	v_mov_b32_e32 v132, v60
	v_mov_b32_e32 v131, v59
	v_mov_b32_e32 v130, v58
	s_cbranch_vccnz .LBB0_323
	v_add_u32_e32 v132, 0x90, v163
	v_mov_b32_e32 v130, v226
	v_mov_b32_e32 v131, v227
	v_lshlrev_b32_e32 v132, 16, v130
	v_and_b32_e32 v130, 0xffff0000, v130
	v_lshlrev_b32_e32 v133, 16, v131
	v_and_b32_e32 v131, 0xffff0000, v131
	v_mul_f32_e32 v132, 0xbfb8aa3b, v132
	v_mul_f32_e32 v130, 0xbfb8aa3b, v130
	v_mul_f32_e32 v133, 0xbfb8aa3b, v133
	v_mul_f32_e32 v131, 0xbfb8aa3b, v131
	v_exp_f32_e32 v132, v132
	v_exp_f32_e32 v130, v130
	v_exp_f32_e32 v133, v133
	v_exp_f32_e32 v131, v131
	v_add_f32_e32 v132, 1.0, v132
	v_add_f32_e32 v148, 1.0, v130
	v_add_f32_e32 v133, 1.0, v133
	v_add_f32_e32 v149, 1.0, v131
	v_rcp_f32_e32 v130, v132
	v_rcp_f32_e32 v131, v148
	v_rcp_f32_e32 v132, v133
	v_rcp_f32_e32 v133, v149
	v_pk_mul_f32 v[130:131], v[58:59], v[130:131]
	v_pk_mul_f32 v[132:133], v[60:61], v[132:133]

; DEV unsigned pack2h(float a, float b) { unsigned r; asm("v_cvt_pk_bf16_f32 %0, %1, %2" : "=v"(r) : "v"(a), "v"(b)); return r; }
; DEV float bflo(unsigned u) { return __uint_as_float(u << 16); }
; DEV float bfhi(unsigned u) { return __uint_as_float(u & 0xffff0000u); }
; DEV float sigm(float x) { return __builtin_amdgcn_rcpf(1.f + __expf(-x)); }
; DEV void gemm_phase(const GemmJob& J) {
;     ...
;               for (int m = 0; m < 4; ++m) {
;                 f32x4 v = acc[ai][bj][m][n];
;                 float v0 = v[0], v1 = v[1], v2 = v[2], v3 = v[3];
;                 if (mode == 4) {
;                   v0 = fmaxf(v0, 0.f); v1 = fmaxf(v1, 0.f); v2 = fmaxf(v2, 0.f); v3 = fmaxf(v3, 0.f);
;                   v0 *= v0; v1 *= v1; v2 *= v2; v3 *= v3;
;                 } else if (mode == 2) {
;                   const u32x2 gb = *(const u32x2*)(J.gate + (long)(brow + ai * HALF + wr * 64 + m * 16 + fr) * LDR + C_GB + bcol + bj * HALF + wc * 32 + n * 16 + fq * 4);
;                   v0 *= sigm(bflo(gb.x)); v1 *= sigm(bfhi(gb.x)); v2 *= sigm(bflo(gb.y)); v3 *= sigm(bfhi(gb.y));
;                 }
;                 u32x2 o; o.x = pack2h(v0, v1); o.y = pack2h(v2, v3);
;                 *(u32x2*)(sw + m * 16 * 264 + bj * HALF + n * 16) = o;
.LBB0_326:
	v_cvt_pk_bf16_f32 v130, v130, v131
	s_nop 0
	v_cvt_pk_bf16_f32 v131, v132, v133
	s_and_b64 vcc, exec, s[8:9]
	s_mov_b64 s[0:1], -1
	ds_write_b64 v159, v[130:131] offset:8448
	s_cbranch_vccnz .LBB0_330
	s_andn2_b64 vcc, exec, s[14:15]
	v_mov_b32_e32 v133, v53
	v_mov_b32_e32 v132, v52
	v_mov_b32_e32 v131, v51
	v_mov_b32_e32 v130, v50
	s_cbranch_vccnz .LBB0_329
	v_add_u32_e32 v132, 0xa0, v163
	v_mov_b32_e32 v130, v228
	v_mov_b32_e32 v131, v229
	v_lshlrev_b32_e32 v132, 16, v130
	v_and_b32_e32 v130, 0xffff0000, v130
	v_lshlrev_b32_e32 v133, 16, v131
	v_and_b32_e32 v131, 0xffff0000, v131
	v_mul_f32_e32 v132, 0xbfb8aa3b, v132
	v_mul_f32_e32 v130, 0xbfb8aa3b, v130
	v_mul_f32_e32 v133, 0xbfb8aa3b, v133
	v_mul_f32_e32 v131, 0xbfb8aa3b, v131
	v_exp_f32_e32 v132, v132
	v_exp_f32_e32 v130, v130
	v_exp_f32_e32 v133, v133
	v_exp_f32_e32 v131, v131
	v_add_f32_e32 v132, 1.0, v132
	v_add_f32_e32 v148, 1.0, v130
	v_add_f32_e32 v133, 1.0, v133
	v_add_f32_e32 v149, 1.0, v131
	v_rcp_f32_e32 v130, v132
	v_rcp_f32_e32 v131, v148
	v_rcp_f32_e32 v132, v133
	v_rcp_f32_e32 v133, v149
	v_pk_mul_f32 v[130:131], v[50:51], v[130:131]
	v_pk_mul_f32 v[132:133], v[52:53], v[132:133]

; DEV unsigned pack2h(float a, float b) { unsigned r; asm("v_cvt_pk_bf16_f32 %0, %1, %2" : "=v"(r) : "v"(a), "v"(b)); return r; }
; DEV float bflo(unsigned u) { return __uint_as_float(u << 16); }
; DEV float bfhi(unsigned u) { return __uint_as_float(u & 0xffff0000u); }
; DEV float sigm(float x) { return __builtin_amdgcn_rcpf(1.f + __expf(-x)); }
; DEV void gemm_phase(const GemmJob& J) {
;     ...
;               for (int m = 0; m < 4; ++m) {
;                 f32x4 v = acc[ai][bj][m][n];
;                 float v0 = v[0], v1 = v[1], v2 = v[2], v3 = v[3];
;                 if (mode == 4) {
;                   v0 = fmaxf(v0, 0.f); v1 = fmaxf(v1, 0.f); v2 = fmaxf(v2, 0.f); v3 = fmaxf(v3, 0.f);
;                   v0 *= v0; v1 *= v1; v2 *= v2; v3 *= v3;
;                 } else if (mode == 2) {
;                   const u32x2 gb = *(const u32x2*)(J.gate + (long)(brow + ai * HALF + wr * 64 + m * 16 + fr) * LDR + C_GB + bcol + bj * HALF + wc * 32 + n * 16 + fq * 4);
;                   v0 *= sigm(bflo(gb.x)); v1 *= sigm(bfhi(gb.x)); v2 *= sigm(bflo(gb.y)); v3 *= sigm(bfhi(gb.y));
;                 }
;                 u32x2 o; o.x = pack2h(v0, v1); o.y = pack2h(v2, v3);
;                 *(u32x2*)(sw + m * 16 * 264 + bj * HALF + n * 16) = o;
.LBB0_332:
	v_cvt_pk_bf16_f32 v130, v130, v131
	s_nop 0
	v_cvt_pk_bf16_f32 v131, v132, v133
	s_and_b64 vcc, exec, s[8:9]
	s_mov_b64 s[0:1], -1
	ds_write_b64 v159, v[130:131] offset:16896
	s_cbranch_vccnz .LBB0_336
	s_andn2_b64 vcc, exec, s[14:15]
	v_mov_b32_e32 v131, v45
	v_mov_b32_e32 v130, v44
	v_mov_b32_e32 v133, v43
	v_mov_b32_e32 v132, v42
	s_cbranch_vccnz .LBB0_335
	v_add_u32_e32 v132, 0xb0, v163
	v_mov_b32_e32 v130, v230
	v_mov_b32_e32 v131, v231
	v_lshlrev_b32_e32 v132, 16, v130
	v_and_b32_e32 v130, 0xffff0000, v130
	v_lshlrev_b32_e32 v133, 16, v131
	v_and_b32_e32 v131, 0xffff0000, v131
	v_mul_f32_e32 v132, 0xbfb8aa3b, v132
	v_mul_f32_e32 v130, 0xbfb8aa3b, v130
	v_mul_f32_e32 v133, 0xbfb8aa3b, v133
	v_mul_f32_e32 v131, 0xbfb8aa3b, v131
	v_exp_f32_e32 v132, v132
	v_exp_f32_e32 v130, v130
	v_exp_f32_e32 v133, v133
	v_exp_f32_e32 v131, v131
	v_add_f32_e32 v132, 1.0, v132
	v_add_f32_e32 v148, 1.0, v130
	v_add_f32_e32 v133, 1.0, v133
	v_add_f32_e32 v149, 1.0, v131
	v_rcp_f32_e32 v130, v132
	v_rcp_f32_e32 v131, v148
	v_rcp_f32_e32 v148, v133
	v_rcp_f32_e32 v149, v149
	v_pk_mul_f32 v[132:133], v[42:43], v[130:131]
	v_pk_mul_f32 v[130:131], v[44:45], v[148:149]

; DEV unsigned pack2h(float a, float b) { unsigned r; asm("v_cvt_pk_bf16_f32 %0, %1, %2" : "=v"(r) : "v"(a), "v"(b)); return r; }
; DEV float bflo(unsigned u) { return __uint_as_float(u << 16); }
; DEV float bfhi(unsigned u) { return __uint_as_float(u & 0xffff0000u); }
; DEV float sigm(float x) { return __builtin_amdgcn_rcpf(1.f + __expf(-x)); }
; DEV void gemm_phase(const GemmJob& J) {
;     ...
;               for (int m = 0; m < 4; ++m) {
;                 f32x4 v = acc[ai][bj][m][n];
;                 float v0 = v[0], v1 = v[1], v2 = v[2], v3 = v[3];
;                 if (mode == 4) {
;                   v0 = fmaxf(v0, 0.f); v1 = fmaxf(v1, 0.f); v2 = fmaxf(v2, 0.f); v3 = fmaxf(v3, 0.f);
;                   v0 *= v0; v1 *= v1; v2 *= v2; v3 *= v3;
;                 } else if (mode == 2) {
;                   const u32x2 gb = *(const u32x2*)(J.gate + (long)(brow + ai * HALF + wr * 64 + m * 16 + fr) * LDR + C_GB + bcol + bj * HALF + wc * 32 + n * 16 + fq * 4);
;                   v0 *= sigm(bflo(gb.x)); v1 *= sigm(bfhi(gb.x)); v2 *= sigm(bflo(gb.y)); v3 *= sigm(bfhi(gb.y));
;                 }
;                 u32x2 o; o.x = pack2h(v0, v1); o.y = pack2h(v2, v3);
;                 *(u32x2*)(sw + m * 16 * 264 + bj * HALF + n * 16) = o;
.LBB0_341:
	s_and_b64 vcc, exec, s[10:11]
	s_mov_b64 s[0:1], -1
	ds_write_b64 v159, v[132:133] offset:25344
	s_cbranch_vccnz .LBB0_367
	s_and_b64 vcc, exec, s[8:9]
	s_cbranch_vccnz .LBB0_346
	s_andn2_b64 vcc, exec, s[14:15]
	v_mov_b32_e32 v133, v65
	v_mov_b32_e32 v132, v64
	v_mov_b32_e32 v131, v63
	v_mov_b32_e32 v130, v62
	s_cbranch_vccnz .LBB0_345
	v_mov_b32_e32 v130, v232
	v_mov_b32_e32 v131, v233
	v_lshlrev_b32_e32 v132, 16, v130
	v_and_b32_e32 v130, 0xffff0000, v130
	v_lshlrev_b32_e32 v133, 16, v131
	v_and_b32_e32 v131, 0xffff0000, v131
	v_mul_f32_e32 v132, 0xbfb8aa3b, v132
	v_mul_f32_e32 v130, 0xbfb8aa3b, v130
	v_mul_f32_e32 v133, 0xbfb8aa3b, v133
	v_mul_f32_e32 v131, 0xbfb8aa3b, v131
	v_exp_f32_e32 v132, v132
	v_exp_f32_e32 v130, v130
	v_exp_f32_e32 v133, v133
	v_exp_f32_e32 v131, v131
	v_add_f32_e32 v132, 1.0, v132
	v_add_f32_e32 v148, 1.0, v130
	v_add_f32_e32 v133, 1.0, v133
	v_add_f32_e32 v149, 1.0, v131
	v_rcp_f32_e32 v130, v132
	v_rcp_f32_e32 v131, v148
	v_rcp_f32_e32 v132, v133
	v_rcp_f32_e32 v133, v149
	v_pk_mul_f32 v[130:131], v[62:63], v[130:131]
	v_pk_mul_f32 v[132:133], v[64:65], v[132:133]

; DEV unsigned pack2h(float a, float b) { unsigned r; asm("v_cvt_pk_bf16_f32 %0, %1, %2" : "=v"(r) : "v"(a), "v"(b)); return r; }
; DEV float bflo(unsigned u) { return __uint_as_float(u << 16); }
; DEV float bfhi(unsigned u) { return __uint_as_float(u & 0xffff0000u); }
; DEV float sigm(float x) { return __builtin_amdgcn_rcpf(1.f + __expf(-x)); }
; DEV void gemm_phase(const GemmJob& J) {
;     ...
;               for (int m = 0; m < 4; ++m) {
;                 f32x4 v = acc[ai][bj][m][n];
;                 float v0 = v[0], v1 = v[1], v2 = v[2], v3 = v[3];
;                 if (mode == 4) {
;                   v0 = fmaxf(v0, 0.f); v1 = fmaxf(v1, 0.f); v2 = fmaxf(v2, 0.f); v3 = fmaxf(v3, 0.f);
;                   v0 *= v0; v1 *= v1; v2 *= v2; v3 *= v3;
;                 } else if (mode == 2) {
;                   const u32x2 gb = *(const u32x2*)(J.gate + (long)(brow + ai * HALF + wr * 64 + m * 16 + fr) * LDR + C_GB + bcol + bj * HALF + wc * 32 + n * 16 + fq * 4);
;                   v0 *= sigm(bflo(gb.x)); v1 *= sigm(bfhi(gb.x)); v2 *= sigm(bflo(gb.y)); v3 *= sigm(bfhi(gb.y));
;                 }
;                 u32x2 o; o.x = pack2h(v0, v1); o.y = pack2h(v2, v3);
;                 *(u32x2*)(sw + m * 16 * 264 + bj * HALF + n * 16) = o;
.LBB0_348:
	v_cvt_pk_bf16_f32 v130, v130, v131
	s_nop 0
	v_cvt_pk_bf16_f32 v131, v132, v133
	s_and_b64 vcc, exec, s[8:9]
	s_mov_b64 s[0:1], -1
	ds_write_b64 v159, v[130:131] offset:32
	s_cbranch_vccnz .LBB0_352
	s_andn2_b64 vcc, exec, s[14:15]
	v_mov_b32_e32 v133, v57
	v_mov_b32_e32 v132, v56
	v_mov_b32_e32 v131, v55
	v_mov_b32_e32 v130, v54
	s_cbranch_vccnz .LBB0_351
	v_add_u32_e32 v132, 0x90, v163
	v_mov_b32_e32 v130, v234
	v_mov_b32_e32 v131, v235
	v_lshlrev_b32_e32 v132, 16, v130
	v_and_b32_e32 v130, 0xffff0000, v130
	v_lshlrev_b32_e32 v133, 16, v131
	v_and_b32_e32 v131, 0xffff0000, v131
	v_mul_f32_e32 v132, 0xbfb8aa3b, v132
	v_mul_f32_e32 v130, 0xbfb8aa3b, v130
	v_mul_f32_e32 v133, 0xbfb8aa3b, v133
	v_mul_f32_e32 v131, 0xbfb8aa3b, v131
	v_exp_f32_e32 v132, v132
	v_exp_f32_e32 v130, v130
	v_exp_f32_e32 v133, v133
	v_exp_f32_e32 v131, v131
	v_add_f32_e32 v132, 1.0, v132
	v_add_f32_e32 v148, 1.0, v130
	v_add_f32_e32 v133, 1.0, v133
	v_add_f32_e32 v149, 1.0, v131
	v_rcp_f32_e32 v130, v132
	v_rcp_f32_e32 v131, v148
	v_rcp_f32_e32 v132, v133
	v_rcp_f32_e32 v133, v149
	v_pk_mul_f32 v[130:131], v[54:55], v[130:131]
	v_pk_mul_f32 v[132:133], v[56:57], v[132:133]

; DEV unsigned pack2h(float a, float b) { unsigned r; asm("v_cvt_pk_bf16_f32 %0, %1, %2" : "=v"(r) : "v"(a), "v"(b)); return r; }
; DEV float bflo(unsigned u) { return __uint_as_float(u << 16); }
; DEV float bfhi(unsigned u) { return __uint_as_float(u & 0xffff0000u); }
; DEV float sigm(float x) { return __builtin_amdgcn_rcpf(1.f + __expf(-x)); }
; DEV void gemm_phase(const GemmJob& J) {
;     ...
;               for (int m = 0; m < 4; ++m) {
;                 f32x4 v = acc[ai][bj][m][n];
;                 float v0 = v[0], v1 = v[1], v2 = v[2], v3 = v[3];
;                 if (mode == 4) {
;                   v0 = fmaxf(v0, 0.f); v1 = fmaxf(v1, 0.f); v2 = fmaxf(v2, 0.f); v3 = fmaxf(v3, 0.f);
;                   v0 *= v0; v1 *= v1; v2 *= v2; v3 *= v3;
;                 } else if (mode == 2) {
;                   const u32x2 gb = *(const u32x2*)(J.gate + (long)(brow + ai * HALF + wr * 64 + m * 16 + fr) * LDR + C_GB + bcol + bj * HALF + wc * 32 + n * 16 + fq * 4);
;                   v0 *= sigm(bflo(gb.x)); v1 *= sigm(bfhi(gb.x)); v2 *= sigm(bflo(gb.y)); v3 *= sigm(bfhi(gb.y));
;                 }
;                 u32x2 o; o.x = pack2h(v0, v1); o.y = pack2h(v2, v3);
;                 *(u32x2*)(sw + m * 16 * 264 + bj * HALF + n * 16) = o;
.LBB0_354:
	v_cvt_pk_bf16_f32 v130, v130, v131
	s_nop 0
	v_cvt_pk_bf16_f32 v131, v132, v133
	s_and_b64 vcc, exec, s[8:9]
	s_mov_b64 s[0:1], -1
	ds_write_b64 v159, v[130:131] offset:8480
	s_cbranch_vccnz .LBB0_358
	s_andn2_b64 vcc, exec, s[14:15]
	v_mov_b32_e32 v133, v49
	v_mov_b32_e32 v132, v48
	v_mov_b32_e32 v131, v47
	v_mov_b32_e32 v130, v46
	s_cbranch_vccnz .LBB0_357
	v_add_u32_e32 v132, 0xa0, v163
	v_mov_b32_e32 v130, v236
	v_mov_b32_e32 v131, v237
	v_lshlrev_b32_e32 v132, 16, v130
	v_and_b32_e32 v130, 0xffff0000, v130
	v_lshlrev_b32_e32 v133, 16, v131
	v_and_b32_e32 v131, 0xffff0000, v131
	v_mul_f32_e32 v132, 0xbfb8aa3b, v132
	v_mul_f32_e32 v130, 0xbfb8aa3b, v130
	v_mul_f32_e32 v133, 0xbfb8aa3b, v133
	v_mul_f32_e32 v131, 0xbfb8aa3b, v131
	v_exp_f32_e32 v132, v132
	v_exp_f32_e32 v130, v130
	v_exp_f32_e32 v133, v133
	v_exp_f32_e32 v131, v131
	v_add_f32_e32 v132, 1.0, v132
	v_add_f32_e32 v148, 1.0, v130
	v_add_f32_e32 v133, 1.0, v133
	v_add_f32_e32 v149, 1.0, v131
	v_rcp_f32_e32 v130, v132
	v_rcp_f32_e32 v131, v148
	v_rcp_f32_e32 v132, v133
	v_rcp_f32_e32 v133, v149
	v_pk_mul_f32 v[130:131], v[46:47], v[130:131]
	v_pk_mul_f32 v[132:133], v[48:49], v[132:133]

; DEV unsigned pack2h(float a, float b) { unsigned r; asm("v_cvt_pk_bf16_f32 %0, %1, %2" : "=v"(r) : "v"(a), "v"(b)); return r; }
; DEV float bflo(unsigned u) { return __uint_as_float(u << 16); }
; DEV float bfhi(unsigned u) { return __uint_as_float(u & 0xffff0000u); }
; DEV float sigm(float x) { return __builtin_amdgcn_rcpf(1.f + __expf(-x)); }
; DEV void gemm_phase(const GemmJob& J) {
;     ...
;               for (int m = 0; m < 4; ++m) {
;                 f32x4 v = acc[ai][bj][m][n];
;                 float v0 = v[0], v1 = v[1], v2 = v[2], v3 = v[3];
;                 if (mode == 4) {
;                   v0 = fmaxf(v0, 0.f); v1 = fmaxf(v1, 0.f); v2 = fmaxf(v2, 0.f); v3 = fmaxf(v3, 0.f);
;                   v0 *= v0; v1 *= v1; v2 *= v2; v3 *= v3;
;                 } else if (mode == 2) {
;                   const u32x2 gb = *(const u32x2*)(J.gate + (long)(brow + ai * HALF + wr * 64 + m * 16 + fr) * LDR + C_GB + bcol + bj * HALF + wc * 32 + n * 16 + fq * 4);
;                   v0 *= sigm(bflo(gb.x)); v1 *= sigm(bfhi(gb.x)); v2 *= sigm(bflo(gb.y)); v3 *= sigm(bfhi(gb.y));
;                 }
;                 u32x2 o; o.x = pack2h(v0, v1); o.y = pack2h(v2, v3);
;                 *(u32x2*)(sw + m * 16 * 264 + bj * HALF + n * 16) = o;
.LBB0_360:
	v_cvt_pk_bf16_f32 v130, v130, v131
	s_nop 0
	v_cvt_pk_bf16_f32 v131, v132, v133
	s_and_b64 vcc, exec, s[8:9]
	s_mov_b64 s[0:1], -1
	ds_write_b64 v159, v[130:131] offset:16928
	s_cbranch_vccnz .LBB0_364
	s_andn2_b64 vcc, exec, s[14:15]
	v_mov_b32_e32 v131, v41
	v_mov_b32_e32 v130, v40
	v_mov_b32_e32 v133, v39
	v_mov_b32_e32 v132, v38
	s_cbranch_vccnz .LBB0_363
	v_add_u32_e32 v132, 0xb0, v163
	v_mov_b32_e32 v130, v238
	v_mov_b32_e32 v131, v239
	v_lshlrev_b32_e32 v132, 16, v130
	v_and_b32_e32 v130, 0xffff0000, v130
	v_lshlrev_b32_e32 v133, 16, v131
	v_and_b32_e32 v131, 0xffff0000, v131
	v_mul_f32_e32 v132, 0xbfb8aa3b, v132
	v_mul_f32_e32 v130, 0xbfb8aa3b, v130
	v_mul_f32_e32 v133, 0xbfb8aa3b, v133
	v_mul_f32_e32 v131, 0xbfb8aa3b, v131
	v_exp_f32_e32 v132, v132
	v_exp_f32_e32 v130, v130
	v_exp_f32_e32 v133, v133
	v_exp_f32_e32 v131, v131
	v_add_f32_e32 v132, 1.0, v132
	v_add_f32_e32 v148, 1.0, v130
	v_add_f32_e32 v133, 1.0, v133
	v_add_f32_e32 v149, 1.0, v131
	v_rcp_f32_e32 v130, v132
	v_rcp_f32_e32 v131, v148
	v_rcp_f32_e32 v148, v133
	v_rcp_f32_e32 v149, v149
	v_pk_mul_f32 v[132:133], v[38:39], v[130:131]
	v_pk_mul_f32 v[130:131], v[40:41], v[148:149]

; DEV unsigned pack2h(float a, float b) { unsigned r; asm("v_cvt_pk_bf16_f32 %0, %1, %2" : "=v"(r) : "v"(a), "v"(b)); return r; }
; DEV float bflo(unsigned u) { return __uint_as_float(u << 16); }
; DEV float bfhi(unsigned u) { return __uint_as_float(u & 0xffff0000u); }
; DEV float sigm(float x) { return __builtin_amdgcn_rcpf(1.f + __expf(-x)); }
; DEV void gemm_phase(const GemmJob& J) {
;     ...
;               for (int m = 0; m < 4; ++m) {
;                 f32x4 v = acc[ai][bj][m][n];
;                 float v0 = v[0], v1 = v[1], v2 = v[2], v3 = v[3];
;                 if (mode == 4) {
;                   v0 = fmaxf(v0, 0.f); v1 = fmaxf(v1, 0.f); v2 = fmaxf(v2, 0.f); v3 = fmaxf(v3, 0.f);
;                   v0 *= v0; v1 *= v1; v2 *= v2; v3 *= v3;
;                 } else if (mode == 2) {
;                   const u32x2 gb = *(const u32x2*)(J.gate + (long)(brow + ai * HALF + wr * 64 + m * 16 + fr) * LDR + C_GB + bcol + bj * HALF + wc * 32 + n * 16 + fq * 4);
;                   v0 *= sigm(bflo(gb.x)); v1 *= sigm(bfhi(gb.x)); v2 *= sigm(bflo(gb.y)); v3 *= sigm(bfhi(gb.y));
;                 }
;                 u32x2 o; o.x = pack2h(v0, v1); o.y = pack2h(v2, v3);
;                 *(u32x2*)(sw + m * 16 * 264 + bj * HALF + n * 16) = o;
.LBB0_369:
	s_and_b64 vcc, exec, s[10:11]
	s_mov_b64 s[0:1], -1
	ds_write_b64 v159, v[132:133] offset:25376
	s_cbranch_vccnz .LBB0_395
	s_and_b64 vcc, exec, s[8:9]
	s_cbranch_vccnz .LBB0_374
	s_andn2_b64 vcc, exec, s[14:15]
	v_mov_b32_e32 v133, v37
	v_mov_b32_e32 v132, v36
	v_mov_b32_e32 v131, v35
	v_mov_b32_e32 v130, v34
	s_cbranch_vccnz .LBB0_373
	v_mov_b32_e32 v130, v240
	v_mov_b32_e32 v131, v241
	v_lshlrev_b32_e32 v132, 16, v130
	v_and_b32_e32 v130, 0xffff0000, v130
	v_lshlrev_b32_e32 v133, 16, v131
	v_and_b32_e32 v131, 0xffff0000, v131
	v_mul_f32_e32 v132, 0xbfb8aa3b, v132
	v_mul_f32_e32 v130, 0xbfb8aa3b, v130
	v_mul_f32_e32 v133, 0xbfb8aa3b, v133
	v_mul_f32_e32 v131, 0xbfb8aa3b, v131
	v_exp_f32_e32 v132, v132
	v_exp_f32_e32 v130, v130
	v_exp_f32_e32 v133, v133
	v_exp_f32_e32 v131, v131
	v_add_f32_e32 v132, 1.0, v132
	v_add_f32_e32 v148, 1.0, v130
	v_add_f32_e32 v133, 1.0, v133
	v_add_f32_e32 v149, 1.0, v131
	v_rcp_f32_e32 v130, v132
	v_rcp_f32_e32 v131, v148
	v_rcp_f32_e32 v132, v133
	v_rcp_f32_e32 v133, v149
	v_pk_mul_f32 v[130:131], v[34:35], v[130:131]
	v_pk_mul_f32 v[132:133], v[36:37], v[132:133]

; DEV unsigned pack2h(float a, float b) { unsigned r; asm("v_cvt_pk_bf16_f32 %0, %1, %2" : "=v"(r) : "v"(a), "v"(b)); return r; }
; DEV float bflo(unsigned u) { return __uint_as_float(u << 16); }
; DEV float bfhi(unsigned u) { return __uint_as_float(u & 0xffff0000u); }
; DEV float sigm(float x) { return __builtin_amdgcn_rcpf(1.f + __expf(-x)); }
; DEV void gemm_phase(const GemmJob& J) {
;     ...
;               for (int m = 0; m < 4; ++m) {
;                 f32x4 v = acc[ai][bj][m][n];
;                 float v0 = v[0], v1 = v[1], v2 = v[2], v3 = v[3];
;                 if (mode == 4) {
;                   v0 = fmaxf(v0, 0.f); v1 = fmaxf(v1, 0.f); v2 = fmaxf(v2, 0.f); v3 = fmaxf(v3, 0.f);
;                   v0 *= v0; v1 *= v1; v2 *= v2; v3 *= v3;
;                 } else if (mode == 2) {
;                   const u32x2 gb = *(const u32x2*)(J.gate + (long)(brow + ai * HALF + wr * 64 + m * 16 + fr) * LDR + C_GB + bcol + bj * HALF + wc * 32 + n * 16 + fq * 4);
;                   v0 *= sigm(bflo(gb.x)); v1 *= sigm(bfhi(gb.x)); v2 *= sigm(bflo(gb.y)); v3 *= sigm(bfhi(gb.y));
;                 }
;                 u32x2 o; o.x = pack2h(v0, v1); o.y = pack2h(v2, v3);
;                 *(u32x2*)(sw + m * 16 * 264 + bj * HALF + n * 16) = o;
.LBB0_376:
	v_cvt_pk_bf16_f32 v130, v130, v131
	s_nop 0
	v_cvt_pk_bf16_f32 v131, v132, v133
	s_and_b64 vcc, exec, s[8:9]
	s_mov_b64 s[0:1], -1
	ds_write_b64 v159, v[130:131] offset:256
	s_cbranch_vccnz .LBB0_380
	s_andn2_b64 vcc, exec, s[14:15]
	v_mov_b32_e32 v133, v29
	v_mov_b32_e32 v132, v28
	v_mov_b32_e32 v131, v27
	v_mov_b32_e32 v130, v26
	s_cbranch_vccnz .LBB0_379
	v_add_u32_e32 v132, 0x90, v163
	v_mov_b32_e32 v130, v242
	v_mov_b32_e32 v131, v243
	v_lshlrev_b32_e32 v132, 16, v130
	v_and_b32_e32 v130, 0xffff0000, v130
	v_lshlrev_b32_e32 v133, 16, v131
	v_and_b32_e32 v131, 0xffff0000, v131
	v_mul_f32_e32 v132, 0xbfb8aa3b, v132
	v_mul_f32_e32 v130, 0xbfb8aa3b, v130
	v_mul_f32_e32 v133, 0xbfb8aa3b, v133
	v_mul_f32_e32 v131, 0xbfb8aa3b, v131
	v_exp_f32_e32 v132, v132
	v_exp_f32_e32 v130, v130
	v_exp_f32_e32 v133, v133
	v_exp_f32_e32 v131, v131
	v_add_f32_e32 v132, 1.0, v132
	v_add_f32_e32 v148, 1.0, v130
	v_add_f32_e32 v133, 1.0, v133
	v_add_f32_e32 v149, 1.0, v131
	v_rcp_f32_e32 v130, v132
	v_rcp_f32_e32 v131, v148
	v_rcp_f32_e32 v132, v133
	v_rcp_f32_e32 v133, v149
	v_pk_mul_f32 v[130:131], v[26:27], v[130:131]
	v_pk_mul_f32 v[132:133], v[28:29], v[132:133]

; DEV unsigned pack2h(float a, float b) { unsigned r; asm("v_cvt_pk_bf16_f32 %0, %1, %2" : "=v"(r) : "v"(a), "v"(b)); return r; }
; DEV float bflo(unsigned u) { return __uint_as_float(u << 16); }
; DEV float bfhi(unsigned u) { return __uint_as_float(u & 0xffff0000u); }
; DEV float sigm(float x) { return __builtin_amdgcn_rcpf(1.f + __expf(-x)); }
; DEV void gemm_phase(const GemmJob& J) {
;     ...
;               for (int m = 0; m < 4; ++m) {
;                 f32x4 v = acc[ai][bj][m][n];
;                 float v0 = v[0], v1 = v[1], v2 = v[2], v3 = v[3];
;                 if (mode == 4) {
;                   v0 = fmaxf(v0, 0.f); v1 = fmaxf(v1, 0.f); v2 = fmaxf(v2, 0.f); v3 = fmaxf(v3, 0.f);
;                   v0 *= v0; v1 *= v1; v2 *= v2; v3 *= v3;
;                 } else if (mode == 2) {
;                   const u32x2 gb = *(const u32x2*)(J.gate + (long)(brow + ai * HALF + wr * 64 + m * 16 + fr) * LDR + C_GB + bcol + bj * HALF + wc * 32 + n * 16 + fq * 4);
;                   v0 *= sigm(bflo(gb.x)); v1 *= sigm(bfhi(gb.x)); v2 *= sigm(bflo(gb.y)); v3 *= sigm(bfhi(gb.y));
;                 }
;                 u32x2 o; o.x = pack2h(v0, v1); o.y = pack2h(v2, v3);
;                 *(u32x2*)(sw + m * 16 * 264 + bj * HALF + n * 16) = o;
.LBB0_382:
	v_cvt_pk_bf16_f32 v130, v130, v131
	s_nop 0
	v_cvt_pk_bf16_f32 v131, v132, v133
	s_and_b64 vcc, exec, s[8:9]
	s_mov_b64 s[0:1], -1
	ds_write_b64 v159, v[130:131] offset:8704
	s_cbranch_vccnz .LBB0_386
	s_andn2_b64 vcc, exec, s[14:15]
	v_mov_b32_e32 v133, v21
	v_mov_b32_e32 v132, v20
	v_mov_b32_e32 v131, v19
	v_mov_b32_e32 v130, v18
	s_cbranch_vccnz .LBB0_385
	v_add_u32_e32 v132, 0xa0, v163
	v_mov_b32_e32 v130, v244
	v_mov_b32_e32 v131, v245
	v_lshlrev_b32_e32 v132, 16, v130
	v_and_b32_e32 v130, 0xffff0000, v130
	v_lshlrev_b32_e32 v133, 16, v131
	v_and_b32_e32 v131, 0xffff0000, v131
	v_mul_f32_e32 v132, 0xbfb8aa3b, v132
	v_mul_f32_e32 v130, 0xbfb8aa3b, v130
	v_mul_f32_e32 v133, 0xbfb8aa3b, v133
	v_mul_f32_e32 v131, 0xbfb8aa3b, v131
	v_exp_f32_e32 v132, v132
	v_exp_f32_e32 v130, v130
	v_exp_f32_e32 v133, v133
	v_exp_f32_e32 v131, v131
	v_add_f32_e32 v132, 1.0, v132
	v_add_f32_e32 v148, 1.0, v130
	v_add_f32_e32 v133, 1.0, v133
	v_add_f32_e32 v149, 1.0, v131
	v_rcp_f32_e32 v130, v132
	v_rcp_f32_e32 v131, v148
	v_rcp_f32_e32 v132, v133
	v_rcp_f32_e32 v133, v149
	v_pk_mul_f32 v[130:131], v[18:19], v[130:131]
	v_pk_mul_f32 v[132:133], v[20:21], v[132:133]

; DEV unsigned pack2h(float a, float b) { unsigned r; asm("v_cvt_pk_bf16_f32 %0, %1, %2" : "=v"(r) : "v"(a), "v"(b)); return r; }
; DEV float bflo(unsigned u) { return __uint_as_float(u << 16); }
; DEV float bfhi(unsigned u) { return __uint_as_float(u & 0xffff0000u); }
; DEV float sigm(float x) { return __builtin_amdgcn_rcpf(1.f + __expf(-x)); }
; DEV void gemm_phase(const GemmJob& J) {
;     ...
;               for (int m = 0; m < 4; ++m) {
;                 f32x4 v = acc[ai][bj][m][n];
;                 float v0 = v[0], v1 = v[1], v2 = v[2], v3 = v[3];
;                 if (mode == 4) {
;                   v0 = fmaxf(v0, 0.f); v1 = fmaxf(v1, 0.f); v2 = fmaxf(v2, 0.f); v3 = fmaxf(v3, 0.f);
;                   v0 *= v0; v1 *= v1; v2 *= v2; v3 *= v3;
;                 } else if (mode == 2) {
;                   const u32x2 gb = *(const u32x2*)(J.gate + (long)(brow + ai * HALF + wr * 64 + m * 16 + fr) * LDR + C_GB + bcol + bj * HALF + wc * 32 + n * 16 + fq * 4);
;                   v0 *= sigm(bflo(gb.x)); v1 *= sigm(bfhi(gb.x)); v2 *= sigm(bflo(gb.y)); v3 *= sigm(bfhi(gb.y));
;                 }
;                 u32x2 o; o.x = pack2h(v0, v1); o.y = pack2h(v2, v3);
;                 *(u32x2*)(sw + m * 16 * 264 + bj * HALF + n * 16) = o;
.LBB0_388:
	v_cvt_pk_bf16_f32 v130, v130, v131
	s_nop 0
	v_cvt_pk_bf16_f32 v131, v132, v133
	s_and_b64 vcc, exec, s[8:9]
	s_mov_b64 s[0:1], -1
	ds_write_b64 v159, v[130:131] offset:17152
	s_cbranch_vccnz .LBB0_392
	s_andn2_b64 vcc, exec, s[14:15]
	v_mov_b32_e32 v131, v13
	v_mov_b32_e32 v130, v12
	v_mov_b32_e32 v133, v11
	v_mov_b32_e32 v132, v10
	s_cbranch_vccnz .LBB0_391
	v_add_u32_e32 v132, 0xb0, v163
	v_mov_b32_e32 v130, v246
	v_mov_b32_e32 v131, v247
	v_lshlrev_b32_e32 v132, 16, v130
	v_and_b32_e32 v130, 0xffff0000, v130
	v_lshlrev_b32_e32 v133, 16, v131
	v_and_b32_e32 v131, 0xffff0000, v131
	v_mul_f32_e32 v132, 0xbfb8aa3b, v132
	v_mul_f32_e32 v130, 0xbfb8aa3b, v130
	v_mul_f32_e32 v133, 0xbfb8aa3b, v133
	v_mul_f32_e32 v131, 0xbfb8aa3b, v131
	v_exp_f32_e32 v132, v132
	v_exp_f32_e32 v130, v130
	v_exp_f32_e32 v133, v133
	v_exp_f32_e32 v131, v131
	v_add_f32_e32 v132, 1.0, v132
	v_add_f32_e32 v148, 1.0, v130
	v_add_f32_e32 v133, 1.0, v133
	v_add_f32_e32 v149, 1.0, v131
	v_rcp_f32_e32 v130, v132
	v_rcp_f32_e32 v131, v148
	v_rcp_f32_e32 v148, v133
	v_rcp_f32_e32 v149, v149
	v_pk_mul_f32 v[132:133], v[10:11], v[130:131]
	v_pk_mul_f32 v[130:131], v[12:13], v[148:149]

; DEV unsigned pack2h(float a, float b) { unsigned r; asm("v_cvt_pk_bf16_f32 %0, %1, %2" : "=v"(r) : "v"(a), "v"(b)); return r; }
; DEV float bflo(unsigned u) { return __uint_as_float(u << 16); }
; DEV float bfhi(unsigned u) { return __uint_as_float(u & 0xffff0000u); }
; DEV float sigm(float x) { return __builtin_amdgcn_rcpf(1.f + __expf(-x)); }
; DEV void gemm_phase(const GemmJob& J) {
;     ...
;               for (int m = 0; m < 4; ++m) {
;                 f32x4 v = acc[ai][bj][m][n];
;                 float v0 = v[0], v1 = v[1], v2 = v[2], v3 = v[3];
;                 if (mode == 4) {
;                   v0 = fmaxf(v0, 0.f); v1 = fmaxf(v1, 0.f); v2 = fmaxf(v2, 0.f); v3 = fmaxf(v3, 0.f);
;                   v0 *= v0; v1 *= v1; v2 *= v2; v3 *= v3;
;                 } else if (mode == 2) {
;                   const u32x2 gb = *(const u32x2*)(J.gate + (long)(brow + ai * HALF + wr * 64 + m * 16 + fr) * LDR + C_GB + bcol + bj * HALF + wc * 32 + n * 16 + fq * 4);
;                   v0 *= sigm(bflo(gb.x)); v1 *= sigm(bfhi(gb.x)); v2 *= sigm(bflo(gb.y)); v3 *= sigm(bfhi(gb.y));
;                 }
;                 u32x2 o; o.x = pack2h(v0, v1); o.y = pack2h(v2, v3);
;                 *(u32x2*)(sw + m * 16 * 264 + bj * HALF + n * 16) = o;
.LBB0_397:
	s_and_b64 vcc, exec, s[10:11]
	s_mov_b64 s[0:1], -1
	ds_write_b64 v159, v[132:133] offset:25600
	s_cbranch_vccnz .LBB0_423
	s_and_b64 vcc, exec, s[8:9]
	v_cmp_ne_u32_e64 s[10:11], 1, v147
	s_cbranch_vccnz .LBB0_402
	s_and_b64 vcc, exec, s[10:11]
	v_mov_b32_e32 v133, v33
	v_mov_b32_e32 v132, v32
	v_mov_b32_e32 v131, v31
	v_mov_b32_e32 v130, v30
	s_cbranch_vccnz .LBB0_401
	v_mov_b32_e32 v130, v248
	v_mov_b32_e32 v131, v249
	v_lshlrev_b32_e32 v132, 16, v130
	v_and_b32_e32 v130, 0xffff0000, v130
	v_lshlrev_b32_e32 v133, 16, v131
	v_and_b32_e32 v131, 0xffff0000, v131
	v_mul_f32_e32 v132, 0xbfb8aa3b, v132
	v_mul_f32_e32 v130, 0xbfb8aa3b, v130
	v_mul_f32_e32 v133, 0xbfb8aa3b, v133
	v_mul_f32_e32 v131, 0xbfb8aa3b, v131
	v_exp_f32_e32 v132, v132
	v_exp_f32_e32 v130, v130
	v_exp_f32_e32 v133, v133
	v_exp_f32_e32 v131, v131
	v_add_f32_e32 v132, 1.0, v132
	v_add_f32_e32 v136, 1.0, v130
	v_add_f32_e32 v133, 1.0, v133
	v_add_f32_e32 v137, 1.0, v131
	v_rcp_f32_e32 v130, v132
	v_rcp_f32_e32 v131, v136
	v_rcp_f32_e32 v132, v133
	v_rcp_f32_e32 v133, v137
	v_pk_mul_f32 v[130:131], v[30:31], v[130:131]
	v_pk_mul_f32 v[132:133], v[32:33], v[132:133]

; DEV unsigned pack2h(float a, float b) { unsigned r; asm("v_cvt_pk_bf16_f32 %0, %1, %2" : "=v"(r) : "v"(a), "v"(b)); return r; }
; DEV float bflo(unsigned u) { return __uint_as_float(u << 16); }
; DEV float bfhi(unsigned u) { return __uint_as_float(u & 0xffff0000u); }
; DEV float sigm(float x) { return __builtin_amdgcn_rcpf(1.f + __expf(-x)); }
; DEV void gemm_phase(const GemmJob& J) {
;     ...
;               for (int m = 0; m < 4; ++m) {
;                 f32x4 v = acc[ai][bj][m][n];
;                 float v0 = v[0], v1 = v[1], v2 = v[2], v3 = v[3];
;                 if (mode == 4) {
;                   v0 = fmaxf(v0, 0.f); v1 = fmaxf(v1, 0.f); v2 = fmaxf(v2, 0.f); v3 = fmaxf(v3, 0.f);
;                   v0 *= v0; v1 *= v1; v2 *= v2; v3 *= v3;
;                 } else if (mode == 2) {
;                   const u32x2 gb = *(const u32x2*)(J.gate + (long)(brow + ai * HALF + wr * 64 + m * 16 + fr) * LDR + C_GB + bcol + bj * HALF + wc * 32 + n * 16 + fq * 4);
;                   v0 *= sigm(bflo(gb.x)); v1 *= sigm(bfhi(gb.x)); v2 *= sigm(bflo(gb.y)); v3 *= sigm(bfhi(gb.y));
;                 }
;                 u32x2 o; o.x = pack2h(v0, v1); o.y = pack2h(v2, v3);
;                 *(u32x2*)(sw + m * 16 * 264 + bj * HALF + n * 16) = o;
.LBB0_404:
	v_cvt_pk_bf16_f32 v130, v130, v131
	s_nop 0
	v_cvt_pk_bf16_f32 v131, v132, v133
	s_and_b64 vcc, exec, s[8:9]
	s_mov_b64 s[0:1], -1
	ds_write_b64 v159, v[130:131] offset:288
	s_cbranch_vccnz .LBB0_408
	s_and_b64 vcc, exec, s[10:11]
	v_mov_b32_e32 v133, v25
	v_mov_b32_e32 v132, v24
	v_mov_b32_e32 v131, v23
	v_mov_b32_e32 v130, v22
	s_cbranch_vccnz .LBB0_407
	v_add_u32_e32 v132, 0x90, v163
	v_mov_b32_e32 v130, v250
	v_mov_b32_e32 v131, v251
	v_lshlrev_b32_e32 v132, 16, v130
	v_and_b32_e32 v130, 0xffff0000, v130
	v_lshlrev_b32_e32 v133, 16, v131
	v_and_b32_e32 v131, 0xffff0000, v131
	v_mul_f32_e32 v132, 0xbfb8aa3b, v132
	v_mul_f32_e32 v130, 0xbfb8aa3b, v130
	v_mul_f32_e32 v133, 0xbfb8aa3b, v133
	v_mul_f32_e32 v131, 0xbfb8aa3b, v131
	v_exp_f32_e32 v132, v132
	v_exp_f32_e32 v130, v130
	v_exp_f32_e32 v133, v133
	v_exp_f32_e32 v131, v131
	v_add_f32_e32 v132, 1.0, v132
	v_add_f32_e32 v136, 1.0, v130
	v_add_f32_e32 v133, 1.0, v133
	v_add_f32_e32 v137, 1.0, v131
	v_rcp_f32_e32 v130, v132
	v_rcp_f32_e32 v131, v136
	v_rcp_f32_e32 v132, v133
	v_rcp_f32_e32 v133, v137
	v_pk_mul_f32 v[130:131], v[22:23], v[130:131]
	v_pk_mul_f32 v[132:133], v[24:25], v[132:133]

; DEV unsigned pack2h(float a, float b) { unsigned r; asm("v_cvt_pk_bf16_f32 %0, %1, %2" : "=v"(r) : "v"(a), "v"(b)); return r; }
; DEV float bflo(unsigned u) { return __uint_as_float(u << 16); }
; DEV float bfhi(unsigned u) { return __uint_as_float(u & 0xffff0000u); }
; DEV float sigm(float x) { return __builtin_amdgcn_rcpf(1.f + __expf(-x)); }
; DEV void gemm_phase(const GemmJob& J) {
;     ...
;               for (int m = 0; m < 4; ++m) {
;                 f32x4 v = acc[ai][bj][m][n];
;                 float v0 = v[0], v1 = v[1], v2 = v[2], v3 = v[3];
;                 if (mode == 4) {
;                   v0 = fmaxf(v0, 0.f); v1 = fmaxf(v1, 0.f); v2 = fmaxf(v2, 0.f); v3 = fmaxf(v3, 0.f);
;                   v0 *= v0; v1 *= v1; v2 *= v2; v3 *= v3;
;                 } else if (mode == 2) {
;                   const u32x2 gb = *(const u32x2*)(J.gate + (long)(brow + ai * HALF + wr * 64 + m * 16 + fr) * LDR + C_GB + bcol + bj * HALF + wc * 32 + n * 16 + fq * 4);
;                   v0 *= sigm(bflo(gb.x)); v1 *= sigm(bfhi(gb.x)); v2 *= sigm(bflo(gb.y)); v3 *= sigm(bfhi(gb.y));
;                 }
;                 u32x2 o; o.x = pack2h(v0, v1); o.y = pack2h(v2, v3);
;                 *(u32x2*)(sw + m * 16 * 264 + bj * HALF + n * 16) = o;
.LBB0_410:
	v_cvt_pk_bf16_f32 v130, v130, v131
	s_nop 0
	v_cvt_pk_bf16_f32 v131, v132, v133
	s_and_b64 vcc, exec, s[8:9]
	s_mov_b64 s[0:1], -1
	ds_write_b64 v159, v[130:131] offset:8736
	s_cbranch_vccnz .LBB0_414
	s_and_b64 vcc, exec, s[10:11]
	v_mov_b32_e32 v133, v17
	v_mov_b32_e32 v132, v16
	v_mov_b32_e32 v131, v15
	v_mov_b32_e32 v130, v14
	s_cbranch_vccnz .LBB0_413
	v_add_u32_e32 v132, 0xa0, v163
	v_mov_b32_e32 v130, v252
	v_mov_b32_e32 v131, v253
	v_lshlrev_b32_e32 v132, 16, v130
	v_and_b32_e32 v130, 0xffff0000, v130
	v_lshlrev_b32_e32 v133, 16, v131
	v_and_b32_e32 v131, 0xffff0000, v131
	v_mul_f32_e32 v132, 0xbfb8aa3b, v132
	v_mul_f32_e32 v130, 0xbfb8aa3b, v130
	v_mul_f32_e32 v133, 0xbfb8aa3b, v133
	v_mul_f32_e32 v131, 0xbfb8aa3b, v131
	v_exp_f32_e32 v132, v132
	v_exp_f32_e32 v130, v130
	v_exp_f32_e32 v133, v133
	v_exp_f32_e32 v131, v131
	v_add_f32_e32 v132, 1.0, v132
	v_add_f32_e32 v136, 1.0, v130
	v_add_f32_e32 v133, 1.0, v133
	v_add_f32_e32 v137, 1.0, v131
	v_rcp_f32_e32 v130, v132
	v_rcp_f32_e32 v131, v136
	v_rcp_f32_e32 v132, v133
	v_rcp_f32_e32 v133, v137
	v_pk_mul_f32 v[130:131], v[14:15], v[130:131]
	v_pk_mul_f32 v[132:133], v[16:17], v[132:133]

; DEV unsigned pack2h(float a, float b) { unsigned r; asm("v_cvt_pk_bf16_f32 %0, %1, %2" : "=v"(r) : "v"(a), "v"(b)); return r; }
; DEV float bflo(unsigned u) { return __uint_as_float(u << 16); }
; DEV float bfhi(unsigned u) { return __uint_as_float(u & 0xffff0000u); }
; DEV float sigm(float x) { return __builtin_amdgcn_rcpf(1.f + __expf(-x)); }
; DEV void gemm_phase(const GemmJob& J) {
;     ...
;               for (int m = 0; m < 4; ++m) {
;                 f32x4 v = acc[ai][bj][m][n];
;                 float v0 = v[0], v1 = v[1], v2 = v[2], v3 = v[3];
;                 if (mode == 4) {
;                   v0 = fmaxf(v0, 0.f); v1 = fmaxf(v1, 0.f); v2 = fmaxf(v2, 0.f); v3 = fmaxf(v3, 0.f);
;                   v0 *= v0; v1 *= v1; v2 *= v2; v3 *= v3;
;                 } else if (mode == 2) {
;                   const u32x2 gb = *(const u32x2*)(J.gate + (long)(brow + ai * HALF + wr * 64 + m * 16 + fr) * LDR + C_GB + bcol + bj * HALF + wc * 32 + n * 16 + fq * 4);
;                   v0 *= sigm(bflo(gb.x)); v1 *= sigm(bfhi(gb.x)); v2 *= sigm(bflo(gb.y)); v3 *= sigm(bfhi(gb.y));
;                 }
;                 u32x2 o; o.x = pack2h(v0, v1); o.y = pack2h(v2, v3);
;                 *(u32x2*)(sw + m * 16 * 264 + bj * HALF + n * 16) = o;
.LBB0_416:
	v_cvt_pk_bf16_f32 v130, v130, v131
	s_nop 0
	v_cvt_pk_bf16_f32 v131, v132, v133
	s_and_b64 vcc, exec, s[8:9]
	s_mov_b64 s[0:1], -1
	ds_write_b64 v159, v[130:131] offset:17184
	s_cbranch_vccnz .LBB0_420
	s_and_b64 vcc, exec, s[10:11]
	v_mov_b32_e32 v131, v9
	v_mov_b32_e32 v130, v8
	v_mov_b32_e32 v133, v7
	v_mov_b32_e32 v132, v6
	s_cbranch_vccnz .LBB0_419
	v_add_u32_e32 v132, 0xb0, v163
	v_mov_b32_e32 v130, v154
	v_mov_b32_e32 v131, v155
	v_lshlrev_b32_e32 v132, 16, v130
	v_and_b32_e32 v130, 0xffff0000, v130
	v_lshlrev_b32_e32 v133, 16, v131
	v_and_b32_e32 v131, 0xffff0000, v131
	v_mul_f32_e32 v132, 0xbfb8aa3b, v132
	v_mul_f32_e32 v130, 0xbfb8aa3b, v130
	v_mul_f32_e32 v133, 0xbfb8aa3b, v133
	v_mul_f32_e32 v131, 0xbfb8aa3b, v131
	v_exp_f32_e32 v132, v132
	v_exp_f32_e32 v130, v130
	v_exp_f32_e32 v133, v133
	v_exp_f32_e32 v131, v131
	v_add_f32_e32 v132, 1.0, v132
	v_add_f32_e32 v136, 1.0, v130
	v_add_f32_e32 v133, 1.0, v133
	v_add_f32_e32 v137, 1.0, v131
	v_rcp_f32_e32 v130, v132
	v_rcp_f32_e32 v131, v136
	v_rcp_f32_e32 v136, v133
	v_rcp_f32_e32 v137, v137
	v_pk_mul_f32 v[132:133], v[6:7], v[130:131]
	v_pk_mul_f32 v[130:131], v[8:9], v[136:137]

; DEV float bflo(unsigned u) { return __uint_as_float(u << 16); }
; DEV float bfhi(unsigned u) { return __uint_as_float(u & 0xffff0000u); }
; DEV void gemm_phase(const GemmJob& J) {
;     ...
;         const u16* gp = J.gate + (long)(brow + wr * 64 + fr) * LDR + bcol + wc * 32 + fq * 4;
; #pragma unroll
;         for (int ai = 0; ai < 2; ++ai)
; #pragma unroll
;           for (int bj = 0; bj < 2; ++bj) {
; #pragma unroll
;             for (int m = 0; m < 4; ++m)
; #pragma unroll
;               for (int n = 0; n < 2; ++n) {
;                 const u16* g2 = gp + (long)(ai * HALF + m * 16) * LDR + bj * HALF + n * 16;
;                 const u32x2 ga = *(const u32x2*)(g2 + C_GA), gb = *(const u32x2*)(g2 + C_GB);
;                 f32x4 v = acc[ai][bj][m][n];
;                 v[0] *= (1.f + __expf(-bflo(gb.x))) * __builtin_amdgcn_rcpf(1.f + __expf(-bflo(ga.x)));
;                 v[1] *= (1.f + __expf(-bfhi(gb.x))) * __builtin_amdgcn_rcpf(1.f + __expf(-bfhi(ga.x)));
;                 v[2] *= (1.f + __expf(-bflo(gb.y))) * __builtin_amdgcn_rcpf(1.f + __expf(-bflo(ga.y)));
;                 v[3] *= (1.f + __expf(-bfhi(gb.y))) * __builtin_amdgcn_rcpf(1.f + __expf(-bfhi(ga.y)));
;                 acc[ai][bj][m][n] = v;
;               }
.LBB0_433:
	v_lshl_add_u32 v4, v201, 6, s63
	v_or_b32_e32 v4, v4, v202
	v_mov_b64_e32 v[130:131], s[76:77]
	v_mad_i64_i32 v[130:131], s[0:1], v4, s61, v[130:131]
	s_ashr_i32 s49, s48, 31
	v_lshl_add_u64 v[130:131], s[48:49], 1, v[130:131]
	v_lshlrev_b32_e32 v4, 6, v200
	v_lshl_add_u64 v[130:131], v[130:131], 0, v[4:5]
	v_lshlrev_b32_e32 v4, 3, v199
	v_lshl_add_u64 v[130:131], v[130:131], 0, v[4:5]
	v_add_co_u32_e32 v132, vcc, 0x2000, v130
	s_nop 1
	v_addc_co_u32_e32 v133, vcc, 0, v131, vcc
	global_load_dwordx2 v[162:163], v[132:133], off offset:-2048
	global_load_dwordx2 v[164:165], v[132:133], off
	global_load_dwordx2 v[166:167], v[132:133], off offset:-2016
	global_load_dwordx2 v[168:169], v[132:133], off offset:32
	global_load_dwordx2 v[220:221], v[132:133], off offset:-1792
	global_load_dwordx2 v[222:223], v[132:133], off offset:256
	global_load_dwordx2 v[224:225], v[132:133], off offset:-1760
	global_load_dwordx2 v[226:227], v[132:133], off offset:288
	v_add_co_u32_e32 v132, vcc, 0x30000, v132
	s_nop 1
	v_addc_co_u32_e32 v133, vcc, 0, v133, vcc
	global_load_dwordx2 v[170:171], v[132:133], off offset:-2048
	global_load_dwordx2 v[172:173], v[132:133], off
	global_load_dwordx2 v[174:175], v[132:133], off offset:-2016
	global_load_dwordx2 v[176:177], v[132:133], off offset:32
	global_load_dwordx2 v[228:229], v[132:133], off offset:-1792
	global_load_dwordx2 v[230:231], v[132:133], off offset:256
	global_load_dwordx2 v[232:233], v[132:133], off offset:-1760
	global_load_dwordx2 v[234:235], v[132:133], off offset:288
	v_add_co_u32_e32 v132, vcc, 0x30000, v132
	s_nop 1
	v_addc_co_u32_e32 v133, vcc, 0, v133, vcc
	global_load_dwordx2 v[204:205], v[132:133], off offset:-2048
	global_load_dwordx2 v[206:207], v[132:133], off
	global_load_dwordx2 v[208:209], v[132:133], off offset:-2016
	global_load_dwordx2 v[210:211], v[132:133], off offset:32
	global_load_dwordx2 v[236:237], v[132:133], off offset:-1792
	global_load_dwordx2 v[238:239], v[132:133], off offset:256
	global_load_dwordx2 v[240:241], v[132:133], off offset:-1760
	global_load_dwordx2 v[242:243], v[132:133], off offset:288
	v_add_co_u32_e32 v132, vcc, 0x30000, v132
	s_nop 1
	v_addc_co_u32_e32 v133, vcc, 0, v133, vcc
	global_load_dwordx2 v[212:213], v[132:133], off offset:-2048
	global_load_dwordx2 v[214:215], v[132:133], off
	global_load_dwordx2 v[216:217], v[132:133], off offset:-2016
	global_load_dwordx2 v[218:219], v[132:133], off offset:32
	global_load_dwordx2 v[244:245], v[132:133], off offset:-1792
	global_load_dwordx2 v[246:247], v[132:133], off offset:256
	global_load_dwordx2 v[248:249], v[132:133], off offset:-1760
	global_load_dwordx2 v[250:251], v[132:133], off offset:288
	s_waitcnt vmcnt(0)
	v_add_co_u32_e32 v148, vcc, 0x1000, v130
	s_mov_b32 s0, 0x31000
	s_nop 0
	v_addc_co_u32_e32 v149, vcc, 0, v131, vcc
	v_add_co_u32_e32 v136, vcc, s60, v130
	v_mov_b32_e32 v132, v162
	v_mov_b32_e32 v133, v163
	s_nop 0
	v_addc_co_u32_e32 v137, vcc, 0, v131, vcc
	v_mov_b32_e32 v134, v164
	v_mov_b32_e32 v135, v165
	s_waitcnt vmcnt(0)
	v_lshlrev_b32_e32 v4, 16, v134
	v_mul_f32_e32 v4, 0xbfb8aa3b, v4
	v_exp_f32_e32 v138, v4
	v_lshlrev_b32_e32 v4, 16, v132
	v_mul_f32_e32 v4, 0xbfb8aa3b, v4
	v_exp_f32_e32 v4, v4
	s_nop 0
	v_add_f32_e32 v4, 1.0, v4
	v_rcp_f32_e32 v140, v4
	v_and_b32_e32 v4, 0xffff0000, v134
	v_mul_f32_e32 v4, 0xbfb8aa3b, v4
	v_exp_f32_e32 v139, v4
	v_and_b32_e32 v4, 0xffff0000, v132
	v_mul_f32_e32 v4, 0xbfb8aa3b, v4
	v_exp_f32_e32 v4, v4
	v_pk_add_f32 v[138:139], v[138:139], 1.0 op_sel_hi:[1,0]
	v_add_f32_e32 v4, 1.0, v4
	v_rcp_f32_e32 v141, v4
	v_lshlrev_b32_e32 v4, 16, v135
	v_mul_f32_e32 v4, 0xbfb8aa3b, v4
	v_exp_f32_e32 v134, v4
	v_lshlrev_b32_e32 v4, 16, v133
	v_mul_f32_e32 v4, 0xbfb8aa3b, v4
	v_exp_f32_e32 v4, v4
	v_pk_mul_f32 v[138:139], v[138:139], v[140:141]
	v_add_f32_e32 v4, 1.0, v4
	v_rcp_f32_e32 v132, v4
	v_and_b32_e32 v4, 0xffff0000, v135
	v_mul_f32_e32 v4, 0xbfb8aa3b, v4
	v_exp_f32_e32 v135, v4
	v_and_b32_e32 v4, 0xffff0000, v133
	v_mul_f32_e32 v4, 0xbfb8aa3b, v4
	v_exp_f32_e32 v4, v4
	v_pk_add_f32 v[134:135], v[134:135], 1.0 op_sel_hi:[1,0]
	v_pk_mul_f32 v[0:1], v[0:1], v[138:139]
	v_add_f32_e32 v4, 1.0, v4
	v_rcp_f32_e32 v133, v4
	s_nop 0
	v_pk_mul_f32 v[132:133], v[134:135], v[132:133]
	s_nop 0
	v_pk_mul_f32 v[2:3], v[2:3], v[132:133]
	v_mov_b32_e32 v132, v166
	v_mov_b32_e32 v133, v167
	v_mov_b32_e32 v134, v168
	v_mov_b32_e32 v135, v169
	s_waitcnt vmcnt(0)
	v_lshlrev_b32_e32 v4, 16, v134
	v_mul_f32_e32 v4, 0xbfb8aa3b, v4
	v_exp_f32_e32 v138, v4
	v_lshlrev_b32_e32 v4, 16, v132
	v_mul_f32_e32 v4, 0xbfb8aa3b, v4
	v_exp_f32_e32 v4, v4
	s_nop 0
	v_add_f32_e32 v4, 1.0, v4
	v_rcp_f32_e32 v140, v4
	v_and_b32_e32 v4, 0xffff0000, v134
	v_mul_f32_e32 v4, 0xbfb8aa3b, v4
	v_exp_f32_e32 v139, v4
	v_and_b32_e32 v4, 0xffff0000, v132
	v_mul_f32_e32 v4, 0xbfb8aa3b, v4
	v_exp_f32_e32 v4, v4
	v_pk_add_f32 v[138:139], v[138:139], 1.0 op_sel_hi:[1,0]
	v_add_f32_e32 v4, 1.0, v4
	v_rcp_f32_e32 v141, v4
	v_lshlrev_b32_e32 v4, 16, v135
	v_mul_f32_e32 v4, 0xbfb8aa3b, v4
	v_exp_f32_e32 v134, v4
	v_lshlrev_b32_e32 v4, 16, v133
	v_mul_f32_e32 v4, 0xbfb8aa3b, v4
	v_exp_f32_e32 v4, v4
	v_pk_mul_f32 v[138:139], v[138:139], v[140:141]
	v_add_co_u32_e32 v140, vcc, s0, v130
	v_add_f32_e32 v4, 1.0, v4
	v_rcp_f32_e32 v132, v4
	v_and_b32_e32 v4, 0xffff0000, v135
	v_mul_f32_e32 v4, 0xbfb8aa3b, v4
	v_exp_f32_e32 v135, v4
	v_and_b32_e32 v4, 0xffff0000, v133
	v_mul_f32_e32 v4, 0xbfb8aa3b, v4
	v_exp_f32_e32 v4, v4
	v_addc_co_u32_e32 v141, vcc, 0, v131, vcc
	s_mov_b32 s0, 0x32000
	v_add_f32_e32 v4, 1.0, v4
	v_rcp_f32_e32 v133, v4
	v_pk_add_f32 v[134:135], v[134:135], 1.0 op_sel_hi:[1,0]
	v_pk_mul_f32 v[126:127], v[126:127], v[138:139]
	v_add_co_u32_e32 v138, vcc, s0, v130
	v_pk_mul_f32 v[132:133], v[134:135], v[132:133]
	s_nop 0
	v_addc_co_u32_e32 v139, vcc, 0, v131, vcc
	v_pk_mul_f32 v[128:129], v[128:129], v[132:133]
	v_mov_b32_e32 v132, v170
	v_mov_b32_e32 v133, v171
	v_mov_b32_e32 v134, v172
	v_mov_b32_e32 v135, v173
	s_mov_b32 s0, 0x61000
	s_waitcnt vmcnt(0)
; DEV float bflo(unsigned u) { return __uint_as_float(u << 16); }
; DEV float bfhi(unsigned u) { return __uint_as_float(u & 0xffff0000u); }
; DEV void gemm_phase(const GemmJob& J) {
;     ...
;         const u16* gp = J.gate + (long)(brow + wr * 64 + fr) * LDR + bcol + wc * 32 + fq * 4;
; #pragma unroll
;         for (int ai = 0; ai < 2; ++ai)
; #pragma unroll
;           for (int bj = 0; bj < 2; ++bj) {
; #pragma unroll
;             for (int m = 0; m < 4; ++m)
; #pragma unroll
;               for (int n = 0; n < 2; ++n) {
;                 const u16* g2 = gp + (long)(ai * HALF + m * 16) * LDR + bj * HALF + n * 16;
;                 const u32x2 ga = *(const u32x2*)(g2 + C_GA), gb = *(const u32x2*)(g2 + C_GB);
;                 f32x4 v = acc[ai][bj][m][n];
;                 v[0] *= (1.f + __expf(-bflo(gb.x))) * __builtin_amdgcn_rcpf(1.f + __expf(-bflo(ga.x)));
;                 v[1] *= (1.f + __expf(-bfhi(gb.x))) * __builtin_amdgcn_rcpf(1.f + __expf(-bfhi(ga.x)));
;                 v[2] *= (1.f + __expf(-bflo(gb.y))) * __builtin_amdgcn_rcpf(1.f + __expf(-bflo(ga.y)));
;                 v[3] *= (1.f + __expf(-bfhi(gb.y))) * __builtin_amdgcn_rcpf(1.f + __expf(-bfhi(ga.y)));
;                 acc[ai][bj][m][n] = v;
;               }
	v_lshlrev_b32_e32 v4, 16, v134
	v_mul_f32_e32 v4, 0xbfb8aa3b, v4
	v_exp_f32_e32 v150, v4
	v_lshlrev_b32_e32 v4, 16, v132
	v_mul_f32_e32 v4, 0xbfb8aa3b, v4
	v_exp_f32_e32 v4, v4
	s_nop 0
	v_add_f32_e32 v4, 1.0, v4
	v_rcp_f32_e32 v152, v4
	v_and_b32_e32 v4, 0xffff0000, v134
	v_mul_f32_e32 v4, 0xbfb8aa3b, v4
	v_exp_f32_e32 v151, v4
	v_and_b32_e32 v4, 0xffff0000, v132
	v_mul_f32_e32 v4, 0xbfb8aa3b, v4
	v_exp_f32_e32 v4, v4
	v_pk_add_f32 v[150:151], v[150:151], 1.0 op_sel_hi:[1,0]
	v_add_f32_e32 v4, 1.0, v4
	v_rcp_f32_e32 v153, v4
	v_lshlrev_b32_e32 v4, 16, v135
	v_mul_f32_e32 v4, 0xbfb8aa3b, v4
	v_exp_f32_e32 v134, v4
	v_lshlrev_b32_e32 v4, 16, v133
	v_mul_f32_e32 v4, 0xbfb8aa3b, v4
	v_exp_f32_e32 v4, v4
	v_pk_mul_f32 v[150:151], v[150:151], v[152:153]
	v_add_f32_e32 v4, 1.0, v4
	v_rcp_f32_e32 v132, v4
	v_and_b32_e32 v4, 0xffff0000, v135
	v_mul_f32_e32 v4, 0xbfb8aa3b, v4
	v_exp_f32_e32 v135, v4
	v_and_b32_e32 v4, 0xffff0000, v133
	v_mul_f32_e32 v4, 0xbfb8aa3b, v4
	v_exp_f32_e32 v4, v4
	v_pk_add_f32 v[134:135], v[134:135], 1.0 op_sel_hi:[1,0]
	v_pk_mul_f32 v[122:123], v[122:123], v[150:151]
	v_add_f32_e32 v4, 1.0, v4
	v_rcp_f32_e32 v133, v4
	s_nop 0
	v_pk_mul_f32 v[132:133], v[134:135], v[132:133]
	s_nop 0
	v_pk_mul_f32 v[124:125], v[124:125], v[132:133]
	v_mov_b32_e32 v132, v174
	v_mov_b32_e32 v133, v175
	v_mov_b32_e32 v134, v176
	v_mov_b32_e32 v135, v177
	s_waitcnt vmcnt(0)
	v_lshlrev_b32_e32 v4, 16, v134
	v_mul_f32_e32 v4, 0xbfb8aa3b, v4
	v_exp_f32_e32 v150, v4
	v_lshlrev_b32_e32 v4, 16, v132
	v_mul_f32_e32 v4, 0xbfb8aa3b, v4
	v_exp_f32_e32 v4, v4
	s_nop 0
	v_add_f32_e32 v4, 1.0, v4
	v_rcp_f32_e32 v152, v4
	v_and_b32_e32 v4, 0xffff0000, v134
	v_mul_f32_e32 v4, 0xbfb8aa3b, v4
	v_exp_f32_e32 v151, v4
	v_and_b32_e32 v4, 0xffff0000, v132
	v_mul_f32_e32 v4, 0xbfb8aa3b, v4
	v_exp_f32_e32 v4, v4
	v_pk_add_f32 v[150:151], v[150:151], 1.0 op_sel_hi:[1,0]
	v_add_f32_e32 v4, 1.0, v4
	v_rcp_f32_e32 v153, v4
	v_lshlrev_b32_e32 v4, 16, v135
	v_mul_f32_e32 v4, 0xbfb8aa3b, v4
	v_exp_f32_e32 v134, v4
	v_lshlrev_b32_e32 v4, 16, v133
	v_mul_f32_e32 v4, 0xbfb8aa3b, v4
	v_exp_f32_e32 v4, v4
	v_pk_mul_f32 v[150:151], v[150:151], v[152:153]
	v_add_co_u32_e32 v152, vcc, s0, v130
	v_add_f32_e32 v4, 1.0, v4
	v_rcp_f32_e32 v132, v4
	v_and_b32_e32 v4, 0xffff0000, v135
	v_mul_f32_e32 v4, 0xbfb8aa3b, v4
	v_exp_f32_e32 v135, v4
	v_and_b32_e32 v4, 0xffff0000, v133
	v_mul_f32_e32 v4, 0xbfb8aa3b, v4
	v_exp_f32_e32 v4, v4
	v_pk_add_f32 v[134:135], v[134:135], 1.0 op_sel_hi:[1,0]
	v_addc_co_u32_e32 v153, vcc, 0, v131, vcc
	v_add_f32_e32 v4, 1.0, v4
	v_rcp_f32_e32 v133, v4
	s_mov_b32 s0, 0x62000
	v_pk_mul_f32 v[118:119], v[118:119], v[150:151]
	v_pk_mul_f32 v[132:133], v[134:135], v[132:133]
	v_add_co_u32_e32 v134, vcc, s0, v130
	v_pk_mul_f32 v[120:121], v[120:121], v[132:133]
	s_nop 0
	v_addc_co_u32_e32 v135, vcc, 0, v131, vcc
	v_mov_b32_e32 v132, v204
	v_mov_b32_e32 v133, v205
	v_mov_b32_e32 v150, v206
	v_mov_b32_e32 v151, v207
	s_mov_b32 s0, 0x91000
	s_waitcnt vmcnt(0)
	v_lshlrev_b32_e32 v4, 16, v150
	v_mul_f32_e32 v4, 0xbfb8aa3b, v4
	v_exp_f32_e32 v154, v4
	v_lshlrev_b32_e32 v4, 16, v132
	v_mul_f32_e32 v4, 0xbfb8aa3b, v4
	v_exp_f32_e32 v4, v4
	s_nop 0
	v_add_f32_e32 v4, 1.0, v4
	v_rcp_f32_e32 v156, v4
	v_and_b32_e32 v4, 0xffff0000, v150
	v_mul_f32_e32 v4, 0xbfb8aa3b, v4
	v_exp_f32_e32 v155, v4
	v_and_b32_e32 v4, 0xffff0000, v132
	v_mul_f32_e32 v4, 0xbfb8aa3b, v4
	v_exp_f32_e32 v4, v4
	v_pk_add_f32 v[154:155], v[154:155], 1.0 op_sel_hi:[1,0]
	v_add_f32_e32 v4, 1.0, v4
	v_rcp_f32_e32 v157, v4
	v_lshlrev_b32_e32 v4, 16, v151
	v_mul_f32_e32 v4, 0xbfb8aa3b, v4
	v_exp_f32_e32 v150, v4
	v_lshlrev_b32_e32 v4, 16, v133
	v_mul_f32_e32 v4, 0xbfb8aa3b, v4
	v_exp_f32_e32 v4, v4
	v_pk_mul_f32 v[154:155], v[154:155], v[156:157]
	v_add_f32_e32 v4, 1.0, v4
	v_rcp_f32_e32 v132, v4
	v_and_b32_e32 v4, 0xffff0000, v151
	v_mul_f32_e32 v4, 0xbfb8aa3b, v4
	v_exp_f32_e32 v151, v4
	v_and_b32_e32 v4, 0xffff0000, v133
	v_mul_f32_e32 v4, 0xbfb8aa3b, v4
	v_exp_f32_e32 v4, v4
	v_pk_add_f32 v[150:151], v[150:151], 1.0 op_sel_hi:[1,0]
	v_pk_mul_f32 v[114:115], v[114:115], v[154:155]
	v_add_f32_e32 v4, 1.0, v4
	v_rcp_f32_e32 v133, v4
	s_nop 0
	v_pk_mul_f32 v[132:133], v[150:151], v[132:133]
	s_nop 0
	v_pk_mul_f32 v[116:117], v[116:117], v[132:133]
	v_mov_b32_e32 v132, v208
	v_mov_b32_e32 v133, v209
	v_mov_b32_e32 v150, v210
	v_mov_b32_e32 v151, v211
	s_waitcnt vmcnt(0)
	v_lshlrev_b32_e32 v4, 16, v150
	v_mul_f32_e32 v4, 0xbfb8aa3b, v4
	v_exp_f32_e32 v154, v4
	v_lshlrev_b32_e32 v4, 16, v132
	v_mul_f32_e32 v4, 0xbfb8aa3b, v4
	v_exp_f32_e32 v4, v4
	s_nop 0
	v_add_f32_e32 v4, 1.0, v4
	v_rcp_f32_e32 v156, v4
	v_and_b32_e32 v4, 0xffff0000, v150
	v_mul_f32_e32 v4, 0xbfb8aa3b, v4
	v_exp_f32_e32 v155, v4
	v_and_b32_e32 v4, 0xffff0000, v132
	v_mul_f32_e32 v4, 0xbfb8aa3b, v4
	v_exp_f32_e32 v4, v4
	v_pk_add_f32 v[154:155], v[154:155], 1.0 op_sel_hi:[1,0]
	v_add_f32_e32 v4, 1.0, v4
	v_rcp_f32_e32 v157, v4
	v_lshlrev_b32_e32 v4, 16, v151
	v_mul_f32_e32 v4, 0xbfb8aa3b, v4
	v_exp_f32_e32 v150, v4
	v_lshlrev_b32_e32 v4, 16, v133
	v_mul_f32_e32 v4, 0xbfb8aa3b, v4
	v_exp_f32_e32 v4, v4
	v_pk_mul_f32 v[154:155], v[154:155], v[156:157]
	v_add_f32_e32 v4, 1.0, v4
	v_rcp_f32_e32 v132, v4
	v_and_b32_e32 v4, 0xffff0000, v151
	v_mul_f32_e32 v4, 0xbfb8aa3b, v4
	v_exp_f32_e32 v151, v4
	v_and_b32_e32 v4, 0xffff0000, v133
	v_mul_f32_e32 v4, 0xbfb8aa3b, v4
	v_exp_f32_e32 v4, v4
	v_pk_add_f32 v[150:151], v[150:151], 1.0 op_sel_hi:[1,0]
	v_pk_mul_f32 v[110:111], v[110:111], v[154:155]
	v_add_f32_e32 v4, 1.0, v4
	v_rcp_f32_e32 v133, v4
	s_nop 0
	v_pk_mul_f32 v[132:133], v[150:151], v[132:133]
	v_add_co_u32_e32 v150, vcc, s0, v130
	s_mov_b32 s0, 0x92000
	s_nop 0
	v_addc_co_u32_e32 v151, vcc, 0, v131, vcc
	v_pk_mul_f32 v[112:113], v[112:113], v[132:133]
	v_add_co_u32_e32 v132, vcc, s0, v130
	v_mov_b32_e32 v154, v212
	v_mov_b32_e32 v155, v213
	s_nop 0
	v_addc_co_u32_e32 v133, vcc, 0, v131, vcc
	v_mov_b32_e32 v156, v214
	v_mov_b32_e32 v157, v215
	s_waitcnt vmcnt(0)
; DEV float bflo(unsigned u) { return __uint_as_float(u << 16); }
; DEV float bfhi(unsigned u) { return __uint_as_float(u & 0xffff0000u); }
; DEV void gemm_phase(const GemmJob& J) {
;     ...
;         const u16* gp = J.gate + (long)(brow + wr * 64 + fr) * LDR + bcol + wc * 32 + fq * 4;
; #pragma unroll
;         for (int ai = 0; ai < 2; ++ai)
; #pragma unroll
;           for (int bj = 0; bj < 2; ++bj) {
; #pragma unroll
;             for (int m = 0; m < 4; ++m)
; #pragma unroll
;               for (int n = 0; n < 2; ++n) {
;                 const u16* g2 = gp + (long)(ai * HALF + m * 16) * LDR + bj * HALF + n * 16;
;                 const u32x2 ga = *(const u32x2*)(g2 + C_GA), gb = *(const u32x2*)(g2 + C_GB);
;                 f32x4 v = acc[ai][bj][m][n];
;                 v[0] *= (1.f + __expf(-bflo(gb.x))) * __builtin_amdgcn_rcpf(1.f + __expf(-bflo(ga.x)));
;                 v[1] *= (1.f + __expf(-bfhi(gb.x))) * __builtin_amdgcn_rcpf(1.f + __expf(-bfhi(ga.x)));
;                 v[2] *= (1.f + __expf(-bflo(gb.y))) * __builtin_amdgcn_rcpf(1.f + __expf(-bflo(ga.y)));
;                 v[3] *= (1.f + __expf(-bfhi(gb.y))) * __builtin_amdgcn_rcpf(1.f + __expf(-bfhi(ga.y)));
;                 acc[ai][bj][m][n] = v;
;               }
	v_lshlrev_b32_e32 v4, 16, v156
	v_mul_f32_e32 v4, 0xbfb8aa3b, v4
	v_exp_f32_e32 v158, v4
	v_lshlrev_b32_e32 v4, 16, v154
	v_mul_f32_e32 v4, 0xbfb8aa3b, v4
	v_exp_f32_e32 v4, v4
	s_nop 0
	v_add_f32_e32 v4, 1.0, v4
	v_rcp_f32_e32 v160, v4
	v_and_b32_e32 v4, 0xffff0000, v156
	v_mul_f32_e32 v4, 0xbfb8aa3b, v4
	v_exp_f32_e32 v159, v4
	v_and_b32_e32 v4, 0xffff0000, v154
	v_mul_f32_e32 v4, 0xbfb8aa3b, v4
	v_exp_f32_e32 v4, v4
	v_pk_add_f32 v[158:159], v[158:159], 1.0 op_sel_hi:[1,0]
	v_add_f32_e32 v4, 1.0, v4
	v_rcp_f32_e32 v161, v4
	v_lshlrev_b32_e32 v4, 16, v157
	v_mul_f32_e32 v4, 0xbfb8aa3b, v4
	v_exp_f32_e32 v156, v4
	v_lshlrev_b32_e32 v4, 16, v155
	v_mul_f32_e32 v4, 0xbfb8aa3b, v4
	v_exp_f32_e32 v4, v4
	v_pk_mul_f32 v[158:159], v[158:159], v[160:161]
	v_add_f32_e32 v4, 1.0, v4
	v_rcp_f32_e32 v154, v4
	v_and_b32_e32 v4, 0xffff0000, v157
	v_mul_f32_e32 v4, 0xbfb8aa3b, v4
	v_exp_f32_e32 v157, v4
	v_and_b32_e32 v4, 0xffff0000, v155
	v_mul_f32_e32 v4, 0xbfb8aa3b, v4
	v_exp_f32_e32 v4, v4
	v_pk_add_f32 v[156:157], v[156:157], 1.0 op_sel_hi:[1,0]
	v_pk_mul_f32 v[106:107], v[106:107], v[158:159]
	v_add_f32_e32 v4, 1.0, v4
	v_rcp_f32_e32 v155, v4
	s_nop 0
	v_pk_mul_f32 v[154:155], v[156:157], v[154:155]
	s_nop 0
	v_pk_mul_f32 v[108:109], v[108:109], v[154:155]
	v_mov_b32_e32 v154, v216
	v_mov_b32_e32 v155, v217
	v_mov_b32_e32 v158, v218
	v_mov_b32_e32 v159, v219
	s_waitcnt vmcnt(0)
	v_lshlrev_b32_e32 v4, 16, v158
	v_mul_f32_e32 v4, 0xbfb8aa3b, v4
	v_exp_f32_e32 v156, v4
	v_lshlrev_b32_e32 v4, 16, v154
	v_mul_f32_e32 v4, 0xbfb8aa3b, v4
	v_exp_f32_e32 v4, v4
	s_nop 0
	v_add_f32_e32 v4, 1.0, v4
	v_rcp_f32_e32 v160, v4
	v_and_b32_e32 v4, 0xffff0000, v158
	v_mul_f32_e32 v4, 0xbfb8aa3b, v4
	v_exp_f32_e32 v157, v4
	v_and_b32_e32 v4, 0xffff0000, v154
	v_mul_f32_e32 v4, 0xbfb8aa3b, v4
	v_exp_f32_e32 v4, v4
	v_pk_add_f32 v[156:157], v[156:157], 1.0 op_sel_hi:[1,0]
	v_add_f32_e32 v4, 1.0, v4
	v_rcp_f32_e32 v161, v4
	v_lshlrev_b32_e32 v4, 16, v159
	v_mul_f32_e32 v4, 0xbfb8aa3b, v4
	v_exp_f32_e32 v158, v4
	v_lshlrev_b32_e32 v4, 16, v155
	v_mul_f32_e32 v4, 0xbfb8aa3b, v4
	v_exp_f32_e32 v4, v4
	v_pk_mul_f32 v[156:157], v[156:157], v[160:161]
	v_add_f32_e32 v4, 1.0, v4
	v_rcp_f32_e32 v154, v4
	v_and_b32_e32 v4, 0xffff0000, v159
	v_mul_f32_e32 v4, 0xbfb8aa3b, v4
	v_exp_f32_e32 v159, v4
	v_and_b32_e32 v4, 0xffff0000, v155
	v_mul_f32_e32 v4, 0xbfb8aa3b, v4
	v_exp_f32_e32 v4, v4
	v_pk_add_f32 v[158:159], v[158:159], 1.0 op_sel_hi:[1,0]
	v_pk_mul_f32 v[102:103], v[102:103], v[156:157]
	v_add_f32_e32 v4, 1.0, v4
	v_rcp_f32_e32 v155, v4
	s_nop 0
	v_pk_mul_f32 v[154:155], v[158:159], v[154:155]
	s_nop 0
	v_pk_mul_f32 v[104:105], v[104:105], v[154:155]
	v_mov_b32_e32 v154, v220
	v_mov_b32_e32 v155, v221
	v_mov_b32_e32 v156, v222
	v_mov_b32_e32 v157, v223
	s_nop 0
	v_mov_b32_e32 v148, v224
	v_mov_b32_e32 v149, v225
	s_nop 0
	v_mov_b32_e32 v136, v226
	v_mov_b32_e32 v137, v227
	s_waitcnt vmcnt(2)
	v_lshlrev_b32_e32 v4, 16, v156
	v_mul_f32_e32 v4, 0xbfb8aa3b, v4
	v_exp_f32_e32 v158, v4
	v_lshlrev_b32_e32 v4, 16, v154
	v_mul_f32_e32 v4, 0xbfb8aa3b, v4
	v_exp_f32_e32 v4, v4
	s_nop 0
	v_add_f32_e32 v4, 1.0, v4
	v_rcp_f32_e32 v160, v4
	v_and_b32_e32 v4, 0xffff0000, v156
	v_mul_f32_e32 v4, 0xbfb8aa3b, v4
	v_exp_f32_e32 v159, v4
	v_and_b32_e32 v4, 0xffff0000, v154
	v_mul_f32_e32 v4, 0xbfb8aa3b, v4
	v_exp_f32_e32 v4, v4
	v_pk_add_f32 v[158:159], v[158:159], 1.0 op_sel_hi:[1,0]
	v_add_f32_e32 v4, 1.0, v4
	v_rcp_f32_e32 v161, v4
	v_lshlrev_b32_e32 v4, 16, v157
	v_mul_f32_e32 v4, 0xbfb8aa3b, v4
	v_exp_f32_e32 v156, v4
	v_lshlrev_b32_e32 v4, 16, v155
	v_mul_f32_e32 v4, 0xbfb8aa3b, v4
	v_exp_f32_e32 v4, v4
	v_pk_mul_f32 v[158:159], v[158:159], v[160:161]
	v_add_f32_e32 v4, 1.0, v4
	v_rcp_f32_e32 v154, v4
	v_and_b32_e32 v4, 0xffff0000, v157
	v_mul_f32_e32 v4, 0xbfb8aa3b, v4
	v_exp_f32_e32 v157, v4
	v_and_b32_e32 v4, 0xffff0000, v155
	v_mul_f32_e32 v4, 0xbfb8aa3b, v4
	v_exp_f32_e32 v4, v4
	v_pk_add_f32 v[156:157], v[156:157], 1.0 op_sel_hi:[1,0]
	v_pk_mul_f32 v[98:99], v[98:99], v[158:159]
	v_add_f32_e32 v4, 1.0, v4
	v_rcp_f32_e32 v155, v4
	s_waitcnt vmcnt(0)
	v_lshlrev_b32_e32 v4, 16, v136
	v_mul_f32_e32 v4, 0xbfb8aa3b, v4
	v_pk_mul_f32 v[154:155], v[156:157], v[154:155]
	s_nop 0
	v_pk_mul_f32 v[100:101], v[100:101], v[154:155]
	v_exp_f32_e32 v154, v4
	v_lshlrev_b32_e32 v4, 16, v148
	v_mul_f32_e32 v4, 0xbfb8aa3b, v4
	v_exp_f32_e32 v4, v4
	s_nop 0
	v_add_f32_e32 v4, 1.0, v4
	v_rcp_f32_e32 v156, v4
	v_and_b32_e32 v4, 0xffff0000, v136
	v_mul_f32_e32 v4, 0xbfb8aa3b, v4
	v_exp_f32_e32 v155, v4
	v_and_b32_e32 v4, 0xffff0000, v148
	v_mul_f32_e32 v4, 0xbfb8aa3b, v4
	v_exp_f32_e32 v4, v4
	v_pk_add_f32 v[154:155], v[154:155], 1.0 op_sel_hi:[1,0]
	v_add_f32_e32 v4, 1.0, v4
	v_rcp_f32_e32 v157, v4
	v_lshlrev_b32_e32 v4, 16, v137
	v_mul_f32_e32 v4, 0xbfb8aa3b, v4
	v_exp_f32_e32 v136, v4
	v_lshlrev_b32_e32 v4, 16, v149
	v_mul_f32_e32 v4, 0xbfb8aa3b, v4
	v_exp_f32_e32 v4, v4
	v_pk_mul_f32 v[154:155], v[154:155], v[156:157]
	v_add_f32_e32 v4, 1.0, v4
	v_rcp_f32_e32 v148, v4
	v_and_b32_e32 v4, 0xffff0000, v137
	v_mul_f32_e32 v4, 0xbfb8aa3b, v4
	v_exp_f32_e32 v137, v4
	v_and_b32_e32 v4, 0xffff0000, v149
	v_mul_f32_e32 v4, 0xbfb8aa3b, v4
	v_exp_f32_e32 v4, v4
	v_pk_add_f32 v[136:137], v[136:137], 1.0 op_sel_hi:[1,0]
	v_pk_mul_f32 v[94:95], v[94:95], v[154:155]
	v_add_f32_e32 v4, 1.0, v4
	v_rcp_f32_e32 v149, v4
	s_nop 0
	v_pk_mul_f32 v[136:137], v[136:137], v[148:149]
	s_nop 0
	v_pk_mul_f32 v[96:97], v[96:97], v[136:137]
	v_mov_b32_e32 v136, v228
	v_mov_b32_e32 v137, v229
	v_mov_b32_e32 v148, v230
	v_mov_b32_e32 v149, v231
	s_waitcnt vmcnt(0)
; DEV float bflo(unsigned u) { return __uint_as_float(u << 16); }
; DEV float bfhi(unsigned u) { return __uint_as_float(u & 0xffff0000u); }
; DEV void gemm_phase(const GemmJob& J) {
;     ...
;         const u16* gp = J.gate + (long)(brow + wr * 64 + fr) * LDR + bcol + wc * 32 + fq * 4;
; #pragma unroll
;         for (int ai = 0; ai < 2; ++ai)
; #pragma unroll
;           for (int bj = 0; bj < 2; ++bj) {
; #pragma unroll
;             for (int m = 0; m < 4; ++m)
; #pragma unroll
;               for (int n = 0; n < 2; ++n) {
;                 const u16* g2 = gp + (long)(ai * HALF + m * 16) * LDR + bj * HALF + n * 16;
;                 const u32x2 ga = *(const u32x2*)(g2 + C_GA), gb = *(const u32x2*)(g2 + C_GB);
;                 f32x4 v = acc[ai][bj][m][n];
;                 v[0] *= (1.f + __expf(-bflo(gb.x))) * __builtin_amdgcn_rcpf(1.f + __expf(-bflo(ga.x)));
;                 v[1] *= (1.f + __expf(-bfhi(gb.x))) * __builtin_amdgcn_rcpf(1.f + __expf(-bfhi(ga.x)));
;                 v[2] *= (1.f + __expf(-bflo(gb.y))) * __builtin_amdgcn_rcpf(1.f + __expf(-bflo(ga.y)));
;                 v[3] *= (1.f + __expf(-bfhi(gb.y))) * __builtin_amdgcn_rcpf(1.f + __expf(-bfhi(ga.y)));
;                 acc[ai][bj][m][n] = v;
;               }
	v_lshlrev_b32_e32 v4, 16, v148
	v_mul_f32_e32 v4, 0xbfb8aa3b, v4
	v_exp_f32_e32 v154, v4
	v_lshlrev_b32_e32 v4, 16, v136
	v_mul_f32_e32 v4, 0xbfb8aa3b, v4
	v_exp_f32_e32 v4, v4
	s_nop 0
	v_add_f32_e32 v4, 1.0, v4
	v_rcp_f32_e32 v156, v4
	v_and_b32_e32 v4, 0xffff0000, v148
	v_mul_f32_e32 v4, 0xbfb8aa3b, v4
	v_exp_f32_e32 v155, v4
	v_and_b32_e32 v4, 0xffff0000, v136
	v_mul_f32_e32 v4, 0xbfb8aa3b, v4
	v_exp_f32_e32 v4, v4
	v_pk_add_f32 v[154:155], v[154:155], 1.0 op_sel_hi:[1,0]
	v_add_f32_e32 v4, 1.0, v4
	v_rcp_f32_e32 v157, v4
	v_lshlrev_b32_e32 v4, 16, v149
	v_mul_f32_e32 v4, 0xbfb8aa3b, v4
	v_exp_f32_e32 v148, v4
	v_lshlrev_b32_e32 v4, 16, v137
	v_mul_f32_e32 v4, 0xbfb8aa3b, v4
	v_exp_f32_e32 v4, v4
	v_pk_mul_f32 v[154:155], v[154:155], v[156:157]
	v_add_f32_e32 v4, 1.0, v4
	v_rcp_f32_e32 v136, v4
	v_and_b32_e32 v4, 0xffff0000, v149
	v_mul_f32_e32 v4, 0xbfb8aa3b, v4
	v_exp_f32_e32 v149, v4
	v_and_b32_e32 v4, 0xffff0000, v137
	v_mul_f32_e32 v4, 0xbfb8aa3b, v4
	v_exp_f32_e32 v4, v4
	v_pk_add_f32 v[148:149], v[148:149], 1.0 op_sel_hi:[1,0]
	v_pk_mul_f32 v[90:91], v[90:91], v[154:155]
	v_add_f32_e32 v4, 1.0, v4
	v_rcp_f32_e32 v137, v4
	s_nop 0
	v_pk_mul_f32 v[136:137], v[148:149], v[136:137]
	s_nop 0
	v_pk_mul_f32 v[92:93], v[92:93], v[136:137]
	v_mov_b32_e32 v136, v232
	v_mov_b32_e32 v137, v233
	s_nop 0
	v_mov_b32_e32 v138, v234
	v_mov_b32_e32 v139, v235
	s_waitcnt vmcnt(0)
	v_lshlrev_b32_e32 v4, 16, v138
	v_mul_f32_e32 v4, 0xbfb8aa3b, v4
	v_exp_f32_e32 v140, v4
	v_lshlrev_b32_e32 v4, 16, v136
	v_mul_f32_e32 v4, 0xbfb8aa3b, v4
	v_exp_f32_e32 v4, v4
	s_nop 0
	v_add_f32_e32 v4, 1.0, v4
	v_rcp_f32_e32 v148, v4
	v_and_b32_e32 v4, 0xffff0000, v138
	v_mul_f32_e32 v4, 0xbfb8aa3b, v4
	v_exp_f32_e32 v141, v4
	v_and_b32_e32 v4, 0xffff0000, v136
	v_mul_f32_e32 v4, 0xbfb8aa3b, v4
	v_exp_f32_e32 v4, v4
	v_pk_add_f32 v[140:141], v[140:141], 1.0 op_sel_hi:[1,0]
	v_add_f32_e32 v4, 1.0, v4
	v_rcp_f32_e32 v149, v4
	v_lshlrev_b32_e32 v4, 16, v139
	v_mul_f32_e32 v4, 0xbfb8aa3b, v4
	v_exp_f32_e32 v138, v4
	v_lshlrev_b32_e32 v4, 16, v137
	v_mul_f32_e32 v4, 0xbfb8aa3b, v4
	v_exp_f32_e32 v4, v4
	v_pk_mul_f32 v[140:141], v[140:141], v[148:149]
	v_add_f32_e32 v4, 1.0, v4
	v_rcp_f32_e32 v136, v4
	v_and_b32_e32 v4, 0xffff0000, v139
	v_mul_f32_e32 v4, 0xbfb8aa3b, v4
	v_exp_f32_e32 v139, v4
	v_and_b32_e32 v4, 0xffff0000, v137
	v_mul_f32_e32 v4, 0xbfb8aa3b, v4
	v_exp_f32_e32 v4, v4
	v_pk_add_f32 v[138:139], v[138:139], 1.0 op_sel_hi:[1,0]
	v_pk_mul_f32 v[86:87], v[86:87], v[140:141]
	v_add_f32_e32 v4, 1.0, v4
	v_rcp_f32_e32 v137, v4
	s_nop 0
	v_pk_mul_f32 v[136:137], v[138:139], v[136:137]
	s_nop 0
	v_pk_mul_f32 v[88:89], v[88:89], v[136:137]
	v_mov_b32_e32 v136, v236
	v_mov_b32_e32 v137, v237
	v_mov_b32_e32 v138, v238
	v_mov_b32_e32 v139, v239
	s_waitcnt vmcnt(0)
	v_lshlrev_b32_e32 v4, 16, v138
	v_mul_f32_e32 v4, 0xbfb8aa3b, v4
	v_exp_f32_e32 v140, v4
	v_lshlrev_b32_e32 v4, 16, v136
	v_mul_f32_e32 v4, 0xbfb8aa3b, v4
	v_exp_f32_e32 v4, v4
	s_nop 0
	v_add_f32_e32 v4, 1.0, v4
	v_rcp_f32_e32 v148, v4
	v_and_b32_e32 v4, 0xffff0000, v138
	v_mul_f32_e32 v4, 0xbfb8aa3b, v4
	v_exp_f32_e32 v141, v4
	v_and_b32_e32 v4, 0xffff0000, v136
	v_mul_f32_e32 v4, 0xbfb8aa3b, v4
	v_exp_f32_e32 v4, v4
	v_pk_add_f32 v[140:141], v[140:141], 1.0 op_sel_hi:[1,0]
	v_add_f32_e32 v4, 1.0, v4
	v_rcp_f32_e32 v149, v4
	v_lshlrev_b32_e32 v4, 16, v139
	v_mul_f32_e32 v4, 0xbfb8aa3b, v4
	v_exp_f32_e32 v138, v4
	v_lshlrev_b32_e32 v4, 16, v137
	v_mul_f32_e32 v4, 0xbfb8aa3b, v4
	v_exp_f32_e32 v4, v4
	v_pk_mul_f32 v[140:141], v[140:141], v[148:149]
	v_add_f32_e32 v4, 1.0, v4
	v_rcp_f32_e32 v136, v4
	v_and_b32_e32 v4, 0xffff0000, v139
	v_mul_f32_e32 v4, 0xbfb8aa3b, v4
	v_exp_f32_e32 v139, v4
	v_and_b32_e32 v4, 0xffff0000, v137
	v_mul_f32_e32 v4, 0xbfb8aa3b, v4
	v_exp_f32_e32 v4, v4
	v_pk_add_f32 v[138:139], v[138:139], 1.0 op_sel_hi:[1,0]
	v_pk_mul_f32 v[82:83], v[82:83], v[140:141]
	v_add_f32_e32 v4, 1.0, v4
	v_rcp_f32_e32 v137, v4
	s_nop 0
	v_pk_mul_f32 v[136:137], v[138:139], v[136:137]
	s_nop 0
	v_pk_mul_f32 v[84:85], v[84:85], v[136:137]
	v_mov_b32_e32 v136, v240
	v_mov_b32_e32 v137, v241
	s_nop 0
	v_mov_b32_e32 v134, v242
	v_mov_b32_e32 v135, v243
	s_waitcnt vmcnt(0)
	v_lshlrev_b32_e32 v4, 16, v134
	v_mul_f32_e32 v4, 0xbfb8aa3b, v4
	v_exp_f32_e32 v138, v4
	v_lshlrev_b32_e32 v4, 16, v136
	v_mul_f32_e32 v4, 0xbfb8aa3b, v4
	v_exp_f32_e32 v4, v4
	s_nop 0
	v_add_f32_e32 v4, 1.0, v4
	v_rcp_f32_e32 v140, v4
	v_and_b32_e32 v4, 0xffff0000, v134
	v_mul_f32_e32 v4, 0xbfb8aa3b, v4
	v_exp_f32_e32 v139, v4
	v_and_b32_e32 v4, 0xffff0000, v136
	v_mul_f32_e32 v4, 0xbfb8aa3b, v4
	v_exp_f32_e32 v4, v4
	v_pk_add_f32 v[138:139], v[138:139], 1.0 op_sel_hi:[1,0]
	v_add_f32_e32 v4, 1.0, v4
	v_rcp_f32_e32 v141, v4
	v_lshlrev_b32_e32 v4, 16, v135
	v_mul_f32_e32 v4, 0xbfb8aa3b, v4
	v_exp_f32_e32 v134, v4
	v_lshlrev_b32_e32 v4, 16, v137
	v_mul_f32_e32 v4, 0xbfb8aa3b, v4
	v_exp_f32_e32 v4, v4
	v_pk_mul_f32 v[138:139], v[138:139], v[140:141]
	v_add_f32_e32 v4, 1.0, v4
	v_rcp_f32_e32 v136, v4
	v_and_b32_e32 v4, 0xffff0000, v135
	v_mul_f32_e32 v4, 0xbfb8aa3b, v4
	v_exp_f32_e32 v135, v4
	v_and_b32_e32 v4, 0xffff0000, v137
	v_mul_f32_e32 v4, 0xbfb8aa3b, v4
	v_exp_f32_e32 v4, v4
	v_pk_add_f32 v[134:135], v[134:135], 1.0 op_sel_hi:[1,0]
	v_pk_mul_f32 v[78:79], v[78:79], v[138:139]
	v_add_f32_e32 v4, 1.0, v4
	v_rcp_f32_e32 v137, v4
	s_nop 0
	v_pk_mul_f32 v[134:135], v[134:135], v[136:137]
	s_nop 0
	v_pk_mul_f32 v[80:81], v[80:81], v[134:135]
	v_mov_b32_e32 v134, v244
	v_mov_b32_e32 v135, v245
	v_mov_b32_e32 v136, v246
	v_mov_b32_e32 v137, v247
	s_waitcnt vmcnt(0)
; DEV float bflo(unsigned u) { return __uint_as_float(u << 16); }
; DEV float bfhi(unsigned u) { return __uint_as_float(u & 0xffff0000u); }
; DEV void gemm_phase(const GemmJob& J) {
;     ...
;         const u16* gp = J.gate + (long)(brow + wr * 64 + fr) * LDR + bcol + wc * 32 + fq * 4;
; #pragma unroll
;         for (int ai = 0; ai < 2; ++ai)
; #pragma unroll
;           for (int bj = 0; bj < 2; ++bj) {
; #pragma unroll
;             for (int m = 0; m < 4; ++m)
; #pragma unroll
;               for (int n = 0; n < 2; ++n) {
;                 const u16* g2 = gp + (long)(ai * HALF + m * 16) * LDR + bj * HALF + n * 16;
;                 const u32x2 ga = *(const u32x2*)(g2 + C_GA), gb = *(const u32x2*)(g2 + C_GB);
;                 f32x4 v = acc[ai][bj][m][n];
;                 v[0] *= (1.f + __expf(-bflo(gb.x))) * __builtin_amdgcn_rcpf(1.f + __expf(-bflo(ga.x)));
;                 v[1] *= (1.f + __expf(-bfhi(gb.x))) * __builtin_amdgcn_rcpf(1.f + __expf(-bfhi(ga.x)));
;                 v[2] *= (1.f + __expf(-bflo(gb.y))) * __builtin_amdgcn_rcpf(1.f + __expf(-bflo(ga.y)));
;                 v[3] *= (1.f + __expf(-bfhi(gb.y))) * __builtin_amdgcn_rcpf(1.f + __expf(-bfhi(ga.y)));
;                 acc[ai][bj][m][n] = v;
;               }
	v_lshlrev_b32_e32 v4, 16, v136
	v_mul_f32_e32 v4, 0xbfb8aa3b, v4
	v_exp_f32_e32 v138, v4
	v_lshlrev_b32_e32 v4, 16, v134
	v_mul_f32_e32 v4, 0xbfb8aa3b, v4
	v_exp_f32_e32 v4, v4
	s_nop 0
	v_add_f32_e32 v4, 1.0, v4
	v_rcp_f32_e32 v140, v4
	v_and_b32_e32 v4, 0xffff0000, v136
	v_mul_f32_e32 v4, 0xbfb8aa3b, v4
	v_exp_f32_e32 v139, v4
	v_and_b32_e32 v4, 0xffff0000, v134
	v_mul_f32_e32 v4, 0xbfb8aa3b, v4
	v_exp_f32_e32 v4, v4
	v_pk_add_f32 v[138:139], v[138:139], 1.0 op_sel_hi:[1,0]
	v_add_f32_e32 v4, 1.0, v4
	v_rcp_f32_e32 v141, v4
	v_lshlrev_b32_e32 v4, 16, v137
	v_mul_f32_e32 v4, 0xbfb8aa3b, v4
	v_exp_f32_e32 v136, v4
	v_lshlrev_b32_e32 v4, 16, v135
	v_mul_f32_e32 v4, 0xbfb8aa3b, v4
	v_exp_f32_e32 v4, v4
	v_pk_mul_f32 v[138:139], v[138:139], v[140:141]
	v_add_f32_e32 v4, 1.0, v4
	v_rcp_f32_e32 v134, v4
	v_and_b32_e32 v4, 0xffff0000, v137
	v_mul_f32_e32 v4, 0xbfb8aa3b, v4
	v_exp_f32_e32 v137, v4
	v_and_b32_e32 v4, 0xffff0000, v135
	v_mul_f32_e32 v4, 0xbfb8aa3b, v4
	v_exp_f32_e32 v4, v4
	v_pk_add_f32 v[136:137], v[136:137], 1.0 op_sel_hi:[1,0]
	v_pk_mul_f32 v[74:75], v[74:75], v[138:139]
	v_add_f32_e32 v4, 1.0, v4
	v_rcp_f32_e32 v135, v4
	s_nop 0
	v_pk_mul_f32 v[134:135], v[136:137], v[134:135]
	s_nop 0
	v_pk_mul_f32 v[76:77], v[76:77], v[134:135]
	v_mov_b32_e32 v134, v248
	v_mov_b32_e32 v135, v249
	v_mov_b32_e32 v136, v250
	v_mov_b32_e32 v137, v251
	s_waitcnt vmcnt(0)
	v_lshlrev_b32_e32 v4, 16, v136
	v_mul_f32_e32 v4, 0xbfb8aa3b, v4
	v_exp_f32_e32 v132, v4
	v_lshlrev_b32_e32 v4, 16, v134
	v_mul_f32_e32 v4, 0xbfb8aa3b, v4
	v_exp_f32_e32 v4, v4
	s_nop 0
	v_add_f32_e32 v4, 1.0, v4
	v_rcp_f32_e32 v138, v4
	v_and_b32_e32 v4, 0xffff0000, v136
	v_mul_f32_e32 v4, 0xbfb8aa3b, v4
	v_exp_f32_e32 v133, v4
	v_and_b32_e32 v4, 0xffff0000, v134
	v_mul_f32_e32 v4, 0xbfb8aa3b, v4
	v_exp_f32_e32 v4, v4
	v_pk_add_f32 v[132:133], v[132:133], 1.0 op_sel_hi:[1,0]
	v_add_f32_e32 v4, 1.0, v4
	v_rcp_f32_e32 v139, v4
	v_lshlrev_b32_e32 v4, 16, v137
	v_mul_f32_e32 v4, 0xbfb8aa3b, v4
	v_exp_f32_e32 v136, v4
	v_lshlrev_b32_e32 v4, 16, v135
	v_mul_f32_e32 v4, 0xbfb8aa3b, v4
	v_exp_f32_e32 v4, v4
	v_pk_mul_f32 v[132:133], v[132:133], v[138:139]
	v_add_f32_e32 v4, 1.0, v4
	v_rcp_f32_e32 v134, v4
	v_and_b32_e32 v4, 0xffff0000, v137
	v_mul_f32_e32 v4, 0xbfb8aa3b, v4
	v_exp_f32_e32 v137, v4
	v_and_b32_e32 v4, 0xffff0000, v135
	v_mul_f32_e32 v4, 0xbfb8aa3b, v4
	v_exp_f32_e32 v4, v4
	v_pk_add_f32 v[136:137], v[136:137], 1.0 op_sel_hi:[1,0]
	v_pk_mul_f32 v[70:71], v[70:71], v[132:133]
	v_add_f32_e32 v4, 1.0, v4
	v_rcp_f32_e32 v135, v4
	s_nop 0
	v_pk_mul_f32 v[134:135], v[136:137], v[134:135]
	s_nop 0
	v_pk_mul_f32 v[72:73], v[72:73], v[134:135]
	s_mov_b32 s0, 0x181000
	v_add_co_u32_e32 v140, vcc, s0, v130
	s_mov_b32 s0, 0x182000
	s_nop 0
	v_addc_co_u32_e32 v141, vcc, 0, v131, vcc
	v_add_co_u32_e32 v134, vcc, s0, v130
	v_add_co_u32_e32 v132, vcc, 0x182000, v130
	s_nop 1
	v_addc_co_u32_e32 v133, vcc, 0, v131, vcc
	global_load_dwordx2 v[162:163], v[132:133], off offset:-2048
	global_load_dwordx2 v[164:165], v[132:133], off
	global_load_dwordx2 v[166:167], v[132:133], off offset:-2016
	global_load_dwordx2 v[168:169], v[132:133], off offset:32
	global_load_dwordx2 v[220:221], v[132:133], off offset:-1792
	global_load_dwordx2 v[222:223], v[132:133], off offset:256
	global_load_dwordx2 v[224:225], v[132:133], off offset:-1760
	global_load_dwordx2 v[226:227], v[132:133], off offset:288
	v_add_co_u32_e32 v132, vcc, 0x30000, v132
	s_nop 1
	v_addc_co_u32_e32 v133, vcc, 0, v133, vcc
	global_load_dwordx2 v[170:171], v[132:133], off offset:-2048
	global_load_dwordx2 v[172:173], v[132:133], off
	global_load_dwordx2 v[174:175], v[132:133], off offset:-2016
	global_load_dwordx2 v[176:177], v[132:133], off offset:32
	global_load_dwordx2 v[228:229], v[132:133], off offset:-1792
	global_load_dwordx2 v[230:231], v[132:133], off offset:256
	global_load_dwordx2 v[232:233], v[132:133], off offset:-1760
	global_load_dwordx2 v[234:235], v[132:133], off offset:288
	v_add_co_u32_e32 v132, vcc, 0x30000, v132
	s_nop 1
	v_addc_co_u32_e32 v133, vcc, 0, v133, vcc
	global_load_dwordx2 v[204:205], v[132:133], off offset:-2048
	global_load_dwordx2 v[206:207], v[132:133], off
	global_load_dwordx2 v[208:209], v[132:133], off offset:-2016
	global_load_dwordx2 v[210:211], v[132:133], off offset:32
	global_load_dwordx2 v[236:237], v[132:133], off offset:-1792
	global_load_dwordx2 v[238:239], v[132:133], off offset:256
	global_load_dwordx2 v[240:241], v[132:133], off offset:-1760
	global_load_dwordx2 v[242:243], v[132:133], off offset:288
	v_add_co_u32_e32 v132, vcc, 0x30000, v132
	s_nop 1
	v_addc_co_u32_e32 v133, vcc, 0, v133, vcc
	global_load_dwordx2 v[212:213], v[132:133], off offset:-2048
	global_load_dwordx2 v[214:215], v[132:133], off
	global_load_dwordx2 v[216:217], v[132:133], off offset:-2016
	global_load_dwordx2 v[218:219], v[132:133], off offset:32
	global_load_dwordx2 v[244:245], v[132:133], off offset:-1792
	global_load_dwordx2 v[246:247], v[132:133], off offset:256
	global_load_dwordx2 v[248:249], v[132:133], off offset:-1760
	global_load_dwordx2 v[250:251], v[132:133], off offset:288
	s_waitcnt vmcnt(0)
	v_mov_b32_e32 v132, v162
	v_mov_b32_e32 v133, v163
	s_nop 0
	v_addc_co_u32_e32 v135, vcc, 0, v131, vcc
	v_mov_b32_e32 v136, v164
	v_mov_b32_e32 v137, v165
	s_mov_b32 s0, 0x1b1000
	s_waitcnt vmcnt(0)
; DEV float bflo(unsigned u) { return __uint_as_float(u << 16); }
; DEV float bfhi(unsigned u) { return __uint_as_float(u & 0xffff0000u); }
; DEV void gemm_phase(const GemmJob& J) {
;     ...
;         const u16* gp = J.gate + (long)(brow + wr * 64 + fr) * LDR + bcol + wc * 32 + fq * 4;
; #pragma unroll
;         for (int ai = 0; ai < 2; ++ai)
; #pragma unroll
;           for (int bj = 0; bj < 2; ++bj) {
; #pragma unroll
;             for (int m = 0; m < 4; ++m)
; #pragma unroll
;               for (int n = 0; n < 2; ++n) {
;                 const u16* g2 = gp + (long)(ai * HALF + m * 16) * LDR + bj * HALF + n * 16;
;                 const u32x2 ga = *(const u32x2*)(g2 + C_GA), gb = *(const u32x2*)(g2 + C_GB);
;                 f32x4 v = acc[ai][bj][m][n];
;                 v[0] *= (1.f + __expf(-bflo(gb.x))) * __builtin_amdgcn_rcpf(1.f + __expf(-bflo(ga.x)));
;                 v[1] *= (1.f + __expf(-bfhi(gb.x))) * __builtin_amdgcn_rcpf(1.f + __expf(-bfhi(ga.x)));
;                 v[2] *= (1.f + __expf(-bflo(gb.y))) * __builtin_amdgcn_rcpf(1.f + __expf(-bflo(ga.y)));
;                 v[3] *= (1.f + __expf(-bfhi(gb.y))) * __builtin_amdgcn_rcpf(1.f + __expf(-bfhi(ga.y)));
;                 acc[ai][bj][m][n] = v;
;               }
	v_lshlrev_b32_e32 v4, 16, v136
	v_mul_f32_e32 v4, 0xbfb8aa3b, v4
	v_exp_f32_e32 v138, v4
	v_lshlrev_b32_e32 v4, 16, v132
	v_mul_f32_e32 v4, 0xbfb8aa3b, v4
	v_exp_f32_e32 v4, v4
	s_nop 0
	v_add_f32_e32 v4, 1.0, v4
	v_rcp_f32_e32 v148, v4
	v_and_b32_e32 v4, 0xffff0000, v136
	v_mul_f32_e32 v4, 0xbfb8aa3b, v4
	v_exp_f32_e32 v139, v4
	v_and_b32_e32 v4, 0xffff0000, v132
	v_mul_f32_e32 v4, 0xbfb8aa3b, v4
	v_exp_f32_e32 v4, v4
	v_pk_add_f32 v[138:139], v[138:139], 1.0 op_sel_hi:[1,0]
	v_add_f32_e32 v4, 1.0, v4
	v_rcp_f32_e32 v149, v4
	v_lshlrev_b32_e32 v4, 16, v137
	v_mul_f32_e32 v4, 0xbfb8aa3b, v4
	v_exp_f32_e32 v136, v4
	v_lshlrev_b32_e32 v4, 16, v133
	v_mul_f32_e32 v4, 0xbfb8aa3b, v4
	v_exp_f32_e32 v4, v4
	v_pk_mul_f32 v[138:139], v[138:139], v[148:149]
	v_add_f32_e32 v4, 1.0, v4
	v_rcp_f32_e32 v132, v4
	v_and_b32_e32 v4, 0xffff0000, v137
	v_mul_f32_e32 v4, 0xbfb8aa3b, v4
	v_exp_f32_e32 v137, v4
	v_and_b32_e32 v4, 0xffff0000, v133
	v_mul_f32_e32 v4, 0xbfb8aa3b, v4
	v_exp_f32_e32 v4, v4
	v_pk_add_f32 v[136:137], v[136:137], 1.0 op_sel_hi:[1,0]
	v_pk_mul_f32 v[66:67], v[66:67], v[138:139]
	v_add_f32_e32 v4, 1.0, v4
	v_rcp_f32_e32 v133, v4
	s_nop 0
	v_pk_mul_f32 v[132:133], v[136:137], v[132:133]
	s_nop 0
	v_pk_mul_f32 v[68:69], v[68:69], v[132:133]
	v_mov_b32_e32 v132, v166
	v_mov_b32_e32 v133, v167
	v_mov_b32_e32 v136, v168
	v_mov_b32_e32 v137, v169
	s_waitcnt vmcnt(0)
	v_lshlrev_b32_e32 v4, 16, v136
	v_mul_f32_e32 v4, 0xbfb8aa3b, v4
	v_exp_f32_e32 v138, v4
	v_lshlrev_b32_e32 v4, 16, v132
	v_mul_f32_e32 v4, 0xbfb8aa3b, v4
	v_exp_f32_e32 v4, v4
	s_nop 0
	v_add_f32_e32 v4, 1.0, v4
	v_rcp_f32_e32 v148, v4
	v_and_b32_e32 v4, 0xffff0000, v136
	v_mul_f32_e32 v4, 0xbfb8aa3b, v4
	v_exp_f32_e32 v139, v4
	v_and_b32_e32 v4, 0xffff0000, v132
	v_mul_f32_e32 v4, 0xbfb8aa3b, v4
	v_exp_f32_e32 v4, v4
	v_pk_add_f32 v[138:139], v[138:139], 1.0 op_sel_hi:[1,0]
	v_add_f32_e32 v4, 1.0, v4
	v_rcp_f32_e32 v149, v4
	v_lshlrev_b32_e32 v4, 16, v137
	v_mul_f32_e32 v4, 0xbfb8aa3b, v4
	v_exp_f32_e32 v136, v4
	v_lshlrev_b32_e32 v4, 16, v133
	v_mul_f32_e32 v4, 0xbfb8aa3b, v4
	v_exp_f32_e32 v4, v4
	v_pk_mul_f32 v[138:139], v[138:139], v[148:149]
	v_add_f32_e32 v4, 1.0, v4
	v_rcp_f32_e32 v132, v4
	v_and_b32_e32 v4, 0xffff0000, v137
	v_mul_f32_e32 v4, 0xbfb8aa3b, v4
	v_exp_f32_e32 v137, v4
	v_and_b32_e32 v4, 0xffff0000, v133
	v_mul_f32_e32 v4, 0xbfb8aa3b, v4
	v_exp_f32_e32 v4, v4
	v_pk_mul_f32 v[62:63], v[62:63], v[138:139]
	v_add_co_u32_e32 v138, vcc, s0, v130
	v_add_f32_e32 v4, 1.0, v4
	v_rcp_f32_e32 v133, v4
	v_pk_add_f32 v[136:137], v[136:137], 1.0 op_sel_hi:[1,0]
	v_addc_co_u32_e32 v139, vcc, 0, v131, vcc
	s_mov_b32 s0, 0x1b2000
	v_pk_mul_f32 v[132:133], v[136:137], v[132:133]
	v_add_co_u32_e32 v136, vcc, s0, v130
	v_pk_mul_f32 v[64:65], v[64:65], v[132:133]
	s_nop 0
	v_addc_co_u32_e32 v137, vcc, 0, v131, vcc
	v_mov_b32_e32 v132, v170
	v_mov_b32_e32 v133, v171
	v_mov_b32_e32 v148, v172
	v_mov_b32_e32 v149, v173
	s_mov_b32 s0, 0x1e1000
	s_waitcnt vmcnt(0)
	v_lshlrev_b32_e32 v4, 16, v148
	v_mul_f32_e32 v4, 0xbfb8aa3b, v4
	v_exp_f32_e32 v150, v4
	v_lshlrev_b32_e32 v4, 16, v132
	v_mul_f32_e32 v4, 0xbfb8aa3b, v4
	v_exp_f32_e32 v4, v4
	s_nop 0
	v_add_f32_e32 v4, 1.0, v4
	v_rcp_f32_e32 v152, v4
	v_and_b32_e32 v4, 0xffff0000, v148
	v_mul_f32_e32 v4, 0xbfb8aa3b, v4
	v_exp_f32_e32 v151, v4
	v_and_b32_e32 v4, 0xffff0000, v132
	v_mul_f32_e32 v4, 0xbfb8aa3b, v4
	v_exp_f32_e32 v4, v4
	v_pk_add_f32 v[150:151], v[150:151], 1.0 op_sel_hi:[1,0]
	v_add_f32_e32 v4, 1.0, v4
	v_rcp_f32_e32 v153, v4
	v_lshlrev_b32_e32 v4, 16, v149
	v_mul_f32_e32 v4, 0xbfb8aa3b, v4
	v_exp_f32_e32 v148, v4
	v_lshlrev_b32_e32 v4, 16, v133
	v_mul_f32_e32 v4, 0xbfb8aa3b, v4
	v_exp_f32_e32 v4, v4
	v_pk_mul_f32 v[150:151], v[150:151], v[152:153]
	v_add_f32_e32 v4, 1.0, v4
	v_rcp_f32_e32 v132, v4
	v_and_b32_e32 v4, 0xffff0000, v149
	v_mul_f32_e32 v4, 0xbfb8aa3b, v4
	v_exp_f32_e32 v149, v4
	v_and_b32_e32 v4, 0xffff0000, v133
	v_mul_f32_e32 v4, 0xbfb8aa3b, v4
	v_exp_f32_e32 v4, v4
	v_pk_add_f32 v[148:149], v[148:149], 1.0 op_sel_hi:[1,0]
	v_pk_mul_f32 v[58:59], v[58:59], v[150:151]
	v_add_f32_e32 v4, 1.0, v4
	v_rcp_f32_e32 v133, v4
	s_nop 0
	v_pk_mul_f32 v[132:133], v[148:149], v[132:133]
	s_nop 0
	v_pk_mul_f32 v[60:61], v[60:61], v[132:133]
	v_mov_b32_e32 v132, v174
	v_mov_b32_e32 v133, v175
	v_mov_b32_e32 v148, v176
	v_mov_b32_e32 v149, v177
	s_waitcnt vmcnt(0)
	v_lshlrev_b32_e32 v4, 16, v148
	v_mul_f32_e32 v4, 0xbfb8aa3b, v4
	v_exp_f32_e32 v150, v4
	v_lshlrev_b32_e32 v4, 16, v132
	v_mul_f32_e32 v4, 0xbfb8aa3b, v4
	v_exp_f32_e32 v4, v4
	s_nop 0
	v_add_f32_e32 v4, 1.0, v4
	v_rcp_f32_e32 v152, v4
	v_and_b32_e32 v4, 0xffff0000, v148
	v_mul_f32_e32 v4, 0xbfb8aa3b, v4
	v_exp_f32_e32 v151, v4
	v_and_b32_e32 v4, 0xffff0000, v132
	v_mul_f32_e32 v4, 0xbfb8aa3b, v4
	v_exp_f32_e32 v4, v4
	v_pk_add_f32 v[150:151], v[150:151], 1.0 op_sel_hi:[1,0]
	v_add_f32_e32 v4, 1.0, v4
	v_rcp_f32_e32 v153, v4
	v_lshlrev_b32_e32 v4, 16, v149
	v_mul_f32_e32 v4, 0xbfb8aa3b, v4
	v_exp_f32_e32 v148, v4
	v_lshlrev_b32_e32 v4, 16, v133
	v_mul_f32_e32 v4, 0xbfb8aa3b, v4
	v_exp_f32_e32 v4, v4
	v_pk_mul_f32 v[150:151], v[150:151], v[152:153]
	v_add_f32_e32 v4, 1.0, v4
	v_rcp_f32_e32 v132, v4
	v_and_b32_e32 v4, 0xffff0000, v149
	v_mul_f32_e32 v4, 0xbfb8aa3b, v4
	v_exp_f32_e32 v149, v4
	v_and_b32_e32 v4, 0xffff0000, v133
	v_mul_f32_e32 v4, 0xbfb8aa3b, v4
	v_exp_f32_e32 v4, v4
	v_pk_add_f32 v[148:149], v[148:149], 1.0 op_sel_hi:[1,0]
	v_pk_mul_f32 v[54:55], v[54:55], v[150:151]
	v_add_co_u32_e32 v150, vcc, s0, v130
	v_add_f32_e32 v4, 1.0, v4
	v_rcp_f32_e32 v133, v4
	v_addc_co_u32_e32 v151, vcc, 0, v131, vcc
	s_mov_b32 s0, 0x1e2000
	v_pk_mul_f32 v[132:133], v[148:149], v[132:133]
	v_mov_b32_e32 v148, v204
	v_mov_b32_e32 v149, v205
	v_pk_mul_f32 v[56:57], v[56:57], v[132:133]
	v_add_co_u32_e32 v132, vcc, s0, v130
	s_mov_b32 s0, 0x211000
	s_nop 0
	v_addc_co_u32_e32 v133, vcc, 0, v131, vcc
	v_mov_b32_e32 v152, v206
	v_mov_b32_e32 v153, v207
	s_waitcnt vmcnt(0)
; DEV float bflo(unsigned u) { return __uint_as_float(u << 16); }
; DEV float bfhi(unsigned u) { return __uint_as_float(u & 0xffff0000u); }
; #define LBAR() do { asm volatile("s_waitcnt lgkmcnt(0)" ::: "memory"); __builtin_amdgcn_s_barrier(); asm volatile("" ::: "memory"); } while (0)
; DEV void gemm_phase(const GemmJob& J) {
;     ...
;             for (int m = 0; m < 4; ++m)
; #pragma unroll
;               for (int n = 0; n < 2; ++n) {
;                 const u16* g2 = gp + (long)(ai * HALF + m * 16) * LDR + bj * HALF + n * 16;
;                 const u32x2 ga = *(const u32x2*)(g2 + C_GA), gb = *(const u32x2*)(g2 + C_GB);
;                 f32x4 v = acc[ai][bj][m][n];
;                 v[0] *= (1.f + __expf(-bflo(gb.x))) * __builtin_amdgcn_rcpf(1.f + __expf(-bflo(ga.x)));
;                 v[1] *= (1.f + __expf(-bfhi(gb.x))) * __builtin_amdgcn_rcpf(1.f + __expf(-bfhi(ga.x)));
;                 v[2] *= (1.f + __expf(-bflo(gb.y))) * __builtin_amdgcn_rcpf(1.f + __expf(-bflo(ga.y)));
;                 v[3] *= (1.f + __expf(-bfhi(gb.y))) * __builtin_amdgcn_rcpf(1.f + __expf(-bfhi(ga.y)));
;                 acc[ai][bj][m][n] = v;
;               }
;             __builtin_amdgcn_sched_barrier(0);
;           }
;         LBAR();
	v_lshlrev_b32_e32 v4, 16, v152
	v_mul_f32_e32 v4, 0xbfb8aa3b, v4
	v_exp_f32_e32 v154, v4
	v_lshlrev_b32_e32 v4, 16, v148
	v_mul_f32_e32 v4, 0xbfb8aa3b, v4
	v_exp_f32_e32 v4, v4
	s_nop 0
	v_add_f32_e32 v4, 1.0, v4
	v_rcp_f32_e32 v156, v4
	v_and_b32_e32 v4, 0xffff0000, v152
	v_mul_f32_e32 v4, 0xbfb8aa3b, v4
	v_exp_f32_e32 v155, v4
	v_and_b32_e32 v4, 0xffff0000, v148
	v_mul_f32_e32 v4, 0xbfb8aa3b, v4
	v_exp_f32_e32 v4, v4
	v_pk_add_f32 v[154:155], v[154:155], 1.0 op_sel_hi:[1,0]
	v_add_f32_e32 v4, 1.0, v4
	v_rcp_f32_e32 v157, v4
	v_lshlrev_b32_e32 v4, 16, v153
	v_mul_f32_e32 v4, 0xbfb8aa3b, v4
	v_exp_f32_e32 v152, v4
	v_lshlrev_b32_e32 v4, 16, v149
	v_mul_f32_e32 v4, 0xbfb8aa3b, v4
	v_exp_f32_e32 v4, v4
	v_pk_mul_f32 v[154:155], v[154:155], v[156:157]
	v_add_f32_e32 v4, 1.0, v4
	v_rcp_f32_e32 v148, v4
	v_and_b32_e32 v4, 0xffff0000, v153
	v_mul_f32_e32 v4, 0xbfb8aa3b, v4
	v_exp_f32_e32 v153, v4
	v_and_b32_e32 v4, 0xffff0000, v149
	v_mul_f32_e32 v4, 0xbfb8aa3b, v4
	v_exp_f32_e32 v4, v4
	v_pk_add_f32 v[152:153], v[152:153], 1.0 op_sel_hi:[1,0]
	v_pk_mul_f32 v[50:51], v[50:51], v[154:155]
	v_add_f32_e32 v4, 1.0, v4
	v_rcp_f32_e32 v149, v4
	s_nop 0
	v_pk_mul_f32 v[148:149], v[152:153], v[148:149]
	s_nop 0
	v_pk_mul_f32 v[52:53], v[52:53], v[148:149]
	v_mov_b32_e32 v148, v208
	v_mov_b32_e32 v149, v209
	v_mov_b32_e32 v152, v210
	v_mov_b32_e32 v153, v211
	s_waitcnt vmcnt(0)
	v_lshlrev_b32_e32 v4, 16, v152
	v_mul_f32_e32 v4, 0xbfb8aa3b, v4
	v_exp_f32_e32 v154, v4
	v_lshlrev_b32_e32 v4, 16, v148
	v_mul_f32_e32 v4, 0xbfb8aa3b, v4
	v_exp_f32_e32 v4, v4
	s_nop 0
	v_add_f32_e32 v4, 1.0, v4
	v_rcp_f32_e32 v156, v4
	v_and_b32_e32 v4, 0xffff0000, v152
	v_mul_f32_e32 v4, 0xbfb8aa3b, v4
	v_exp_f32_e32 v155, v4
	v_and_b32_e32 v4, 0xffff0000, v148
	v_mul_f32_e32 v4, 0xbfb8aa3b, v4
	v_exp_f32_e32 v4, v4
	v_pk_add_f32 v[154:155], v[154:155], 1.0 op_sel_hi:[1,0]
	v_add_f32_e32 v4, 1.0, v4
	v_rcp_f32_e32 v157, v4
	v_lshlrev_b32_e32 v4, 16, v153
	v_mul_f32_e32 v4, 0xbfb8aa3b, v4
	v_exp_f32_e32 v152, v4
	v_lshlrev_b32_e32 v4, 16, v149
	v_mul_f32_e32 v4, 0xbfb8aa3b, v4
	v_exp_f32_e32 v4, v4
	v_pk_mul_f32 v[154:155], v[154:155], v[156:157]
	v_add_f32_e32 v4, 1.0, v4
	v_rcp_f32_e32 v148, v4
	v_and_b32_e32 v4, 0xffff0000, v153
	v_mul_f32_e32 v4, 0xbfb8aa3b, v4
	v_exp_f32_e32 v153, v4
	v_and_b32_e32 v4, 0xffff0000, v149
	v_mul_f32_e32 v4, 0xbfb8aa3b, v4
	v_exp_f32_e32 v4, v4
	v_pk_add_f32 v[152:153], v[152:153], 1.0 op_sel_hi:[1,0]
	v_pk_mul_f32 v[46:47], v[46:47], v[154:155]
	v_add_f32_e32 v4, 1.0, v4
	v_rcp_f32_e32 v149, v4
	s_nop 0
	v_pk_mul_f32 v[148:149], v[152:153], v[148:149]
	s_nop 0
	v_pk_mul_f32 v[48:49], v[48:49], v[148:149]
	v_add_co_u32_e32 v148, vcc, s0, v130
	s_mov_b32 s0, 0x212000
	s_nop 0
	v_addc_co_u32_e32 v149, vcc, 0, v131, vcc
	v_add_co_u32_e32 v130, vcc, s0, v130
	v_mov_b32_e32 v152, v212
	v_mov_b32_e32 v153, v213
	s_nop 0
	v_addc_co_u32_e32 v131, vcc, 0, v131, vcc
	v_mov_b32_e32 v154, v214
	v_mov_b32_e32 v155, v215
	s_waitcnt vmcnt(0)
	v_lshlrev_b32_e32 v4, 16, v154
	v_mul_f32_e32 v4, 0xbfb8aa3b, v4
	v_exp_f32_e32 v156, v4
	v_lshlrev_b32_e32 v4, 16, v152
	v_mul_f32_e32 v4, 0xbfb8aa3b, v4
	v_exp_f32_e32 v4, v4
	s_nop 0
	v_add_f32_e32 v4, 1.0, v4
	v_rcp_f32_e32 v158, v4
	v_and_b32_e32 v4, 0xffff0000, v154
	v_mul_f32_e32 v4, 0xbfb8aa3b, v4
	v_exp_f32_e32 v157, v4
	v_and_b32_e32 v4, 0xffff0000, v152
	v_mul_f32_e32 v4, 0xbfb8aa3b, v4
	v_exp_f32_e32 v4, v4
	v_pk_add_f32 v[156:157], v[156:157], 1.0 op_sel_hi:[1,0]
	v_add_f32_e32 v4, 1.0, v4
	v_rcp_f32_e32 v159, v4
	v_lshlrev_b32_e32 v4, 16, v155
	v_mul_f32_e32 v4, 0xbfb8aa3b, v4
	v_exp_f32_e32 v154, v4
	v_lshlrev_b32_e32 v4, 16, v153
	v_mul_f32_e32 v4, 0xbfb8aa3b, v4
	v_exp_f32_e32 v4, v4
	v_pk_mul_f32 v[156:157], v[156:157], v[158:159]
	v_add_f32_e32 v4, 1.0, v4
	v_rcp_f32_e32 v152, v4
	v_and_b32_e32 v4, 0xffff0000, v155
	v_mul_f32_e32 v4, 0xbfb8aa3b, v4
	v_exp_f32_e32 v155, v4
	v_and_b32_e32 v4, 0xffff0000, v153
	v_mul_f32_e32 v4, 0xbfb8aa3b, v4
	v_exp_f32_e32 v4, v4
	v_pk_add_f32 v[154:155], v[154:155], 1.0 op_sel_hi:[1,0]
	v_pk_mul_f32 v[42:43], v[42:43], v[156:157]
	v_add_f32_e32 v4, 1.0, v4
	v_rcp_f32_e32 v153, v4
	s_nop 0
	v_pk_mul_f32 v[152:153], v[154:155], v[152:153]
	s_nop 0
	v_pk_mul_f32 v[44:45], v[44:45], v[152:153]
	v_mov_b32_e32 v152, v216
	v_mov_b32_e32 v153, v217
	v_mov_b32_e32 v156, v218
	v_mov_b32_e32 v157, v219
	s_waitcnt vmcnt(0)
	v_lshlrev_b32_e32 v4, 16, v156
	v_mul_f32_e32 v4, 0xbfb8aa3b, v4
	v_exp_f32_e32 v154, v4
	v_lshlrev_b32_e32 v4, 16, v152
	v_mul_f32_e32 v4, 0xbfb8aa3b, v4
	v_exp_f32_e32 v4, v4
	s_nop 0
	v_add_f32_e32 v4, 1.0, v4
	v_rcp_f32_e32 v158, v4
	v_and_b32_e32 v4, 0xffff0000, v156
	v_mul_f32_e32 v4, 0xbfb8aa3b, v4
	v_exp_f32_e32 v155, v4
	v_and_b32_e32 v4, 0xffff0000, v152
	v_mul_f32_e32 v4, 0xbfb8aa3b, v4
	v_exp_f32_e32 v4, v4
	v_pk_add_f32 v[154:155], v[154:155], 1.0 op_sel_hi:[1,0]
	v_add_f32_e32 v4, 1.0, v4
	v_rcp_f32_e32 v159, v4
	v_lshlrev_b32_e32 v4, 16, v157
	v_mul_f32_e32 v4, 0xbfb8aa3b, v4
	v_exp_f32_e32 v156, v4
	v_lshlrev_b32_e32 v4, 16, v153
	v_mul_f32_e32 v4, 0xbfb8aa3b, v4
	v_exp_f32_e32 v4, v4
	v_pk_mul_f32 v[154:155], v[154:155], v[158:159]
	v_add_f32_e32 v4, 1.0, v4
	v_rcp_f32_e32 v152, v4
	v_and_b32_e32 v4, 0xffff0000, v157
	v_mul_f32_e32 v4, 0xbfb8aa3b, v4
	v_exp_f32_e32 v157, v4
	v_and_b32_e32 v4, 0xffff0000, v153
	v_mul_f32_e32 v4, 0xbfb8aa3b, v4
	v_exp_f32_e32 v4, v4
	v_pk_add_f32 v[156:157], v[156:157], 1.0 op_sel_hi:[1,0]
	v_pk_mul_f32 v[38:39], v[38:39], v[154:155]
	v_add_f32_e32 v4, 1.0, v4
	v_rcp_f32_e32 v153, v4
	s_nop 0
	v_pk_mul_f32 v[152:153], v[156:157], v[152:153]
	s_nop 0
	v_pk_mul_f32 v[40:41], v[40:41], v[152:153]
	v_mov_b32_e32 v152, v220
	v_mov_b32_e32 v153, v221
	v_mov_b32_e32 v154, v222
	v_mov_b32_e32 v155, v223
	s_nop 0
	v_mov_b32_e32 v140, v224
	v_mov_b32_e32 v141, v225
	s_nop 0
	v_mov_b32_e32 v134, v226
	v_mov_b32_e32 v135, v227
	s_waitcnt vmcnt(2)
; DEV float bflo(unsigned u) { return __uint_as_float(u << 16); }
; DEV float bfhi(unsigned u) { return __uint_as_float(u & 0xffff0000u); }
; #define LBAR() do { asm volatile("s_waitcnt lgkmcnt(0)" ::: "memory"); __builtin_amdgcn_s_barrier(); asm volatile("" ::: "memory"); } while (0)
; DEV void gemm_phase(const GemmJob& J) {
;     ...
;             for (int m = 0; m < 4; ++m)
; #pragma unroll
;               for (int n = 0; n < 2; ++n) {
;                 const u16* g2 = gp + (long)(ai * HALF + m * 16) * LDR + bj * HALF + n * 16;
;                 const u32x2 ga = *(const u32x2*)(g2 + C_GA), gb = *(const u32x2*)(g2 + C_GB);
;                 f32x4 v = acc[ai][bj][m][n];
;                 v[0] *= (1.f + __expf(-bflo(gb.x))) * __builtin_amdgcn_rcpf(1.f + __expf(-bflo(ga.x)));
;                 v[1] *= (1.f + __expf(-bfhi(gb.x))) * __builtin_amdgcn_rcpf(1.f + __expf(-bfhi(ga.x)));
;                 v[2] *= (1.f + __expf(-bflo(gb.y))) * __builtin_amdgcn_rcpf(1.f + __expf(-bflo(ga.y)));
;                 v[3] *= (1.f + __expf(-bfhi(gb.y))) * __builtin_amdgcn_rcpf(1.f + __expf(-bfhi(ga.y)));
;                 acc[ai][bj][m][n] = v;
;               }
;             __builtin_amdgcn_sched_barrier(0);
;           }
;         LBAR();
	v_lshlrev_b32_e32 v4, 16, v154
	v_mul_f32_e32 v4, 0xbfb8aa3b, v4
	v_exp_f32_e32 v156, v4
	v_lshlrev_b32_e32 v4, 16, v152
	v_mul_f32_e32 v4, 0xbfb8aa3b, v4
	v_exp_f32_e32 v4, v4
	s_nop 0
	v_add_f32_e32 v4, 1.0, v4
	v_rcp_f32_e32 v158, v4
	v_and_b32_e32 v4, 0xffff0000, v154
	v_mul_f32_e32 v4, 0xbfb8aa3b, v4
	v_exp_f32_e32 v157, v4
	v_and_b32_e32 v4, 0xffff0000, v152
	v_mul_f32_e32 v4, 0xbfb8aa3b, v4
	v_exp_f32_e32 v4, v4
	v_pk_add_f32 v[156:157], v[156:157], 1.0 op_sel_hi:[1,0]
	v_add_f32_e32 v4, 1.0, v4
	v_rcp_f32_e32 v159, v4
	v_lshlrev_b32_e32 v4, 16, v155
	v_mul_f32_e32 v4, 0xbfb8aa3b, v4
	v_exp_f32_e32 v154, v4
	v_lshlrev_b32_e32 v4, 16, v153
	v_mul_f32_e32 v4, 0xbfb8aa3b, v4
	v_exp_f32_e32 v4, v4
	v_pk_mul_f32 v[156:157], v[156:157], v[158:159]
	v_add_f32_e32 v4, 1.0, v4
	v_rcp_f32_e32 v152, v4
	v_and_b32_e32 v4, 0xffff0000, v155
	v_mul_f32_e32 v4, 0xbfb8aa3b, v4
	v_exp_f32_e32 v155, v4
	v_and_b32_e32 v4, 0xffff0000, v153
	v_mul_f32_e32 v4, 0xbfb8aa3b, v4
	v_exp_f32_e32 v4, v4
	v_pk_add_f32 v[154:155], v[154:155], 1.0 op_sel_hi:[1,0]
	v_pk_mul_f32 v[34:35], v[34:35], v[156:157]
	v_add_f32_e32 v4, 1.0, v4
	v_rcp_f32_e32 v153, v4
	s_waitcnt vmcnt(0)
	v_lshlrev_b32_e32 v4, 16, v134
	v_mul_f32_e32 v4, 0xbfb8aa3b, v4
	v_pk_mul_f32 v[152:153], v[154:155], v[152:153]
	s_nop 0
	v_pk_mul_f32 v[36:37], v[36:37], v[152:153]
	v_exp_f32_e32 v152, v4
	v_lshlrev_b32_e32 v4, 16, v140
	v_mul_f32_e32 v4, 0xbfb8aa3b, v4
	v_exp_f32_e32 v4, v4
	s_nop 0
	v_add_f32_e32 v4, 1.0, v4
	v_rcp_f32_e32 v154, v4
	v_and_b32_e32 v4, 0xffff0000, v134
	v_mul_f32_e32 v4, 0xbfb8aa3b, v4
	v_exp_f32_e32 v153, v4
	v_and_b32_e32 v4, 0xffff0000, v140
	v_mul_f32_e32 v4, 0xbfb8aa3b, v4
	v_exp_f32_e32 v4, v4
	v_pk_add_f32 v[152:153], v[152:153], 1.0 op_sel_hi:[1,0]
	v_add_f32_e32 v4, 1.0, v4
	v_rcp_f32_e32 v155, v4
	v_lshlrev_b32_e32 v4, 16, v135
	v_mul_f32_e32 v4, 0xbfb8aa3b, v4
	v_exp_f32_e32 v134, v4
	v_lshlrev_b32_e32 v4, 16, v141
	v_mul_f32_e32 v4, 0xbfb8aa3b, v4
	v_exp_f32_e32 v4, v4
	v_pk_mul_f32 v[152:153], v[152:153], v[154:155]
	v_add_f32_e32 v4, 1.0, v4
	v_rcp_f32_e32 v140, v4
	v_and_b32_e32 v4, 0xffff0000, v135
	v_mul_f32_e32 v4, 0xbfb8aa3b, v4
	v_exp_f32_e32 v135, v4
	v_and_b32_e32 v4, 0xffff0000, v141
	v_mul_f32_e32 v4, 0xbfb8aa3b, v4
	v_exp_f32_e32 v4, v4
	v_pk_add_f32 v[134:135], v[134:135], 1.0 op_sel_hi:[1,0]
	v_pk_mul_f32 v[30:31], v[30:31], v[152:153]
	v_add_f32_e32 v4, 1.0, v4
	v_rcp_f32_e32 v141, v4
	s_nop 0
	v_pk_mul_f32 v[134:135], v[134:135], v[140:141]
	s_nop 0
	v_pk_mul_f32 v[32:33], v[32:33], v[134:135]
	v_mov_b32_e32 v134, v228
	v_mov_b32_e32 v135, v229
	v_mov_b32_e32 v140, v230
	v_mov_b32_e32 v141, v231
	s_waitcnt vmcnt(0)
	v_lshlrev_b32_e32 v4, 16, v140
	v_mul_f32_e32 v4, 0xbfb8aa3b, v4
	v_exp_f32_e32 v152, v4
	v_lshlrev_b32_e32 v4, 16, v134
	v_mul_f32_e32 v4, 0xbfb8aa3b, v4
	v_exp_f32_e32 v4, v4
	s_nop 0
	v_add_f32_e32 v4, 1.0, v4
	v_rcp_f32_e32 v154, v4
	v_and_b32_e32 v4, 0xffff0000, v140
	v_mul_f32_e32 v4, 0xbfb8aa3b, v4
	v_exp_f32_e32 v153, v4
	v_and_b32_e32 v4, 0xffff0000, v134
	v_mul_f32_e32 v4, 0xbfb8aa3b, v4
	v_exp_f32_e32 v4, v4
	v_pk_add_f32 v[152:153], v[152:153], 1.0 op_sel_hi:[1,0]
	v_add_f32_e32 v4, 1.0, v4
	v_rcp_f32_e32 v155, v4
	v_lshlrev_b32_e32 v4, 16, v141
	v_mul_f32_e32 v4, 0xbfb8aa3b, v4
	v_exp_f32_e32 v140, v4
	v_lshlrev_b32_e32 v4, 16, v135
	v_mul_f32_e32 v4, 0xbfb8aa3b, v4
	v_exp_f32_e32 v4, v4
	v_pk_mul_f32 v[152:153], v[152:153], v[154:155]
	v_add_f32_e32 v4, 1.0, v4
	v_rcp_f32_e32 v134, v4
	v_and_b32_e32 v4, 0xffff0000, v141
	v_mul_f32_e32 v4, 0xbfb8aa3b, v4
	v_exp_f32_e32 v141, v4
	v_and_b32_e32 v4, 0xffff0000, v135
	v_mul_f32_e32 v4, 0xbfb8aa3b, v4
	v_exp_f32_e32 v4, v4
	v_pk_add_f32 v[140:141], v[140:141], 1.0 op_sel_hi:[1,0]
	v_pk_mul_f32 v[26:27], v[26:27], v[152:153]
	v_add_f32_e32 v4, 1.0, v4
	v_rcp_f32_e32 v135, v4
	s_nop 0
	v_pk_mul_f32 v[134:135], v[140:141], v[134:135]
	s_nop 0
	v_pk_mul_f32 v[28:29], v[28:29], v[134:135]
	v_mov_b32_e32 v134, v232
	v_mov_b32_e32 v135, v233
	s_nop 0
	v_mov_b32_e32 v136, v234
	v_mov_b32_e32 v137, v235
	s_waitcnt vmcnt(0)
	v_lshlrev_b32_e32 v4, 16, v136
	v_mul_f32_e32 v4, 0xbfb8aa3b, v4
	v_exp_f32_e32 v138, v4
	v_lshlrev_b32_e32 v4, 16, v134
	v_mul_f32_e32 v4, 0xbfb8aa3b, v4
	v_exp_f32_e32 v4, v4
	s_nop 0
	v_add_f32_e32 v4, 1.0, v4
	v_rcp_f32_e32 v140, v4
	v_and_b32_e32 v4, 0xffff0000, v136
	v_mul_f32_e32 v4, 0xbfb8aa3b, v4
	v_exp_f32_e32 v139, v4
	v_and_b32_e32 v4, 0xffff0000, v134
	v_mul_f32_e32 v4, 0xbfb8aa3b, v4
	v_exp_f32_e32 v4, v4
	v_pk_add_f32 v[138:139], v[138:139], 1.0 op_sel_hi:[1,0]
	v_add_f32_e32 v4, 1.0, v4
	v_rcp_f32_e32 v141, v4
	v_lshlrev_b32_e32 v4, 16, v137
	v_mul_f32_e32 v4, 0xbfb8aa3b, v4
	v_exp_f32_e32 v136, v4
	v_lshlrev_b32_e32 v4, 16, v135
	v_mul_f32_e32 v4, 0xbfb8aa3b, v4
	v_exp_f32_e32 v4, v4
	v_pk_mul_f32 v[138:139], v[138:139], v[140:141]
	v_add_f32_e32 v4, 1.0, v4
	v_rcp_f32_e32 v134, v4
	v_and_b32_e32 v4, 0xffff0000, v137
	v_mul_f32_e32 v4, 0xbfb8aa3b, v4
	v_exp_f32_e32 v137, v4
	v_and_b32_e32 v4, 0xffff0000, v135
	v_mul_f32_e32 v4, 0xbfb8aa3b, v4
	v_exp_f32_e32 v4, v4
	v_pk_add_f32 v[136:137], v[136:137], 1.0 op_sel_hi:[1,0]
	v_pk_mul_f32 v[22:23], v[22:23], v[138:139]
	v_add_f32_e32 v4, 1.0, v4
	v_rcp_f32_e32 v135, v4
	s_nop 0
	v_pk_mul_f32 v[134:135], v[136:137], v[134:135]
	s_nop 0
	v_pk_mul_f32 v[24:25], v[24:25], v[134:135]
	v_mov_b32_e32 v134, v236
	v_mov_b32_e32 v135, v237
	v_mov_b32_e32 v136, v238
	v_mov_b32_e32 v137, v239
	s_waitcnt vmcnt(0)
; DEV float bflo(unsigned u) { return __uint_as_float(u << 16); }
; DEV float bfhi(unsigned u) { return __uint_as_float(u & 0xffff0000u); }
; #define LBAR() do { asm volatile("s_waitcnt lgkmcnt(0)" ::: "memory"); __builtin_amdgcn_s_barrier(); asm volatile("" ::: "memory"); } while (0)
; DEV void gemm_phase(const GemmJob& J) {
;     ...
;             for (int m = 0; m < 4; ++m)
; #pragma unroll
;               for (int n = 0; n < 2; ++n) {
;                 const u16* g2 = gp + (long)(ai * HALF + m * 16) * LDR + bj * HALF + n * 16;
;                 const u32x2 ga = *(const u32x2*)(g2 + C_GA), gb = *(const u32x2*)(g2 + C_GB);
;                 f32x4 v = acc[ai][bj][m][n];
;                 v[0] *= (1.f + __expf(-bflo(gb.x))) * __builtin_amdgcn_rcpf(1.f + __expf(-bflo(ga.x)));
;                 v[1] *= (1.f + __expf(-bfhi(gb.x))) * __builtin_amdgcn_rcpf(1.f + __expf(-bfhi(ga.x)));
;                 v[2] *= (1.f + __expf(-bflo(gb.y))) * __builtin_amdgcn_rcpf(1.f + __expf(-bflo(ga.y)));
;                 v[3] *= (1.f + __expf(-bfhi(gb.y))) * __builtin_amdgcn_rcpf(1.f + __expf(-bfhi(ga.y)));
;                 acc[ai][bj][m][n] = v;
;               }
;             __builtin_amdgcn_sched_barrier(0);
;           }
;         LBAR();
	v_lshlrev_b32_e32 v4, 16, v136
	v_mul_f32_e32 v4, 0xbfb8aa3b, v4
	v_exp_f32_e32 v138, v4
	v_lshlrev_b32_e32 v4, 16, v134
	v_mul_f32_e32 v4, 0xbfb8aa3b, v4
	v_exp_f32_e32 v4, v4
	s_nop 0
	v_add_f32_e32 v4, 1.0, v4
	v_rcp_f32_e32 v140, v4
	v_and_b32_e32 v4, 0xffff0000, v136
	v_mul_f32_e32 v4, 0xbfb8aa3b, v4
	v_exp_f32_e32 v139, v4
	v_and_b32_e32 v4, 0xffff0000, v134
	v_mul_f32_e32 v4, 0xbfb8aa3b, v4
	v_exp_f32_e32 v4, v4
	v_pk_add_f32 v[138:139], v[138:139], 1.0 op_sel_hi:[1,0]
	v_add_f32_e32 v4, 1.0, v4
	v_rcp_f32_e32 v141, v4
	v_lshlrev_b32_e32 v4, 16, v137
	v_mul_f32_e32 v4, 0xbfb8aa3b, v4
	v_exp_f32_e32 v136, v4
	v_lshlrev_b32_e32 v4, 16, v135
	v_mul_f32_e32 v4, 0xbfb8aa3b, v4
	v_exp_f32_e32 v4, v4
	v_pk_mul_f32 v[138:139], v[138:139], v[140:141]
	v_add_f32_e32 v4, 1.0, v4
	v_rcp_f32_e32 v134, v4
	v_and_b32_e32 v4, 0xffff0000, v137
	v_mul_f32_e32 v4, 0xbfb8aa3b, v4
	v_exp_f32_e32 v137, v4
	v_and_b32_e32 v4, 0xffff0000, v135
	v_mul_f32_e32 v4, 0xbfb8aa3b, v4
	v_exp_f32_e32 v4, v4
	v_pk_add_f32 v[136:137], v[136:137], 1.0 op_sel_hi:[1,0]
	v_pk_mul_f32 v[18:19], v[18:19], v[138:139]
	v_add_f32_e32 v4, 1.0, v4
	v_rcp_f32_e32 v135, v4
	s_nop 0
	v_pk_mul_f32 v[134:135], v[136:137], v[134:135]
	s_nop 0
	v_pk_mul_f32 v[20:21], v[20:21], v[134:135]
	v_mov_b32_e32 v134, v240
	v_mov_b32_e32 v135, v241
	s_nop 0
	v_mov_b32_e32 v132, v242
	v_mov_b32_e32 v133, v243
	s_waitcnt vmcnt(0)
	v_lshlrev_b32_e32 v4, 16, v132
	v_mul_f32_e32 v4, 0xbfb8aa3b, v4
	v_exp_f32_e32 v136, v4
	v_lshlrev_b32_e32 v4, 16, v134
	v_mul_f32_e32 v4, 0xbfb8aa3b, v4
	v_exp_f32_e32 v4, v4
	s_nop 0
	v_add_f32_e32 v4, 1.0, v4
	v_rcp_f32_e32 v138, v4
	v_and_b32_e32 v4, 0xffff0000, v132
	v_mul_f32_e32 v4, 0xbfb8aa3b, v4
	v_exp_f32_e32 v137, v4
	v_and_b32_e32 v4, 0xffff0000, v134
	v_mul_f32_e32 v4, 0xbfb8aa3b, v4
	v_exp_f32_e32 v4, v4
	v_pk_add_f32 v[136:137], v[136:137], 1.0 op_sel_hi:[1,0]
	v_add_f32_e32 v4, 1.0, v4
	v_rcp_f32_e32 v139, v4
	v_lshlrev_b32_e32 v4, 16, v133
	v_mul_f32_e32 v4, 0xbfb8aa3b, v4
	v_exp_f32_e32 v132, v4
	v_lshlrev_b32_e32 v4, 16, v135
	v_mul_f32_e32 v4, 0xbfb8aa3b, v4
	v_exp_f32_e32 v4, v4
	v_pk_mul_f32 v[136:137], v[136:137], v[138:139]
	v_add_f32_e32 v4, 1.0, v4
	v_rcp_f32_e32 v134, v4
	v_and_b32_e32 v4, 0xffff0000, v133
	v_mul_f32_e32 v4, 0xbfb8aa3b, v4
	v_exp_f32_e32 v133, v4
	v_and_b32_e32 v4, 0xffff0000, v135
	v_mul_f32_e32 v4, 0xbfb8aa3b, v4
	v_exp_f32_e32 v4, v4
	v_pk_add_f32 v[132:133], v[132:133], 1.0 op_sel_hi:[1,0]
	v_pk_mul_f32 v[14:15], v[14:15], v[136:137]
	v_add_f32_e32 v4, 1.0, v4
	v_rcp_f32_e32 v135, v4
	s_nop 0
	v_pk_mul_f32 v[132:133], v[132:133], v[134:135]
	s_nop 0
	v_pk_mul_f32 v[16:17], v[16:17], v[132:133]
	v_mov_b32_e32 v132, v244
	v_mov_b32_e32 v133, v245
	v_mov_b32_e32 v134, v246
	v_mov_b32_e32 v135, v247
	s_waitcnt vmcnt(0)
	v_lshlrev_b32_e32 v4, 16, v134
	v_mul_f32_e32 v4, 0xbfb8aa3b, v4
	v_exp_f32_e32 v136, v4
	v_lshlrev_b32_e32 v4, 16, v132
	v_mul_f32_e32 v4, 0xbfb8aa3b, v4
	v_exp_f32_e32 v4, v4
	s_nop 0
	v_add_f32_e32 v4, 1.0, v4
	v_rcp_f32_e32 v138, v4
	v_and_b32_e32 v4, 0xffff0000, v134
	v_mul_f32_e32 v4, 0xbfb8aa3b, v4
	v_exp_f32_e32 v137, v4
	v_and_b32_e32 v4, 0xffff0000, v132
	v_mul_f32_e32 v4, 0xbfb8aa3b, v4
	v_exp_f32_e32 v4, v4
	v_pk_add_f32 v[136:137], v[136:137], 1.0 op_sel_hi:[1,0]
	v_add_f32_e32 v4, 1.0, v4
	v_rcp_f32_e32 v139, v4
	v_lshlrev_b32_e32 v4, 16, v135
	v_mul_f32_e32 v4, 0xbfb8aa3b, v4
	v_exp_f32_e32 v134, v4
	v_lshlrev_b32_e32 v4, 16, v133
	v_mul_f32_e32 v4, 0xbfb8aa3b, v4
	v_exp_f32_e32 v4, v4
	v_pk_mul_f32 v[136:137], v[136:137], v[138:139]
	v_add_f32_e32 v4, 1.0, v4
	v_rcp_f32_e32 v132, v4
	v_and_b32_e32 v4, 0xffff0000, v135
	v_mul_f32_e32 v4, 0xbfb8aa3b, v4
	v_exp_f32_e32 v135, v4
	v_and_b32_e32 v4, 0xffff0000, v133
	v_mul_f32_e32 v4, 0xbfb8aa3b, v4
	v_exp_f32_e32 v4, v4
	v_pk_add_f32 v[134:135], v[134:135], 1.0 op_sel_hi:[1,0]
	v_pk_mul_f32 v[10:11], v[10:11], v[136:137]
	v_add_f32_e32 v4, 1.0, v4
	v_rcp_f32_e32 v133, v4
	s_nop 0
	v_pk_mul_f32 v[132:133], v[134:135], v[132:133]
	s_nop 0
	v_pk_mul_f32 v[12:13], v[12:13], v[132:133]
	v_mov_b32_e32 v132, v248
	v_mov_b32_e32 v133, v249
	v_mov_b32_e32 v134, v250
	v_mov_b32_e32 v135, v251
	s_waitcnt vmcnt(0)
	v_lshlrev_b32_e32 v4, 16, v134
	v_mul_f32_e32 v4, 0xbfb8aa3b, v4
	v_exp_f32_e32 v130, v4
	v_lshlrev_b32_e32 v4, 16, v132
	v_mul_f32_e32 v4, 0xbfb8aa3b, v4
	v_exp_f32_e32 v4, v4
	s_nop 0
	v_add_f32_e32 v4, 1.0, v4
	v_rcp_f32_e32 v136, v4
	v_and_b32_e32 v4, 0xffff0000, v134
	v_mul_f32_e32 v4, 0xbfb8aa3b, v4
	v_exp_f32_e32 v131, v4
	v_and_b32_e32 v4, 0xffff0000, v132
	v_mul_f32_e32 v4, 0xbfb8aa3b, v4
	v_exp_f32_e32 v4, v4
	v_pk_add_f32 v[130:131], v[130:131], 1.0 op_sel_hi:[1,0]
	v_add_f32_e32 v4, 1.0, v4
	v_rcp_f32_e32 v137, v4
	v_lshlrev_b32_e32 v4, 16, v135
	v_mul_f32_e32 v4, 0xbfb8aa3b, v4
	v_exp_f32_e32 v134, v4
	v_lshlrev_b32_e32 v4, 16, v133
	v_mul_f32_e32 v4, 0xbfb8aa3b, v4
	v_exp_f32_e32 v4, v4
	v_pk_mul_f32 v[130:131], v[130:131], v[136:137]
	v_add_f32_e32 v4, 1.0, v4
	v_rcp_f32_e32 v132, v4
	v_and_b32_e32 v4, 0xffff0000, v135
	v_mul_f32_e32 v4, 0xbfb8aa3b, v4
	v_exp_f32_e32 v135, v4
	v_and_b32_e32 v4, 0xffff0000, v133
	v_mul_f32_e32 v4, 0xbfb8aa3b, v4
	v_exp_f32_e32 v4, v4
	v_pk_add_f32 v[134:135], v[134:135], 1.0 op_sel_hi:[1,0]
	v_pk_mul_f32 v[6:7], v[6:7], v[130:131]
	v_add_f32_e32 v4, 1.0, v4
	v_rcp_f32_e32 v133, v4
	s_nop 0
	v_pk_mul_f32 v[132:133], v[134:135], v[132:133]
	s_nop 0
	v_pk_mul_f32 v[8:9], v[8:9], v[132:133]
	s_waitcnt lgkmcnt(0)
	s_barrier
	s_branch .LBB0_180

; DEV unsigned pack2h(float a, float b) { unsigned r; asm("v_cvt_pk_bf16_f32 %0, %1, %2" : "=v"(r) : "v"(a), "v"(b)); return r; }
; DEV float bflo(unsigned u) { return __uint_as_float(u << 16); }
; DEV float bfhi(unsigned u) { return __uint_as_float(u & 0xffff0000u); }
; DEV float sigm(float x) { return __builtin_amdgcn_rcpf(1.f + __expf(-x)); }
; DEV void gemm_phase(const GemmJob& J) {
;     ...
;               for (int m = 0; m < 4; ++m) {
;                 f32x4 v = acc[ai][bj][m][n];
;                 float v0 = v[0], v1 = v[1], v2 = v[2], v3 = v[3];
;                 if (mode == 4) {
;                   v0 = fmaxf(v0, 0.f); v1 = fmaxf(v1, 0.f); v2 = fmaxf(v2, 0.f); v3 = fmaxf(v3, 0.f);
;                   v0 *= v0; v1 *= v1; v2 *= v2; v3 *= v3;
;                 } else if (mode == 2) {
;                   const u32x2 gb = *(const u32x2*)(J.gate + (long)(brow + ai * HALF + wr * 64 + m * 16 + fr) * LDR + C_GB + bcol + bj * HALF + wc * 32 + n * 16 + fq * 4);
;                   v0 *= sigm(bflo(gb.x)); v1 *= sigm(bfhi(gb.x)); v2 *= sigm(bflo(gb.y)); v3 *= sigm(bfhi(gb.y));
;                 }
;                 u32x2 o; o.x = pack2h(v0, v1); o.y = pack2h(v2, v3);
;                 *(u32x2*)(sw + m * 16 * 264 + bj * HALF + n * 16) = o;
.Lfast1_h0:
	v_cvt_pk_bf16_f32 v204, v0, v1
	v_cvt_pk_bf16_f32 v205, v2, v3
	ds_write_b64 v159, v[204:205]
	v_cvt_pk_bf16_f32 v208, v122, v123
	v_cvt_pk_bf16_f32 v209, v124, v125
	ds_write_b64 v159, v[208:209] offset:8448
	v_cvt_pk_bf16_f32 v212, v114, v115
	v_cvt_pk_bf16_f32 v213, v116, v117
	ds_write_b64 v159, v[212:213] offset:16896
	v_cvt_pk_bf16_f32 v216, v106, v107
	v_cvt_pk_bf16_f32 v217, v108, v109
	ds_write_b64 v159, v[216:217] offset:25344
	v_cvt_pk_bf16_f32 v220, v126, v127
	v_cvt_pk_bf16_f32 v221, v128, v129
	ds_write_b64 v159, v[220:221] offset:32
	v_cvt_pk_bf16_f32 v224, v118, v119
	v_cvt_pk_bf16_f32 v225, v120, v121
	ds_write_b64 v159, v[224:225] offset:8480
	v_cvt_pk_bf16_f32 v228, v110, v111
	v_cvt_pk_bf16_f32 v229, v112, v113
	ds_write_b64 v159, v[228:229] offset:16928
	v_cvt_pk_bf16_f32 v232, v102, v103
	v_cvt_pk_bf16_f32 v233, v104, v105
	ds_write_b64 v159, v[232:233] offset:25376
	v_cvt_pk_bf16_f32 v236, v98, v99
	v_cvt_pk_bf16_f32 v237, v100, v101
	ds_write_b64 v159, v[236:237] offset:256
	v_cvt_pk_bf16_f32 v240, v90, v91
	v_cvt_pk_bf16_f32 v241, v92, v93
	ds_write_b64 v159, v[240:241] offset:8704
	v_cvt_pk_bf16_f32 v244, v82, v83
	v_cvt_pk_bf16_f32 v245, v84, v85
	ds_write_b64 v159, v[244:245] offset:17152
	v_cvt_pk_bf16_f32 v248, v74, v75
	v_cvt_pk_bf16_f32 v249, v76, v77
	ds_write_b64 v159, v[248:249] offset:25600
	v_cvt_pk_bf16_f32 v204, v94, v95
	v_cvt_pk_bf16_f32 v205, v96, v97
	ds_write_b64 v159, v[204:205] offset:288
	v_cvt_pk_bf16_f32 v208, v86, v87
	v_cvt_pk_bf16_f32 v209, v88, v89
	ds_write_b64 v159, v[208:209] offset:8736
	v_cvt_pk_bf16_f32 v212, v78, v79
	v_cvt_pk_bf16_f32 v213, v80, v81
	ds_write_b64 v159, v[212:213] offset:17184
	v_cvt_pk_bf16_f32 v132, v70, v71
	v_cvt_pk_bf16_f32 v133, v72, v73
	s_mov_b64 s[10:11], 0
	s_mov_b64 s[8:9], 0
	s_branch .LBB0_309
.Lfast4_h0:
	v_max_f32_e32 v204, v0, v0
	v_max_f32_e32 v205, v1, v1
	v_max_f32_e32 v206, v2, v2
	v_max_f32_e32 v207, v3, v3
	v_max_f32_e32 v204, 0, v204
	v_max_f32_e32 v205, 0, v205
	v_max_f32_e32 v206, 0, v206
	v_max_f32_e32 v207, 0, v207
	v_pk_mul_f32 v[204:205], v[204:205], v[204:205]
	v_pk_mul_f32 v[206:207], v[206:207], v[206:207]
	v_cvt_pk_bf16_f32 v204, v204, v205
	v_cvt_pk_bf16_f32 v205, v206, v207
	ds_write_b64 v159, v[204:205]
	v_max_f32_e32 v208, v122, v122
	v_max_f32_e32 v209, v123, v123
	v_max_f32_e32 v210, v124, v124
	v_max_f32_e32 v211, v125, v125
	v_max_f32_e32 v208, 0, v208
	v_max_f32_e32 v209, 0, v209
	v_max_f32_e32 v210, 0, v210
	v_max_f32_e32 v211, 0, v211
	v_pk_mul_f32 v[208:209], v[208:209], v[208:209]
	v_pk_mul_f32 v[210:211], v[210:211], v[210:211]
	v_cvt_pk_bf16_f32 v208, v208, v209
	v_cvt_pk_bf16_f32 v209, v210, v211
	ds_write_b64 v159, v[208:209] offset:8448
	v_max_f32_e32 v212, v114, v114
	v_max_f32_e32 v213, v115, v115
	v_max_f32_e32 v214, v116, v116
	v_max_f32_e32 v215, v117, v117
	v_max_f32_e32 v212, 0, v212
	v_max_f32_e32 v213, 0, v213
	v_max_f32_e32 v214, 0, v214
	v_max_f32_e32 v215, 0, v215
	v_pk_mul_f32 v[212:213], v[212:213], v[212:213]
	v_pk_mul_f32 v[214:215], v[214:215], v[214:215]
	v_cvt_pk_bf16_f32 v212, v212, v213
	v_cvt_pk_bf16_f32 v213, v214, v215
	ds_write_b64 v159, v[212:213] offset:16896
	v_max_f32_e32 v216, v106, v106
	v_max_f32_e32 v217, v107, v107
	v_max_f32_e32 v218, v108, v108
	v_max_f32_e32 v219, v109, v109
	v_max_f32_e32 v216, 0, v216
	v_max_f32_e32 v217, 0, v217
	v_max_f32_e32 v218, 0, v218
	v_max_f32_e32 v219, 0, v219
	v_pk_mul_f32 v[216:217], v[216:217], v[216:217]
	v_pk_mul_f32 v[218:219], v[218:219], v[218:219]
	v_cvt_pk_bf16_f32 v216, v216, v217
	v_cvt_pk_bf16_f32 v217, v218, v219
	ds_write_b64 v159, v[216:217] offset:25344
	v_max_f32_e32 v220, v126, v126
	v_max_f32_e32 v221, v127, v127
	v_max_f32_e32 v222, v128, v128
	v_max_f32_e32 v223, v129, v129
	v_max_f32_e32 v220, 0, v220
	v_max_f32_e32 v221, 0, v221
	v_max_f32_e32 v222, 0, v222
	v_max_f32_e32 v223, 0, v223
	v_pk_mul_f32 v[220:221], v[220:221], v[220:221]
	v_pk_mul_f32 v[222:223], v[222:223], v[222:223]
	v_cvt_pk_bf16_f32 v220, v220, v221
	v_cvt_pk_bf16_f32 v221, v222, v223
	ds_write_b64 v159, v[220:221] offset:32
	v_max_f32_e32 v224, v118, v118
	v_max_f32_e32 v225, v119, v119
	v_max_f32_e32 v226, v120, v120
	v_max_f32_e32 v227, v121, v121
	v_max_f32_e32 v224, 0, v224
	v_max_f32_e32 v225, 0, v225
	v_max_f32_e32 v226, 0, v226
	v_max_f32_e32 v227, 0, v227
	v_pk_mul_f32 v[224:225], v[224:225], v[224:225]
	v_pk_mul_f32 v[226:227], v[226:227], v[226:227]
	v_cvt_pk_bf16_f32 v224, v224, v225
	v_cvt_pk_bf16_f32 v225, v226, v227
	ds_write_b64 v159, v[224:225] offset:8480
	v_max_f32_e32 v228, v110, v110
	v_max_f32_e32 v229, v111, v111
	v_max_f32_e32 v230, v112, v112
	v_max_f32_e32 v231, v113, v113
	v_max_f32_e32 v228, 0, v228
	v_max_f32_e32 v229, 0, v229
	v_max_f32_e32 v230, 0, v230
	v_max_f32_e32 v231, 0, v231
	v_pk_mul_f32 v[228:229], v[228:229], v[228:229]
	v_pk_mul_f32 v[230:231], v[230:231], v[230:231]
	v_cvt_pk_bf16_f32 v228, v228, v229
	v_cvt_pk_bf16_f32 v229, v230, v231
	ds_write_b64 v159, v[228:229] offset:16928
	v_max_f32_e32 v232, v102, v102
	v_max_f32_e32 v233, v103, v103
	v_max_f32_e32 v234, v104, v104
	v_max_f32_e32 v235, v105, v105
	v_max_f32_e32 v232, 0, v232
	v_max_f32_e32 v233, 0, v233
	v_max_f32_e32 v234, 0, v234
	v_max_f32_e32 v235, 0, v235
	v_pk_mul_f32 v[232:233], v[232:233], v[232:233]
	v_pk_mul_f32 v[234:235], v[234:235], v[234:235]
	v_cvt_pk_bf16_f32 v232, v232, v233
	v_cvt_pk_bf16_f32 v233, v234, v235
	ds_write_b64 v159, v[232:233] offset:25376
	v_max_f32_e32 v236, v98, v98
	v_max_f32_e32 v237, v99, v99
	v_max_f32_e32 v238, v100, v100
	v_max_f32_e32 v239, v101, v101
	v_max_f32_e32 v236, 0, v236
	v_max_f32_e32 v237, 0, v237
; DEV unsigned pack2h(float a, float b) { unsigned r; asm("v_cvt_pk_bf16_f32 %0, %1, %2" : "=v"(r) : "v"(a), "v"(b)); return r; }
; DEV float bflo(unsigned u) { return __uint_as_float(u << 16); }
; DEV float bfhi(unsigned u) { return __uint_as_float(u & 0xffff0000u); }
; DEV float sigm(float x) { return __builtin_amdgcn_rcpf(1.f + __expf(-x)); }
; DEV void gemm_phase(const GemmJob& J) {
;     ...
;               for (int m = 0; m < 4; ++m) {
;                 f32x4 v = acc[ai][bj][m][n];
;                 float v0 = v[0], v1 = v[1], v2 = v[2], v3 = v[3];
;                 if (mode == 4) {
;                   v0 = fmaxf(v0, 0.f); v1 = fmaxf(v1, 0.f); v2 = fmaxf(v2, 0.f); v3 = fmaxf(v3, 0.f);
;                   v0 *= v0; v1 *= v1; v2 *= v2; v3 *= v3;
;                 } else if (mode == 2) {
;                   const u32x2 gb = *(const u32x2*)(J.gate + (long)(brow + ai * HALF + wr * 64 + m * 16 + fr) * LDR + C_GB + bcol + bj * HALF + wc * 32 + n * 16 + fq * 4);
;                   v0 *= sigm(bflo(gb.x)); v1 *= sigm(bfhi(gb.x)); v2 *= sigm(bflo(gb.y)); v3 *= sigm(bfhi(gb.y));
;                 }
;                 u32x2 o; o.x = pack2h(v0, v1); o.y = pack2h(v2, v3);
;                 *(u32x2*)(sw + m * 16 * 264 + bj * HALF + n * 16) = o;
	v_max_f32_e32 v238, 0, v238
	v_max_f32_e32 v239, 0, v239
	v_pk_mul_f32 v[236:237], v[236:237], v[236:237]
	v_pk_mul_f32 v[238:239], v[238:239], v[238:239]
	v_cvt_pk_bf16_f32 v236, v236, v237
	v_cvt_pk_bf16_f32 v237, v238, v239
	ds_write_b64 v159, v[236:237] offset:256
	v_max_f32_e32 v240, v90, v90
	v_max_f32_e32 v241, v91, v91
	v_max_f32_e32 v242, v92, v92
	v_max_f32_e32 v243, v93, v93
	v_max_f32_e32 v240, 0, v240
	v_max_f32_e32 v241, 0, v241
	v_max_f32_e32 v242, 0, v242
	v_max_f32_e32 v243, 0, v243
	v_pk_mul_f32 v[240:241], v[240:241], v[240:241]
	v_pk_mul_f32 v[242:243], v[242:243], v[242:243]
	v_cvt_pk_bf16_f32 v240, v240, v241
	v_cvt_pk_bf16_f32 v241, v242, v243
	ds_write_b64 v159, v[240:241] offset:8704
	v_max_f32_e32 v244, v82, v82
	v_max_f32_e32 v245, v83, v83
	v_max_f32_e32 v246, v84, v84
	v_max_f32_e32 v247, v85, v85
	v_max_f32_e32 v244, 0, v244
	v_max_f32_e32 v245, 0, v245
	v_max_f32_e32 v246, 0, v246
	v_max_f32_e32 v247, 0, v247
	v_pk_mul_f32 v[244:245], v[244:245], v[244:245]
	v_pk_mul_f32 v[246:247], v[246:247], v[246:247]
	v_cvt_pk_bf16_f32 v244, v244, v245
	v_cvt_pk_bf16_f32 v245, v246, v247
	ds_write_b64 v159, v[244:245] offset:17152
	v_max_f32_e32 v248, v74, v74
	v_max_f32_e32 v249, v75, v75
	v_max_f32_e32 v250, v76, v76
	v_max_f32_e32 v251, v77, v77
	v_max_f32_e32 v248, 0, v248
	v_max_f32_e32 v249, 0, v249
	v_max_f32_e32 v250, 0, v250
	v_max_f32_e32 v251, 0, v251
	v_pk_mul_f32 v[248:249], v[248:249], v[248:249]
	v_pk_mul_f32 v[250:251], v[250:251], v[250:251]
	v_cvt_pk_bf16_f32 v248, v248, v249
	v_cvt_pk_bf16_f32 v249, v250, v251
	ds_write_b64 v159, v[248:249] offset:25600
	v_max_f32_e32 v204, v94, v94
	v_max_f32_e32 v205, v95, v95
	v_max_f32_e32 v206, v96, v96
	v_max_f32_e32 v207, v97, v97
	v_max_f32_e32 v204, 0, v204
	v_max_f32_e32 v205, 0, v205
	v_max_f32_e32 v206, 0, v206
	v_max_f32_e32 v207, 0, v207
	v_pk_mul_f32 v[204:205], v[204:205], v[204:205]
	v_pk_mul_f32 v[206:207], v[206:207], v[206:207]
	v_cvt_pk_bf16_f32 v204, v204, v205
	v_cvt_pk_bf16_f32 v205, v206, v207
	ds_write_b64 v159, v[204:205] offset:288
	v_max_f32_e32 v208, v86, v86
	v_max_f32_e32 v209, v87, v87
	v_max_f32_e32 v210, v88, v88
	v_max_f32_e32 v211, v89, v89
	v_max_f32_e32 v208, 0, v208
	v_max_f32_e32 v209, 0, v209
	v_max_f32_e32 v210, 0, v210
	v_max_f32_e32 v211, 0, v211
	v_pk_mul_f32 v[208:209], v[208:209], v[208:209]
	v_pk_mul_f32 v[210:211], v[210:211], v[210:211]
	v_cvt_pk_bf16_f32 v208, v208, v209
	v_cvt_pk_bf16_f32 v209, v210, v211
	ds_write_b64 v159, v[208:209] offset:8736
	v_max_f32_e32 v212, v78, v78
	v_max_f32_e32 v213, v79, v79
	v_max_f32_e32 v214, v80, v80
	v_max_f32_e32 v215, v81, v81
	v_max_f32_e32 v212, 0, v212
	v_max_f32_e32 v213, 0, v213
	v_max_f32_e32 v214, 0, v214
	v_max_f32_e32 v215, 0, v215
	v_pk_mul_f32 v[212:213], v[212:213], v[212:213]
	v_pk_mul_f32 v[214:215], v[214:215], v[214:215]
	v_cvt_pk_bf16_f32 v212, v212, v213
	v_cvt_pk_bf16_f32 v213, v214, v215
	ds_write_b64 v159, v[212:213] offset:17184
	v_max_f32_e32 v216, v70, v70
	v_max_f32_e32 v217, v71, v71
	v_max_f32_e32 v218, v72, v72
	v_max_f32_e32 v219, v73, v73
	v_max_f32_e32 v216, 0, v216
	v_max_f32_e32 v217, 0, v217
	v_max_f32_e32 v218, 0, v218
	v_max_f32_e32 v219, 0, v219
	v_pk_mul_f32 v[216:217], v[216:217], v[216:217]
	v_pk_mul_f32 v[218:219], v[218:219], v[218:219]
	v_cvt_pk_bf16_f32 v132, v216, v217
	v_cvt_pk_bf16_f32 v133, v218, v219
	s_mov_b64 s[10:11], 0
	s_mov_b64 s[8:9], -1
	s_branch .LBB0_309
.Lfast1_h1:
	v_cvt_pk_bf16_f32 v204, v66, v67
	v_cvt_pk_bf16_f32 v205, v68, v69
	ds_write_b64 v159, v[204:205]
	v_cvt_pk_bf16_f32 v208, v58, v59
	v_cvt_pk_bf16_f32 v209, v60, v61
	ds_write_b64 v159, v[208:209] offset:8448
	v_cvt_pk_bf16_f32 v212, v50, v51
	v_cvt_pk_bf16_f32 v213, v52, v53
	ds_write_b64 v159, v[212:213] offset:16896
	v_cvt_pk_bf16_f32 v216, v42, v43
	v_cvt_pk_bf16_f32 v217, v44, v45
	ds_write_b64 v159, v[216:217] offset:25344
	v_cvt_pk_bf16_f32 v220, v62, v63
	v_cvt_pk_bf16_f32 v221, v64, v65
	ds_write_b64 v159, v[220:221] offset:32
	v_cvt_pk_bf16_f32 v224, v54, v55
	v_cvt_pk_bf16_f32 v225, v56, v57
	ds_write_b64 v159, v[224:225] offset:8480
	v_cvt_pk_bf16_f32 v228, v46, v47
	v_cvt_pk_bf16_f32 v229, v48, v49
	ds_write_b64 v159, v[228:229] offset:16928
	v_cvt_pk_bf16_f32 v232, v38, v39
	v_cvt_pk_bf16_f32 v233, v40, v41
	ds_write_b64 v159, v[232:233] offset:25376
	v_cvt_pk_bf16_f32 v236, v34, v35
	v_cvt_pk_bf16_f32 v237, v36, v37
	ds_write_b64 v159, v[236:237] offset:256
	v_cvt_pk_bf16_f32 v240, v26, v27
	v_cvt_pk_bf16_f32 v241, v28, v29
	ds_write_b64 v159, v[240:241] offset:8704
	v_cvt_pk_bf16_f32 v244, v18, v19
	v_cvt_pk_bf16_f32 v245, v20, v21
	ds_write_b64 v159, v[244:245] offset:17152
	v_cvt_pk_bf16_f32 v248, v10, v11
	v_cvt_pk_bf16_f32 v249, v12, v13
	ds_write_b64 v159, v[248:249] offset:25600
	v_cvt_pk_bf16_f32 v204, v30, v31
	v_cvt_pk_bf16_f32 v205, v32, v33
	ds_write_b64 v159, v[204:205] offset:288
	v_cvt_pk_bf16_f32 v208, v22, v23
	v_cvt_pk_bf16_f32 v209, v24, v25
	ds_write_b64 v159, v[208:209] offset:8736
	v_cvt_pk_bf16_f32 v212, v14, v15
	v_cvt_pk_bf16_f32 v213, v16, v17
	ds_write_b64 v159, v[212:213] offset:17184
	v_cvt_pk_bf16_f32 v132, v6, v7
	v_cvt_pk_bf16_f32 v133, v8, v9
	s_branch .LBB0_425
; DEV unsigned pack2h(float a, float b) { unsigned r; asm("v_cvt_pk_bf16_f32 %0, %1, %2" : "=v"(r) : "v"(a), "v"(b)); return r; }
; DEV float bflo(unsigned u) { return __uint_as_float(u << 16); }
; DEV float bfhi(unsigned u) { return __uint_as_float(u & 0xffff0000u); }
; DEV float sigm(float x) { return __builtin_amdgcn_rcpf(1.f + __expf(-x)); }
; DEV void gemm_phase(const GemmJob& J) {
;     ...
;               for (int m = 0; m < 4; ++m) {
;                 f32x4 v = acc[ai][bj][m][n];
;                 float v0 = v[0], v1 = v[1], v2 = v[2], v3 = v[3];
;                 if (mode == 4) {
;                   v0 = fmaxf(v0, 0.f); v1 = fmaxf(v1, 0.f); v2 = fmaxf(v2, 0.f); v3 = fmaxf(v3, 0.f);
;                   v0 *= v0; v1 *= v1; v2 *= v2; v3 *= v3;
;                 } else if (mode == 2) {
;                   const u32x2 gb = *(const u32x2*)(J.gate + (long)(brow + ai * HALF + wr * 64 + m * 16 + fr) * LDR + C_GB + bcol + bj * HALF + wc * 32 + n * 16 + fq * 4);
;                   v0 *= sigm(bflo(gb.x)); v1 *= sigm(bfhi(gb.x)); v2 *= sigm(bflo(gb.y)); v3 *= sigm(bfhi(gb.y));
;                 }
;                 u32x2 o; o.x = pack2h(v0, v1); o.y = pack2h(v2, v3);
;                 *(u32x2*)(sw + m * 16 * 264 + bj * HALF + n * 16) = o;
.Lfast4_h1:
	v_max_f32_e32 v204, v66, v66
	v_max_f32_e32 v205, v67, v67
	v_max_f32_e32 v206, v68, v68
	v_max_f32_e32 v207, v69, v69
	v_max_f32_e32 v204, 0, v204
	v_max_f32_e32 v205, 0, v205
	v_max_f32_e32 v206, 0, v206
	v_max_f32_e32 v207, 0, v207
	v_pk_mul_f32 v[204:205], v[204:205], v[204:205]
	v_pk_mul_f32 v[206:207], v[206:207], v[206:207]
	v_cvt_pk_bf16_f32 v204, v204, v205
	v_cvt_pk_bf16_f32 v205, v206, v207
	ds_write_b64 v159, v[204:205]
	v_max_f32_e32 v208, v58, v58
	v_max_f32_e32 v209, v59, v59
	v_max_f32_e32 v210, v60, v60
	v_max_f32_e32 v211, v61, v61
	v_max_f32_e32 v208, 0, v208
	v_max_f32_e32 v209, 0, v209
	v_max_f32_e32 v210, 0, v210
	v_max_f32_e32 v211, 0, v211
	v_pk_mul_f32 v[208:209], v[208:209], v[208:209]
	v_pk_mul_f32 v[210:211], v[210:211], v[210:211]
	v_cvt_pk_bf16_f32 v208, v208, v209
	v_cvt_pk_bf16_f32 v209, v210, v211
	ds_write_b64 v159, v[208:209] offset:8448
	v_max_f32_e32 v212, v50, v50
	v_max_f32_e32 v213, v51, v51
	v_max_f32_e32 v214, v52, v52
	v_max_f32_e32 v215, v53, v53
	v_max_f32_e32 v212, 0, v212
	v_max_f32_e32 v213, 0, v213
	v_max_f32_e32 v214, 0, v214
	v_max_f32_e32 v215, 0, v215
	v_pk_mul_f32 v[212:213], v[212:213], v[212:213]
	v_pk_mul_f32 v[214:215], v[214:215], v[214:215]
	v_cvt_pk_bf16_f32 v212, v212, v213
	v_cvt_pk_bf16_f32 v213, v214, v215
	ds_write_b64 v159, v[212:213] offset:16896
	v_max_f32_e32 v216, v42, v42
	v_max_f32_e32 v217, v43, v43
	v_max_f32_e32 v218, v44, v44
	v_max_f32_e32 v219, v45, v45
	v_max_f32_e32 v216, 0, v216
	v_max_f32_e32 v217, 0, v217
	v_max_f32_e32 v218, 0, v218
	v_max_f32_e32 v219, 0, v219
	v_pk_mul_f32 v[216:217], v[216:217], v[216:217]
	v_pk_mul_f32 v[218:219], v[218:219], v[218:219]
	v_cvt_pk_bf16_f32 v216, v216, v217
	v_cvt_pk_bf16_f32 v217, v218, v219
	ds_write_b64 v159, v[216:217] offset:25344
	v_max_f32_e32 v220, v62, v62
	v_max_f32_e32 v221, v63, v63
	v_max_f32_e32 v222, v64, v64
	v_max_f32_e32 v223, v65, v65
	v_max_f32_e32 v220, 0, v220
	v_max_f32_e32 v221, 0, v221
	v_max_f32_e32 v222, 0, v222
	v_max_f32_e32 v223, 0, v223
	v_pk_mul_f32 v[220:221], v[220:221], v[220:221]
	v_pk_mul_f32 v[222:223], v[222:223], v[222:223]
	v_cvt_pk_bf16_f32 v220, v220, v221
	v_cvt_pk_bf16_f32 v221, v222, v223
	ds_write_b64 v159, v[220:221] offset:32
	v_max_f32_e32 v224, v54, v54
	v_max_f32_e32 v225, v55, v55
	v_max_f32_e32 v226, v56, v56
	v_max_f32_e32 v227, v57, v57
	v_max_f32_e32 v224, 0, v224
	v_max_f32_e32 v225, 0, v225
	v_max_f32_e32 v226, 0, v226
	v_max_f32_e32 v227, 0, v227
	v_pk_mul_f32 v[224:225], v[224:225], v[224:225]
	v_pk_mul_f32 v[226:227], v[226:227], v[226:227]
	v_cvt_pk_bf16_f32 v224, v224, v225
	v_cvt_pk_bf16_f32 v225, v226, v227
	ds_write_b64 v159, v[224:225] offset:8480
	v_max_f32_e32 v228, v46, v46
	v_max_f32_e32 v229, v47, v47
	v_max_f32_e32 v230, v48, v48
	v_max_f32_e32 v231, v49, v49
	v_max_f32_e32 v228, 0, v228
	v_max_f32_e32 v229, 0, v229
	v_max_f32_e32 v230, 0, v230
	v_max_f32_e32 v231, 0, v231
	v_pk_mul_f32 v[228:229], v[228:229], v[228:229]
	v_pk_mul_f32 v[230:231], v[230:231], v[230:231]
	v_cvt_pk_bf16_f32 v228, v228, v229
	v_cvt_pk_bf16_f32 v229, v230, v231
	ds_write_b64 v159, v[228:229] offset:16928
	v_max_f32_e32 v232, v38, v38
	v_max_f32_e32 v233, v39, v39
	v_max_f32_e32 v234, v40, v40
	v_max_f32_e32 v235, v41, v41
	v_max_f32_e32 v232, 0, v232
	v_max_f32_e32 v233, 0, v233
	v_max_f32_e32 v234, 0, v234
	v_max_f32_e32 v235, 0, v235
	v_pk_mul_f32 v[232:233], v[232:233], v[232:233]
	v_pk_mul_f32 v[234:235], v[234:235], v[234:235]
	v_cvt_pk_bf16_f32 v232, v232, v233
	v_cvt_pk_bf16_f32 v233, v234, v235
	ds_write_b64 v159, v[232:233] offset:25376
; DEV unsigned pack2h(float a, float b) { unsigned r; asm("v_cvt_pk_bf16_f32 %0, %1, %2" : "=v"(r) : "v"(a), "v"(b)); return r; }
; DEV float bflo(unsigned u) { return __uint_as_float(u << 16); }
; DEV float bfhi(unsigned u) { return __uint_as_float(u & 0xffff0000u); }
; DEV float sigm(float x) { return __builtin_amdgcn_rcpf(1.f + __expf(-x)); }
; DEV void gemm_phase(const GemmJob& J) {
;     ...
;               for (int m = 0; m < 4; ++m) {
;                 f32x4 v = acc[ai][bj][m][n];
;                 float v0 = v[0], v1 = v[1], v2 = v[2], v3 = v[3];
;                 if (mode == 4) {
;                   v0 = fmaxf(v0, 0.f); v1 = fmaxf(v1, 0.f); v2 = fmaxf(v2, 0.f); v3 = fmaxf(v3, 0.f);
;                   v0 *= v0; v1 *= v1; v2 *= v2; v3 *= v3;
;                 } else if (mode == 2) {
;                   const u32x2 gb = *(const u32x2*)(J.gate + (long)(brow + ai * HALF + wr * 64 + m * 16 + fr) * LDR + C_GB + bcol + bj * HALF + wc * 32 + n * 16 + fq * 4);
;                   v0 *= sigm(bflo(gb.x)); v1 *= sigm(bfhi(gb.x)); v2 *= sigm(bflo(gb.y)); v3 *= sigm(bfhi(gb.y));
;                 }
;                 u32x2 o; o.x = pack2h(v0, v1); o.y = pack2h(v2, v3);
;                 *(u32x2*)(sw + m * 16 * 264 + bj * HALF + n * 16) = o;
	v_max_f32_e32 v236, v34, v34
	v_max_f32_e32 v237, v35, v35
	v_max_f32_e32 v238, v36, v36
	v_max_f32_e32 v239, v37, v37
	v_max_f32_e32 v236, 0, v236
	v_max_f32_e32 v237, 0, v237
	v_max_f32_e32 v238, 0, v238
	v_max_f32_e32 v239, 0, v239
	v_pk_mul_f32 v[236:237], v[236:237], v[236:237]
	v_pk_mul_f32 v[238:239], v[238:239], v[238:239]
	v_cvt_pk_bf16_f32 v236, v236, v237
	v_cvt_pk_bf16_f32 v237, v238, v239
	ds_write_b64 v159, v[236:237] offset:256
	v_max_f32_e32 v240, v26, v26
	v_max_f32_e32 v241, v27, v27
	v_max_f32_e32 v242, v28, v28
	v_max_f32_e32 v243, v29, v29
	v_max_f32_e32 v240, 0, v240
	v_max_f32_e32 v241, 0, v241
	v_max_f32_e32 v242, 0, v242
	v_max_f32_e32 v243, 0, v243
	v_pk_mul_f32 v[240:241], v[240:241], v[240:241]
	v_pk_mul_f32 v[242:243], v[242:243], v[242:243]
	v_cvt_pk_bf16_f32 v240, v240, v241
	v_cvt_pk_bf16_f32 v241, v242, v243
	ds_write_b64 v159, v[240:241] offset:8704
	v_max_f32_e32 v244, v18, v18
	v_max_f32_e32 v245, v19, v19
	v_max_f32_e32 v246, v20, v20
	v_max_f32_e32 v247, v21, v21
	v_max_f32_e32 v244, 0, v244
	v_max_f32_e32 v245, 0, v245
	v_max_f32_e32 v246, 0, v246
	v_max_f32_e32 v247, 0, v247
	v_pk_mul_f32 v[244:245], v[244:245], v[244:245]
	v_pk_mul_f32 v[246:247], v[246:247], v[246:247]
	v_cvt_pk_bf16_f32 v244, v244, v245
	v_cvt_pk_bf16_f32 v245, v246, v247
	ds_write_b64 v159, v[244:245] offset:17152
	v_max_f32_e32 v248, v10, v10
	v_max_f32_e32 v249, v11, v11
	v_max_f32_e32 v250, v12, v12
	v_max_f32_e32 v251, v13, v13
	v_max_f32_e32 v248, 0, v248
	v_max_f32_e32 v249, 0, v249
	v_max_f32_e32 v250, 0, v250
	v_max_f32_e32 v251, 0, v251
	v_pk_mul_f32 v[248:249], v[248:249], v[248:249]
	v_pk_mul_f32 v[250:251], v[250:251], v[250:251]
	v_cvt_pk_bf16_f32 v248, v248, v249
	v_cvt_pk_bf16_f32 v249, v250, v251
	ds_write_b64 v159, v[248:249] offset:25600
	v_max_f32_e32 v204, v30, v30
	v_max_f32_e32 v205, v31, v31
	v_max_f32_e32 v206, v32, v32
	v_max_f32_e32 v207, v33, v33
	v_max_f32_e32 v204, 0, v204
	v_max_f32_e32 v205, 0, v205
	v_max_f32_e32 v206, 0, v206
	v_max_f32_e32 v207, 0, v207
	v_pk_mul_f32 v[204:205], v[204:205], v[204:205]
	v_pk_mul_f32 v[206:207], v[206:207], v[206:207]
	v_cvt_pk_bf16_f32 v204, v204, v205
	v_cvt_pk_bf16_f32 v205, v206, v207
	ds_write_b64 v159, v[204:205] offset:288
	v_max_f32_e32 v208, v22, v22
	v_max_f32_e32 v209, v23, v23
	v_max_f32_e32 v210, v24, v24
	v_max_f32_e32 v211, v25, v25
	v_max_f32_e32 v208, 0, v208
	v_max_f32_e32 v209, 0, v209
	v_max_f32_e32 v210, 0, v210
	v_max_f32_e32 v211, 0, v211
	v_pk_mul_f32 v[208:209], v[208:209], v[208:209]
	v_pk_mul_f32 v[210:211], v[210:211], v[210:211]
	v_cvt_pk_bf16_f32 v208, v208, v209
	v_cvt_pk_bf16_f32 v209, v210, v211
	ds_write_b64 v159, v[208:209] offset:8736
	v_max_f32_e32 v212, v14, v14
	v_max_f32_e32 v213, v15, v15
	v_max_f32_e32 v214, v16, v16
	v_max_f32_e32 v215, v17, v17
	v_max_f32_e32 v212, 0, v212
	v_max_f32_e32 v213, 0, v213
	v_max_f32_e32 v214, 0, v214
	v_max_f32_e32 v215, 0, v215
	v_pk_mul_f32 v[212:213], v[212:213], v[212:213]
	v_pk_mul_f32 v[214:215], v[214:215], v[214:215]
	v_cvt_pk_bf16_f32 v212, v212, v213
	v_cvt_pk_bf16_f32 v213, v214, v215
	ds_write_b64 v159, v[212:213] offset:17184
	v_max_f32_e32 v216, v6, v6
	v_max_f32_e32 v217, v7, v7
	v_max_f32_e32 v218, v8, v8
	v_max_f32_e32 v219, v9, v9
	v_max_f32_e32 v216, 0, v216
	v_max_f32_e32 v217, 0, v217
	v_max_f32_e32 v218, 0, v218
	v_max_f32_e32 v219, 0, v219
	v_pk_mul_f32 v[216:217], v[216:217], v[216:217]
	v_pk_mul_f32 v[218:219], v[218:219], v[218:219]
	v_cvt_pk_bf16_f32 v132, v216, v217
	v_cvt_pk_bf16_f32 v133, v218, v219
	s_branch .LBB0_425
